# K-loops: wait-state nops replaced by reordered ds_read / SALU, LDS read bases formed once per tile
# speedup vs baseline: 1.0208x; 1.0033x over previous
.LBB0_137:
	s_ashr_i32 s49, s48, 31
	s_lshl_b64 s[22:23], s[48:49], 20
	s_add_u32 s52, s26, s22
	s_addc_u32 s53, s27, s23
	s_and_b64 s[0:1], s[0:1], exec
	s_cselect_b32 s22, s53, s7
	s_cselect_b32 s23, s52, s6
	s_add_u32 s0, s12, 0x80080
	s_addc_u32 s1, s13, 0
	s_add_u32 s38, s6, 0x100
	v_mov_b32_e32 v2, 0
	s_addc_u32 s39, s7, 0
	s_mov_b32 s49, -2
	v_mov_b32_e32 v3, v2
	v_mov_b32_e32 v4, v2
	v_mov_b32_e32 v5, v2
	v_mov_b32_e32 v6, v2
	v_mov_b32_e32 v7, v2
	v_mov_b32_e32 v8, v2
	v_mov_b32_e32 v9, v2
	v_mov_b32_e32 v14, v2
	v_mov_b32_e32 v15, v2
	v_mov_b32_e32 v16, v2
	v_mov_b32_e32 v17, v2
	v_mov_b32_e32 v22, v2
	v_mov_b32_e32 v23, v2
	v_mov_b32_e32 v24, v2
	v_mov_b32_e32 v25, v2
	v_mov_b32_e32 v30, v2
	v_mov_b32_e32 v31, v2
	v_mov_b32_e32 v32, v2
	v_mov_b32_e32 v33, v2
	v_mov_b32_e32 v38, v2
	v_mov_b32_e32 v39, v2
	v_mov_b32_e32 v40, v2
	v_mov_b32_e32 v41, v2
	v_mov_b32_e32 v46, v2
	v_mov_b32_e32 v47, v2
	v_mov_b32_e32 v48, v2
	v_mov_b32_e32 v49, v2
	v_mov_b32_e32 v54, v2
	v_mov_b32_e32 v55, v2
	v_mov_b32_e32 v56, v2
	v_mov_b32_e32 v57, v2
	v_mov_b32_e32 v10, v2
	v_mov_b32_e32 v11, v2
	v_mov_b32_e32 v12, v2
	v_mov_b32_e32 v13, v2
	v_mov_b32_e32 v18, v2
	v_mov_b32_e32 v19, v2
	v_mov_b32_e32 v20, v2
	v_mov_b32_e32 v21, v2
	v_mov_b32_e32 v26, v2
	v_mov_b32_e32 v27, v2
	v_mov_b32_e32 v28, v2
	v_mov_b32_e32 v29, v2
	v_mov_b32_e32 v34, v2
	v_mov_b32_e32 v35, v2
	v_mov_b32_e32 v36, v2
	v_mov_b32_e32 v37, v2
	v_mov_b32_e32 v42, v2
	v_mov_b32_e32 v43, v2
	v_mov_b32_e32 v44, v2
	v_mov_b32_e32 v45, v2
	v_mov_b32_e32 v50, v2
	v_mov_b32_e32 v51, v2
	v_mov_b32_e32 v52, v2
	v_mov_b32_e32 v53, v2
	v_mov_b32_e32 v58, v2
	v_mov_b32_e32 v59, v2
	v_mov_b32_e32 v60, v2
	v_mov_b32_e32 v61, v2
	v_mov_b32_e32 v62, v2
	v_mov_b32_e32 v63, v2
	v_mov_b32_e32 v64, v2
	v_mov_b32_e32 v65, v2
	v_mov_b32_e32 v66, v2
	v_mov_b32_e32 v67, v2
	v_mov_b32_e32 v68, v2
	v_mov_b32_e32 v69, v2
	v_mov_b32_e32 v70, v2
	v_mov_b32_e32 v71, v2
	v_mov_b32_e32 v72, v2
	v_mov_b32_e32 v73, v2
	v_mov_b32_e32 v78, v2
	v_mov_b32_e32 v79, v2
	v_mov_b32_e32 v80, v2
	v_mov_b32_e32 v81, v2
	v_mov_b32_e32 v86, v2
	v_mov_b32_e32 v87, v2
	v_mov_b32_e32 v88, v2
	v_mov_b32_e32 v89, v2
	v_mov_b32_e32 v94, v2
	v_mov_b32_e32 v95, v2
	v_mov_b32_e32 v96, v2
	v_mov_b32_e32 v97, v2
	v_mov_b32_e32 v102, v2
	v_mov_b32_e32 v103, v2
	v_mov_b32_e32 v104, v2
	v_mov_b32_e32 v105, v2
	v_mov_b32_e32 v110, v2
	v_mov_b32_e32 v111, v2
	v_mov_b32_e32 v112, v2
	v_mov_b32_e32 v113, v2
	v_mov_b32_e32 v118, v2
	v_mov_b32_e32 v119, v2
	v_mov_b32_e32 v120, v2
	v_mov_b32_e32 v121, v2
	v_mov_b32_e32 v74, v2
	v_mov_b32_e32 v75, v2
	v_mov_b32_e32 v76, v2
	v_mov_b32_e32 v77, v2
	v_mov_b32_e32 v82, v2
	v_mov_b32_e32 v83, v2
	v_mov_b32_e32 v84, v2
	v_mov_b32_e32 v85, v2
	v_mov_b32_e32 v90, v2
	v_mov_b32_e32 v91, v2
	v_mov_b32_e32 v92, v2
	v_mov_b32_e32 v93, v2
	v_mov_b32_e32 v98, v2
	v_mov_b32_e32 v99, v2
	v_mov_b32_e32 v100, v2
	v_mov_b32_e32 v101, v2
	v_mov_b32_e32 v106, v2
	v_mov_b32_e32 v107, v2
	v_mov_b32_e32 v108, v2
	v_mov_b32_e32 v109, v2
	v_mov_b32_e32 v114, v2
	v_mov_b32_e32 v115, v2
	v_mov_b32_e32 v116, v2
	v_mov_b32_e32 v117, v2
	v_mov_b32_e32 v122, v2
	v_mov_b32_e32 v123, v2
	v_mov_b32_e32 v124, v2
	v_mov_b32_e32 v125, v2
	v_mov_b32_e32 v126, v2
	v_mov_b32_e32 v127, v2
	v_mov_b32_e32 v128, v2
	v_mov_b32_e32 v129, v2
	v_add_u32_e32 v224, 0x10000, v149
	v_add_u32_e32 v225, 0x14000, v149
	v_add_u32_e32 v226, 0x18000, v149
	v_add_u32_e32 v227, 0x1c000, v149
.LBB0_138:
	s_add_u32 s6, s0, 0xfff80080
	s_addc_u32 s7, s1, -1
	s_add_i32 s76, 0, 0x10000
	ds_read_b128 v[130:133], v224
	ds_read_b128 v[134:137], v224 offset:1024
	ds_read_b128 v[138:141], v224 offset:2048
	ds_read_b128 v[142:145], v224 offset:3072
	s_cmp_eq_u32 s49, 28
	s_cselect_b32 s13, s51, s7
	s_cselect_b32 s12, s50, s6
	s_cselect_b32 s7, s22, s39
	s_cselect_b32 s6, s23, s38
	s_add_i32 m0, s31, 0xc000
	ds_read_b128 v[152:155], v174
	ds_read_b128 v[166:169], v174 offset:1024
	ds_read_b128 v[170:173], v174 offset:2048
	ds_read_b128 v[176:179], v174 offset:3072
	ds_read_b128 v[180:183], v174 offset:4096
	ds_read_b128 v[184:187], v174 offset:5120
	ds_read_b128 v[188:191], v174 offset:6144
	global_load_lds_dwordx4 v162, s[0:1]
	s_add_i32 m0, s31, 0xe000
	ds_read_b128 v[192:195], v174 offset:7168
	global_load_lds_dwordx4 v164, s[0:1]
	s_waitcnt lgkmcnt(8)
	s_barrier
	s_setprio 1
	s_waitcnt lgkmcnt(7)
	v_mfma_f32_16x16x32_bf16 v[126:129], v[130:133], v[152:155], v[126:129]
	v_mfma_f32_16x16x32_bf16 v[122:125], v[138:141], v[152:155], v[122:125]
	s_waitcnt lgkmcnt(5)
	v_mfma_f32_16x16x32_bf16 v[114:117], v[130:133], v[170:173], v[114:117]
	v_mfma_f32_16x16x32_bf16 v[106:109], v[138:141], v[170:173], v[106:109]
	s_waitcnt lgkmcnt(3)
	v_mfma_f32_16x16x32_bf16 v[98:101], v[130:133], v[180:183], v[98:101]
	v_mfma_f32_16x16x32_bf16 v[90:93], v[138:141], v[180:183], v[90:93]
	s_waitcnt lgkmcnt(1)
	v_mfma_f32_16x16x32_bf16 v[82:85], v[130:133], v[188:191], v[82:85]
	v_mfma_f32_16x16x32_bf16 v[74:77], v[138:141], v[188:191], v[74:77]
	v_mfma_f32_16x16x32_bf16 v[126:129], v[134:137], v[166:169], v[126:129]
	v_mfma_f32_16x16x32_bf16 v[122:125], v[142:145], v[166:169], v[122:125]
	v_mfma_f32_16x16x32_bf16 v[114:117], v[134:137], v[176:179], v[114:117]
	v_mfma_f32_16x16x32_bf16 v[106:109], v[142:145], v[176:179], v[106:109]
	v_mfma_f32_16x16x32_bf16 v[98:101], v[134:137], v[184:187], v[98:101]
	v_mfma_f32_16x16x32_bf16 v[90:93], v[142:145], v[184:187], v[90:93]
	s_waitcnt lgkmcnt(0)
	v_mfma_f32_16x16x32_bf16 v[82:85], v[134:137], v[192:195], v[82:85]
	v_mfma_f32_16x16x32_bf16 v[74:77], v[142:145], v[192:195], v[74:77]
	s_setprio 0
	s_barrier
	s_add_i32 s78, 0, 0x14000
	s_add_i32 s76, s76, s30
	s_mov_b32 m0, s76
	ds_read_b128 v[196:199], v225
	ds_read_b128 v[200:203], v225 offset:1024
	ds_read_b128 v[204:207], v225 offset:2048
	global_load_lds_dwordx4 v158, s[6:7]
	s_add_i32 m0, s76, 0x2000
	ds_read_b128 v[216:219], v225 offset:3072
	global_load_lds_dwordx4 v146, s[6:7]
	s_barrier
	s_setprio 1
	s_waitcnt lgkmcnt(3)
	v_mfma_f32_16x16x32_bf16 v[118:121], v[196:199], v[152:155], v[118:121]
	s_waitcnt lgkmcnt(1)
	v_mfma_f32_16x16x32_bf16 v[110:113], v[204:207], v[152:155], v[110:113]
	v_mfma_f32_16x16x32_bf16 v[102:105], v[196:199], v[170:173], v[102:105]
	v_mfma_f32_16x16x32_bf16 v[94:97], v[204:207], v[170:173], v[94:97]
	v_mfma_f32_16x16x32_bf16 v[86:89], v[196:199], v[180:183], v[86:89]
	v_mfma_f32_16x16x32_bf16 v[78:81], v[204:207], v[180:183], v[78:81]
	v_mfma_f32_16x16x32_bf16 v[70:73], v[196:199], v[188:191], v[70:73]
	v_mfma_f32_16x16x32_bf16 v[66:69], v[204:207], v[188:191], v[66:69]
	v_mfma_f32_16x16x32_bf16 v[118:121], v[200:203], v[166:169], v[118:121]
	s_waitcnt lgkmcnt(0)
	v_mfma_f32_16x16x32_bf16 v[110:113], v[216:219], v[166:169], v[110:113]
	v_mfma_f32_16x16x32_bf16 v[102:105], v[200:203], v[176:179], v[102:105]
	v_mfma_f32_16x16x32_bf16 v[94:97], v[216:219], v[176:179], v[94:97]
	v_mfma_f32_16x16x32_bf16 v[86:89], v[200:203], v[184:187], v[86:89]
	v_mfma_f32_16x16x32_bf16 v[78:81], v[216:219], v[184:187], v[78:81]
	v_mfma_f32_16x16x32_bf16 v[70:73], v[200:203], v[192:195], v[70:73]
	v_mfma_f32_16x16x32_bf16 v[66:69], v[216:219], v[192:195], v[66:69]
	s_setprio 0
	s_mov_b32 m0, s31
	s_add_u32 s98, s12, 0x80
	s_addc_u32 s99, s13, 0
	s_barrier
	ds_read_b128 v[152:155], v174 offset:16384
	ds_read_b128 v[166:169], v174 offset:17408
	ds_read_b128 v[170:173], v174 offset:18432
	ds_read_b128 v[176:179], v174 offset:19456
	ds_read_b128 v[180:183], v174 offset:20480
	ds_read_b128 v[184:187], v174 offset:21504
	ds_read_b128 v[188:191], v174 offset:22528
	global_load_lds_dwordx4 v160, s[12:13]
	s_mov_b32 m0, s40
	ds_read_b128 v[192:195], v174 offset:23552
	global_load_lds_dwordx4 v156, s[12:13]
	s_barrier
	s_setprio 1
	s_waitcnt lgkmcnt(7)
	v_mfma_f32_16x16x32_bf16 v[62:65], v[130:133], v[152:155], v[62:65]
	v_mfma_f32_16x16x32_bf16 v[58:61], v[138:141], v[152:155], v[58:61]
	s_waitcnt lgkmcnt(5)
	v_mfma_f32_16x16x32_bf16 v[50:53], v[130:133], v[170:173], v[50:53]
	v_mfma_f32_16x16x32_bf16 v[42:45], v[138:141], v[170:173], v[42:45]
	s_waitcnt lgkmcnt(3)
	v_mfma_f32_16x16x32_bf16 v[34:37], v[130:133], v[180:183], v[34:37]
	v_mfma_f32_16x16x32_bf16 v[26:29], v[138:141], v[180:183], v[26:29]
	s_waitcnt lgkmcnt(1)
	v_mfma_f32_16x16x32_bf16 v[18:21], v[130:133], v[188:191], v[18:21]
	v_mfma_f32_16x16x32_bf16 v[10:13], v[138:141], v[188:191], v[10:13]
	v_mfma_f32_16x16x32_bf16 v[62:65], v[134:137], v[166:169], v[62:65]
	v_mfma_f32_16x16x32_bf16 v[58:61], v[142:145], v[166:169], v[58:61]
	v_mfma_f32_16x16x32_bf16 v[50:53], v[134:137], v[176:179], v[50:53]
	v_mfma_f32_16x16x32_bf16 v[42:45], v[142:145], v[176:179], v[42:45]
	v_mfma_f32_16x16x32_bf16 v[34:37], v[134:137], v[184:187], v[34:37]
	v_mfma_f32_16x16x32_bf16 v[26:29], v[142:145], v[184:187], v[26:29]
	s_waitcnt lgkmcnt(0)
	v_mfma_f32_16x16x32_bf16 v[18:21], v[134:137], v[192:195], v[18:21]
	v_mfma_f32_16x16x32_bf16 v[10:13], v[142:145], v[192:195], v[10:13]
	s_setprio 0
	s_barrier
	s_add_i32 s78, s78, s30
	s_mov_b32 m0, s78
	s_add_u32 s76, s6, 0x80000
	s_addc_u32 s77, s7, 0
	global_load_lds_dwordx4 v158, s[76:77]
	s_add_i32 m0, s78, 0x2000
	s_nop 0
	global_load_lds_dwordx4 v146, s[76:77]
	s_waitcnt vmcnt(6)
	s_barrier
	s_setprio 1
	v_mfma_f32_16x16x32_bf16 v[54:57], v[196:199], v[152:155], v[54:57]
	v_mfma_f32_16x16x32_bf16 v[46:49], v[204:207], v[152:155], v[46:49]
	v_mfma_f32_16x16x32_bf16 v[38:41], v[196:199], v[170:173], v[38:41]
	v_mfma_f32_16x16x32_bf16 v[30:33], v[204:207], v[170:173], v[30:33]
	v_mfma_f32_16x16x32_bf16 v[22:25], v[196:199], v[180:183], v[22:25]
	v_mfma_f32_16x16x32_bf16 v[14:17], v[204:207], v[180:183], v[14:17]
	v_mfma_f32_16x16x32_bf16 v[6:9], v[196:199], v[188:191], v[6:9]
	v_mfma_f32_16x16x32_bf16 v[2:5], v[204:207], v[188:191], v[2:5]
	v_mfma_f32_16x16x32_bf16 v[54:57], v[200:203], v[166:169], v[54:57]
	v_mfma_f32_16x16x32_bf16 v[46:49], v[216:219], v[166:169], v[46:49]
	v_mfma_f32_16x16x32_bf16 v[38:41], v[200:203], v[176:179], v[38:41]
	v_mfma_f32_16x16x32_bf16 v[30:33], v[216:219], v[176:179], v[30:33]
	v_mfma_f32_16x16x32_bf16 v[22:25], v[200:203], v[184:187], v[22:25]
	v_mfma_f32_16x16x32_bf16 v[14:17], v[216:219], v[184:187], v[14:17]
	v_mfma_f32_16x16x32_bf16 v[6:9], v[200:203], v[192:195], v[6:9]
	v_mfma_f32_16x16x32_bf16 v[2:5], v[216:219], v[192:195], v[2:5]
	s_setprio 0
	s_add_i32 s76, 0, 0x18000
	s_barrier
	ds_read_b128 v[130:133], v226
	ds_read_b128 v[134:137], v226 offset:1024
	ds_read_b128 v[138:141], v226 offset:2048
	ds_read_b128 v[142:145], v226 offset:3072
	s_add_u32 s12, s12, 0x80000
	s_addc_u32 s13, s13, 0
	s_mov_b32 m0, s41
	ds_read_b128 v[152:155], v174 offset:32768
	ds_read_b128 v[166:169], v174 offset:33792
	ds_read_b128 v[170:173], v174 offset:34816
	ds_read_b128 v[176:179], v174 offset:35840
	ds_read_b128 v[180:183], v174 offset:36864
	ds_read_b128 v[184:187], v174 offset:37888
	ds_read_b128 v[188:191], v174 offset:38912
	global_load_lds_dwordx4 v160, s[12:13]
	s_mov_b32 m0, s60
	ds_read_b128 v[192:195], v174 offset:39936
	global_load_lds_dwordx4 v156, s[12:13]
	s_waitcnt lgkmcnt(8)
	s_barrier
	s_setprio 1
	s_waitcnt lgkmcnt(7)
	v_mfma_f32_16x16x32_bf16 v[126:129], v[130:133], v[152:155], v[126:129]
	v_mfma_f32_16x16x32_bf16 v[122:125], v[138:141], v[152:155], v[122:125]
	s_waitcnt lgkmcnt(5)
	v_mfma_f32_16x16x32_bf16 v[114:117], v[130:133], v[170:173], v[114:117]
	v_mfma_f32_16x16x32_bf16 v[106:109], v[138:141], v[170:173], v[106:109]
	s_waitcnt lgkmcnt(3)
	v_mfma_f32_16x16x32_bf16 v[98:101], v[130:133], v[180:183], v[98:101]
	v_mfma_f32_16x16x32_bf16 v[90:93], v[138:141], v[180:183], v[90:93]
	s_waitcnt lgkmcnt(1)
	v_mfma_f32_16x16x32_bf16 v[82:85], v[130:133], v[188:191], v[82:85]
	v_mfma_f32_16x16x32_bf16 v[74:77], v[138:141], v[188:191], v[74:77]
	v_mfma_f32_16x16x32_bf16 v[126:129], v[134:137], v[166:169], v[126:129]
	v_mfma_f32_16x16x32_bf16 v[122:125], v[142:145], v[166:169], v[122:125]
	v_mfma_f32_16x16x32_bf16 v[114:117], v[134:137], v[176:179], v[114:117]
	v_mfma_f32_16x16x32_bf16 v[106:109], v[142:145], v[176:179], v[106:109]
	v_mfma_f32_16x16x32_bf16 v[98:101], v[134:137], v[184:187], v[98:101]
	v_mfma_f32_16x16x32_bf16 v[90:93], v[142:145], v[184:187], v[90:93]
	s_waitcnt lgkmcnt(0)
	v_mfma_f32_16x16x32_bf16 v[82:85], v[134:137], v[192:195], v[82:85]
	v_mfma_f32_16x16x32_bf16 v[74:77], v[142:145], v[192:195], v[74:77]
	s_setprio 0
	s_barrier
	s_add_i32 s12, 0, 0x1c000
	s_add_i32 s13, s76, s30
	s_add_u32 s100, s6, 0x80
	s_addc_u32 s101, s7, 0
	s_mov_b32 m0, s13
	ds_read_b128 v[196:199], v227
	ds_read_b128 v[200:203], v227 offset:1024
	ds_read_b128 v[204:207], v227 offset:2048
	global_load_lds_dwordx4 v158, s[100:101]
	s_add_i32 m0, s13, 0x2000
	ds_read_b128 v[216:219], v227 offset:3072
	global_load_lds_dwordx4 v146, s[100:101]
	s_barrier
	s_setprio 1
	s_waitcnt lgkmcnt(3)
	v_mfma_f32_16x16x32_bf16 v[118:121], v[196:199], v[152:155], v[118:121]
	s_waitcnt lgkmcnt(1)
	v_mfma_f32_16x16x32_bf16 v[110:113], v[204:207], v[152:155], v[110:113]
	v_mfma_f32_16x16x32_bf16 v[102:105], v[196:199], v[170:173], v[102:105]
	v_mfma_f32_16x16x32_bf16 v[94:97], v[204:207], v[170:173], v[94:97]
	v_mfma_f32_16x16x32_bf16 v[86:89], v[196:199], v[180:183], v[86:89]
	v_mfma_f32_16x16x32_bf16 v[78:81], v[204:207], v[180:183], v[78:81]
	v_mfma_f32_16x16x32_bf16 v[70:73], v[196:199], v[188:191], v[70:73]
	v_mfma_f32_16x16x32_bf16 v[66:69], v[204:207], v[188:191], v[66:69]
	v_mfma_f32_16x16x32_bf16 v[118:121], v[200:203], v[166:169], v[118:121]
	s_waitcnt lgkmcnt(0)
	v_mfma_f32_16x16x32_bf16 v[110:113], v[216:219], v[166:169], v[110:113]
	v_mfma_f32_16x16x32_bf16 v[102:105], v[200:203], v[176:179], v[102:105]
	v_mfma_f32_16x16x32_bf16 v[94:97], v[216:219], v[176:179], v[94:97]
	v_mfma_f32_16x16x32_bf16 v[86:89], v[200:203], v[184:187], v[86:89]
	v_mfma_f32_16x16x32_bf16 v[78:81], v[216:219], v[184:187], v[78:81]
	v_mfma_f32_16x16x32_bf16 v[70:73], v[200:203], v[192:195], v[70:73]
	v_mfma_f32_16x16x32_bf16 v[66:69], v[216:219], v[192:195], v[66:69]
	s_setprio 0
	s_mov_b32 m0, s64
	s_barrier
	ds_read_b128 v[152:155], v174 offset:49152
	ds_read_b128 v[166:169], v174 offset:50176
	ds_read_b128 v[170:173], v174 offset:51200
	ds_read_b128 v[176:179], v174 offset:52224
	ds_read_b128 v[180:183], v174 offset:53248
	ds_read_b128 v[184:187], v174 offset:54272
	ds_read_b128 v[188:191], v174 offset:55296
	global_load_lds_dwordx4 v160, s[98:99]
	s_mov_b32 m0, s65
	ds_read_b128 v[192:195], v174 offset:56320
	global_load_lds_dwordx4 v156, s[98:99]
	s_barrier
	s_setprio 1
	s_waitcnt lgkmcnt(7)
	v_mfma_f32_16x16x32_bf16 v[62:65], v[130:133], v[152:155], v[62:65]
	v_mfma_f32_16x16x32_bf16 v[58:61], v[138:141], v[152:155], v[58:61]
	s_waitcnt lgkmcnt(5)
	v_mfma_f32_16x16x32_bf16 v[50:53], v[130:133], v[170:173], v[50:53]
	v_mfma_f32_16x16x32_bf16 v[42:45], v[138:141], v[170:173], v[42:45]
	s_waitcnt lgkmcnt(3)
	v_mfma_f32_16x16x32_bf16 v[34:37], v[130:133], v[180:183], v[34:37]
	v_mfma_f32_16x16x32_bf16 v[26:29], v[138:141], v[180:183], v[26:29]
	s_waitcnt lgkmcnt(1)
	v_mfma_f32_16x16x32_bf16 v[18:21], v[130:133], v[188:191], v[18:21]
	v_mfma_f32_16x16x32_bf16 v[10:13], v[138:141], v[188:191], v[10:13]
	v_mfma_f32_16x16x32_bf16 v[62:65], v[134:137], v[166:169], v[62:65]
	v_mfma_f32_16x16x32_bf16 v[58:61], v[142:145], v[166:169], v[58:61]
	v_mfma_f32_16x16x32_bf16 v[50:53], v[134:137], v[176:179], v[50:53]
	v_mfma_f32_16x16x32_bf16 v[42:45], v[142:145], v[176:179], v[42:45]
	v_mfma_f32_16x16x32_bf16 v[34:37], v[134:137], v[184:187], v[34:37]
	v_mfma_f32_16x16x32_bf16 v[26:29], v[142:145], v[184:187], v[26:29]
	s_waitcnt lgkmcnt(0)
	v_mfma_f32_16x16x32_bf16 v[18:21], v[134:137], v[192:195], v[18:21]
	v_mfma_f32_16x16x32_bf16 v[10:13], v[142:145], v[192:195], v[10:13]
	s_setprio 0
	s_barrier
	s_add_i32 s12, s12, s30
	s_mov_b32 m0, s12
	s_add_u32 s6, s6, 0x80080
	s_addc_u32 s7, s7, 0
	global_load_lds_dwordx4 v158, s[6:7]
	s_add_i32 m0, s12, 0x2000
	s_nop 0
	global_load_lds_dwordx4 v146, s[6:7]
	s_waitcnt vmcnt(6)
	s_barrier
	s_setprio 1
	v_mfma_f32_16x16x32_bf16 v[54:57], v[196:199], v[152:155], v[54:57]
	v_mfma_f32_16x16x32_bf16 v[46:49], v[204:207], v[152:155], v[46:49]
	v_mfma_f32_16x16x32_bf16 v[38:41], v[196:199], v[170:173], v[38:41]
	v_mfma_f32_16x16x32_bf16 v[30:33], v[204:207], v[170:173], v[30:33]
	v_mfma_f32_16x16x32_bf16 v[22:25], v[196:199], v[180:183], v[22:25]
	v_mfma_f32_16x16x32_bf16 v[14:17], v[204:207], v[180:183], v[14:17]
	v_mfma_f32_16x16x32_bf16 v[6:9], v[196:199], v[188:191], v[6:9]
	v_mfma_f32_16x16x32_bf16 v[2:5], v[204:207], v[188:191], v[2:5]
	v_mfma_f32_16x16x32_bf16 v[54:57], v[200:203], v[166:169], v[54:57]
	v_mfma_f32_16x16x32_bf16 v[46:49], v[216:219], v[166:169], v[46:49]
	v_mfma_f32_16x16x32_bf16 v[38:41], v[200:203], v[176:179], v[38:41]
	v_mfma_f32_16x16x32_bf16 v[30:33], v[216:219], v[176:179], v[30:33]
	v_mfma_f32_16x16x32_bf16 v[22:25], v[200:203], v[184:187], v[22:25]
	v_mfma_f32_16x16x32_bf16 v[14:17], v[216:219], v[184:187], v[14:17]
	v_mfma_f32_16x16x32_bf16 v[6:9], v[200:203], v[192:195], v[6:9]
	v_mfma_f32_16x16x32_bf16 v[2:5], v[216:219], v[192:195], v[2:5]
	s_setprio 0
	s_add_i32 s49, s49, 2
	s_add_u32 s0, s0, 0x100
	s_addc_u32 s1, s1, 0
	s_add_u32 s38, s38, 0x100
	s_addc_u32 s39, s39, 0
	s_cmp_gt_u32 s49, 29
	s_barrier
	s_cbranch_scc0 .LBB0_138
	v_mov_b32_e32 v0, v148
	s_cmp_gt_i32 s69, 15
	v_and_b32_e32 v176, 15, v0
	v_bfe_u32 v175, v0, 4, 2
	s_mov_b64 s[0:1], -1
	s_cbranch_scc0 .LBB0_157
	s_cmp_gt_u32 s69, 23
	s_cbranch_scc0 .LBB0_154
	s_cmp_gt_u32 s69, 31
	s_cbranch_scc0 .LBB0_151
	s_cmp_gt_u32 s69, 39
	s_cbranch_scc0 .LBB0_148
	v_mul_f32_e32 v0, 0xbfb8aa3b, v126
	v_exp_f32_e32 v131, v0
	s_lshr_b32 s0, s75, 3
	s_mulk_i32 s0, 0x880
	s_lshl_b32 s1, s75, 8
	v_add_f32_e32 v131, 1.0, v131
	v_rcp_f32_e32 v132, v131
	v_mul_f32_e32 v131, 0xbfb8aa3b, v122
	v_mul_f32_e32 v133, 0xbfb8aa3b, v127
	v_mul_f32_e32 v134, 0xbfb8aa3b, v123
	v_mul_f32_e32 v135, 0xbfb8aa3b, v128
	v_mul_f32_e32 v136, 0xbfb8aa3b, v124
	v_mul_f32_e32 v137, 0xbfb8aa3b, v129
	v_mul_f32_e32 v138, 0xbfb8aa3b, v125
	v_mul_f32_e32 v139, 0xbfb8aa3b, v118
	v_mul_f32_e32 v140, 0xbfb8aa3b, v110
	v_mul_f32_e32 v141, 0xbfb8aa3b, v119
	v_mul_f32_e32 v142, 0xbfb8aa3b, v111
	v_mul_f32_e32 v143, 0xbfb8aa3b, v120
	v_mul_f32_e32 v152, 0xbfb8aa3b, v112
	v_mul_f32_e32 v153, 0xbfb8aa3b, v121
	v_mul_f32_e32 v154, 0xbfb8aa3b, v113
	v_mul_f32_e32 v155, 0xbfb8aa3b, v114
	v_mul_f32_e32 v177, 0xbfb8aa3b, v106
	v_mul_f32_e32 v178, 0xbfb8aa3b, v115
	v_mul_f32_e32 v179, 0xbfb8aa3b, v107
	v_mul_f32_e32 v180, 0xbfb8aa3b, v116
	v_mul_f32_e32 v181, 0xbfb8aa3b, v108
	v_mul_f32_e32 v182, 0xbfb8aa3b, v117
	v_mul_f32_e32 v183, 0xbfb8aa3b, v109
	v_mul_f32_e32 v184, 0xbfb8aa3b, v102
	v_mul_f32_e32 v185, 0xbfb8aa3b, v94
	v_mul_f32_e32 v186, 0xbfb8aa3b, v103
	v_mul_f32_e32 v187, 0xbfb8aa3b, v95
	v_mul_f32_e32 v188, 0xbfb8aa3b, v104
	v_mul_f32_e32 v189, 0xbfb8aa3b, v96
	v_mul_f32_e32 v190, 0xbfb8aa3b, v105
	v_mul_f32_e32 v191, 0xbfb8aa3b, v97
	v_mul_f32_e32 v192, 0xbfb8aa3b, v98
	v_mul_f32_e32 v193, 0xbfb8aa3b, v90
	v_mul_f32_e32 v194, 0xbfb8aa3b, v99
	v_mul_f32_e32 v195, 0xbfb8aa3b, v91
	v_mul_f32_e32 v196, 0xbfb8aa3b, v100
	v_mul_f32_e32 v197, 0xbfb8aa3b, v92
	v_mul_f32_e32 v198, 0xbfb8aa3b, v101
	v_mul_f32_e32 v199, 0xbfb8aa3b, v93
	v_mul_f32_e32 v200, 0xbfb8aa3b, v86
	v_mul_f32_e32 v201, 0xbfb8aa3b, v78
	v_mul_f32_e32 v202, 0xbfb8aa3b, v87
	v_mul_f32_e32 v203, 0xbfb8aa3b, v79
	v_mul_f32_e32 v204, 0xbfb8aa3b, v88
	v_mul_f32_e32 v205, 0xbfb8aa3b, v80
	v_mul_f32_e32 v206, 0xbfb8aa3b, v89
	v_mul_f32_e32 v207, 0xbfb8aa3b, v81
	v_mul_f32_e32 v208, 0xbfb8aa3b, v82
	v_mul_f32_e32 v209, 0xbfb8aa3b, v74
	v_mul_f32_e32 v215, 0xbfb8aa3b, v83
	v_mul_f32_e32 v216, 0xbfb8aa3b, v75
	v_mul_f32_e32 v217, 0xbfb8aa3b, v84
	v_mul_f32_e32 v218, 0xbfb8aa3b, v76
	v_mul_f32_e32 v219, 0xbfb8aa3b, v85
	v_mul_f32_e32 v220, 0xbfb8aa3b, v77
	v_mul_f32_e32 v221, 0xbfb8aa3b, v70
	v_mul_f32_e32 v222, 0xbfb8aa3b, v66
	v_mul_f32_e32 v223, 0xbfb8aa3b, v71
	v_mul_f32_e32 v224, 0xbfb8aa3b, v67
	v_mul_f32_e32 v225, 0xbfb8aa3b, v72
	v_mul_f32_e32 v226, 0xbfb8aa3b, v68
	v_mul_f32_e32 v227, 0xbfb8aa3b, v73
	v_mul_f32_e32 v228, 0xbfb8aa3b, v69
	v_mul_f32_e32 v229, 0xbfb8aa3b, v62
	v_mul_f32_e32 v230, 0xbfb8aa3b, v58
	v_mul_f32_e32 v231, 0xbfb8aa3b, v63
	v_mul_f32_e32 v232, 0xbfb8aa3b, v59
	v_mul_f32_e32 v233, 0xbfb8aa3b, v64
	v_mul_f32_e32 v234, 0xbfb8aa3b, v60
	v_mul_f32_e32 v235, 0xbfb8aa3b, v65
	v_mul_f32_e32 v236, 0xbfb8aa3b, v61
	v_mul_f32_e32 v237, 0xbfb8aa3b, v54
	v_mul_f32_e32 v238, 0xbfb8aa3b, v46
	v_mul_f32_e32 v239, 0xbfb8aa3b, v55
	s_and_b32 s1, s1, 0x700
	s_add_i32 s0, s0, s66
	v_exp_f32_e32 v173, v131
	v_exp_f32_e32 v133, v133
	v_exp_f32_e32 v172, v134
	v_exp_f32_e32 v171, v135
	v_exp_f32_e32 v170, v136
	v_exp_f32_e32 v169, v137
	v_exp_f32_e32 v131, v138
	v_exp_f32_e32 v168, v139
	v_exp_f32_e32 v167, v140
	v_exp_f32_e32 v166, v141
	v_exp_f32_e32 v145, v142
	v_exp_f32_e32 v144, v143
	v_exp_f32_e32 v143, v152
	v_exp_f32_e32 v142, v153
	v_exp_f32_e32 v141, v154
	v_exp_f32_e32 v140, v155
	v_exp_f32_e32 v139, v177
	v_exp_f32_e32 v138, v178
	v_exp_f32_e32 v213, v179
	v_exp_f32_e32 v155, v180
	v_exp_f32_e32 v154, v181
	v_exp_f32_e32 v153, v182
	v_exp_f32_e32 v152, v183
	v_exp_f32_e32 v212, v184
	v_exp_f32_e32 v211, v185
	v_exp_f32_e32 v252, v186
	v_exp_f32_e32 v251, v187
	v_exp_f32_e32 v250, v188
	v_exp_f32_e32 v249, v189
	v_exp_f32_e32 v248, v190
	v_exp_f32_e32 v247, v191
	v_exp_f32_e32 v246, v192
	v_exp_f32_e32 v245, v193
	v_exp_f32_e32 v244, v194
	v_exp_f32_e32 v243, v195
	v_exp_f32_e32 v242, v196
	v_exp_f32_e32 v241, v197
	v_exp_f32_e32 v184, v198
	v_exp_f32_e32 v177, v199
	v_exp_f32_e32 v198, v200
	v_exp_f32_e32 v199, v201
	v_exp_f32_e32 v197, v202
	v_exp_f32_e32 v196, v203
	v_exp_f32_e32 v195, v204
	v_exp_f32_e32 v194, v205
	v_exp_f32_e32 v193, v206
	v_exp_f32_e32 v192, v207
	v_exp_f32_e32 v191, v208
	v_exp_f32_e32 v190, v209
	v_exp_f32_e32 v189, v215
	v_exp_f32_e32 v188, v216
	v_exp_f32_e32 v187, v217
	v_exp_f32_e32 v186, v218
	v_exp_f32_e32 v185, v219
	v_exp_f32_e32 v201, v220
	v_exp_f32_e32 v200, v221
	v_exp_f32_e32 v221, v222
	v_exp_f32_e32 v220, v223
	v_exp_f32_e32 v219, v224
	v_exp_f32_e32 v218, v225
	v_exp_f32_e32 v217, v226
	v_exp_f32_e32 v216, v227
	v_exp_f32_e32 v215, v228
	v_exp_f32_e32 v209, v229
	v_exp_f32_e32 v208, v230
	v_exp_f32_e32 v207, v231
	v_exp_f32_e32 v206, v232
	v_exp_f32_e32 v205, v233
	v_exp_f32_e32 v204, v234
	v_exp_f32_e32 v203, v235
	v_exp_f32_e32 v202, v236
	v_exp_f32_e32 v223, v237
	v_exp_f32_e32 v222, v238
	v_exp_f32_e32 v238, v239
	s_add_i32 s0, s0, s1
	s_lshl_b32 s1, s69, 8
	v_lshl_or_b32 v130, v175, 3, s1
	s_cmp_gt_u32 s69, 47
	v_or_b32_e32 v240, s0, v176
	v_or_b32_e32 v130, s61, v130
	s_mov_b64 s[0:1], -1
	v_mul_f32_e32 v237, 0xbfb8aa3b, v47
	v_mul_f32_e32 v236, 0xbfb8aa3b, v56
	v_mul_f32_e32 v235, 0xbfb8aa3b, v48
	v_mul_f32_e32 v234, 0xbfb8aa3b, v57
	v_mul_f32_e32 v233, 0xbfb8aa3b, v49
	v_mul_f32_e32 v232, 0xbfb8aa3b, v50
	v_mul_f32_e32 v231, 0xbfb8aa3b, v42
	v_mul_f32_e32 v230, 0xbfb8aa3b, v51
	v_mul_f32_e32 v229, 0xbfb8aa3b, v43
	v_mul_f32_e32 v228, 0xbfb8aa3b, v18
	s_cbranch_scc0 .LBB0_145
	v_add_f32_e32 v178, 1.0, v171
	v_rcp_f32_e32 v179, v178
	v_add_f32_e32 v178, 1.0, v170
	v_add_f32_e32 v134, 1.0, v173
	v_add_f32_e32 v135, 1.0, v133
	v_add_f32_e32 v137, 1.0, v172
	v_rcp_f32_e32 v181, v178
	v_add_f32_e32 v178, 1.0, v169
	v_rcp_f32_e32 v134, v134
	v_rcp_f32_e32 v135, v135
	v_rcp_f32_e32 v137, v137
	v_rcp_f32_e32 v180, v178
	v_add_f32_e32 v178, 1.0, v131
	v_rcp_f32_e32 v182, v178
	v_mov_b32_e32 v0, v240
	v_mov_b32_e32 v136, v130
	v_cvt_pk_bf16_f32 v178, v132, v135
	v_cvt_pk_bf16_f32 v179, v179, v180
	v_cvt_pk_bf16_f32 v180, v134, v137
	v_mov_b64_e32 v[134:135], s[8:9]
	v_ashrrev_i32_e32 v137, 31, v136
	v_cvt_pk_bf16_f32 v181, v181, v182
	v_mad_i64_i32 v[182:183], s[0:1], v0, s47, v[134:135]
	v_lshlrev_b64 v[136:137], 1, v[136:137]
	v_lshl_add_u64 v[182:183], v[182:183], 0, v[136:137]
	global_store_dwordx4 v[182:183], v[178:181], off
	s_nop 1
	v_add_f32_e32 v179, 1.0, v167
	v_add_f32_e32 v178, 1.0, v168
	v_rcp_f32_e32 v180, v179
	v_add_f32_e32 v179, 1.0, v166
	v_add_f32_e32 v181, 1.0, v145
	v_add_f32_e32 v239, 1.0, v144
	v_add_f32_e32 v224, 1.0, v143
	v_add_f32_e32 v225, 1.0, v142
	v_add_f32_e32 v226, 1.0, v141
	v_rcp_f32_e32 v178, v178
	v_rcp_f32_e32 v179, v179
	v_rcp_f32_e32 v181, v181
	v_rcp_f32_e32 v239, v239
	v_rcp_f32_e32 v224, v224
	v_rcp_f32_e32 v225, v225
	v_rcp_f32_e32 v226, v226
	v_cvt_pk_bf16_f32 v178, v178, v179
	v_cvt_pk_bf16_f32 v180, v180, v181
	v_cvt_pk_bf16_f32 v179, v239, v225
	v_cvt_pk_bf16_f32 v181, v224, v226
	global_store_dwordx4 v[182:183], v[178:181], off offset:256
	s_nop 1
	v_add_f32_e32 v179, 1.0, v139
	v_add_f32_e32 v178, 1.0, v140
	v_rcp_f32_e32 v180, v179
	v_add_f32_e32 v179, 1.0, v138
	v_add_f32_e32 v183, 1.0, v155
	v_add_f32_e32 v225, 1.0, v153
	v_rcp_f32_e32 v178, v178
	v_rcp_f32_e32 v179, v179
	v_add_f32_e32 v181, 1.0, v213
	v_rcp_f32_e32 v183, v183
	v_add_f32_e32 v224, 1.0, v154
	v_rcp_f32_e32 v225, v225
	v_add_f32_e32 v226, 1.0, v152
	v_rcp_f32_e32 v181, v181
	v_rcp_f32_e32 v224, v224
	v_rcp_f32_e32 v226, v226
	v_add_u32_e32 v182, 16, v0
	v_cvt_pk_bf16_f32 v178, v178, v179
	v_cvt_pk_bf16_f32 v179, v183, v225
	v_mad_i64_i32 v[182:183], s[0:1], v182, s47, v[134:135]
	v_cvt_pk_bf16_f32 v180, v180, v181
	v_cvt_pk_bf16_f32 v181, v224, v226
	v_lshl_add_u64 v[182:183], v[182:183], 0, v[136:137]
	global_store_dwordx4 v[182:183], v[178:181], off
	s_nop 1
	v_add_f32_e32 v179, 1.0, v211
	v_add_f32_e32 v178, 1.0, v212
	v_rcp_f32_e32 v180, v179
	v_add_f32_e32 v179, 1.0, v252
	v_add_f32_e32 v181, 1.0, v251
	v_add_f32_e32 v224, 1.0, v250
	v_add_f32_e32 v225, 1.0, v249
	v_add_f32_e32 v226, 1.0, v248
	v_add_f32_e32 v239, 1.0, v247
	v_rcp_f32_e32 v178, v178
	v_rcp_f32_e32 v179, v179
	v_rcp_f32_e32 v181, v181
	v_rcp_f32_e32 v224, v224
	v_rcp_f32_e32 v225, v225
	v_rcp_f32_e32 v226, v226
	v_rcp_f32_e32 v239, v239
	v_cvt_pk_bf16_f32 v178, v178, v179
	v_cvt_pk_bf16_f32 v180, v180, v181
	v_cvt_pk_bf16_f32 v179, v224, v226
	v_cvt_pk_bf16_f32 v181, v225, v239
	global_store_dwordx4 v[182:183], v[178:181], off offset:256
	s_nop 1
	v_add_f32_e32 v179, 1.0, v245
	v_add_f32_e32 v178, 1.0, v246
	v_rcp_f32_e32 v180, v179
	v_add_f32_e32 v179, 1.0, v244
	v_add_f32_e32 v183, 1.0, v242
	v_add_f32_e32 v225, 1.0, v184
	v_rcp_f32_e32 v178, v178
	v_rcp_f32_e32 v179, v179
	v_add_f32_e32 v181, 1.0, v243
	v_rcp_f32_e32 v183, v183
	v_add_f32_e32 v224, 1.0, v241
	v_rcp_f32_e32 v225, v225
	v_add_f32_e32 v226, 1.0, v177
	v_rcp_f32_e32 v181, v181
	v_rcp_f32_e32 v224, v224
	v_rcp_f32_e32 v226, v226
	v_add_u32_e32 v182, 32, v0
	v_cvt_pk_bf16_f32 v178, v178, v179
	v_cvt_pk_bf16_f32 v179, v183, v225
	v_mad_i64_i32 v[182:183], s[0:1], v182, s47, v[134:135]
	v_cvt_pk_bf16_f32 v180, v180, v181
	v_cvt_pk_bf16_f32 v181, v224, v226
	v_lshl_add_u64 v[182:183], v[182:183], 0, v[136:137]
	global_store_dwordx4 v[182:183], v[178:181], off
	s_nop 1
	v_add_f32_e32 v179, 1.0, v199
	v_add_f32_e32 v178, 1.0, v198
	v_rcp_f32_e32 v180, v179
	v_add_f32_e32 v179, 1.0, v197
	v_add_f32_e32 v181, 1.0, v196
	v_add_f32_e32 v224, 1.0, v195
	v_add_f32_e32 v225, 1.0, v194
	v_add_f32_e32 v226, 1.0, v193
	v_add_f32_e32 v239, 1.0, v192
	v_rcp_f32_e32 v178, v178
	v_rcp_f32_e32 v179, v179
	v_rcp_f32_e32 v181, v181
	v_rcp_f32_e32 v224, v224
	v_rcp_f32_e32 v225, v225
	v_rcp_f32_e32 v226, v226
	v_rcp_f32_e32 v239, v239
	v_cvt_pk_bf16_f32 v178, v178, v179
	v_cvt_pk_bf16_f32 v180, v180, v181
	v_cvt_pk_bf16_f32 v179, v224, v226
	v_cvt_pk_bf16_f32 v181, v225, v239
	global_store_dwordx4 v[182:183], v[178:181], off offset:256
	s_nop 1
	v_add_f32_e32 v179, 1.0, v190
	v_add_f32_e32 v178, 1.0, v191
	v_rcp_f32_e32 v180, v179
	v_add_f32_e32 v179, 1.0, v189
	v_add_f32_e32 v183, 1.0, v187
	v_add_f32_e32 v225, 1.0, v185
	v_rcp_f32_e32 v178, v178
	v_rcp_f32_e32 v179, v179
	v_add_f32_e32 v181, 1.0, v188
	v_rcp_f32_e32 v183, v183
	v_add_f32_e32 v224, 1.0, v186
	v_rcp_f32_e32 v225, v225
	v_add_f32_e32 v226, 1.0, v201
	v_rcp_f32_e32 v181, v181
	v_rcp_f32_e32 v224, v224
	v_rcp_f32_e32 v226, v226
	v_add_u32_e32 v182, 48, v0
	v_cvt_pk_bf16_f32 v178, v178, v179
	v_cvt_pk_bf16_f32 v179, v183, v225
	v_mad_i64_i32 v[182:183], s[0:1], v182, s47, v[134:135]
	v_cvt_pk_bf16_f32 v180, v180, v181
	v_cvt_pk_bf16_f32 v181, v224, v226
	v_lshl_add_u64 v[182:183], v[182:183], 0, v[136:137]
	global_store_dwordx4 v[182:183], v[178:181], off
	s_nop 1
	v_add_f32_e32 v179, 1.0, v221
	v_add_f32_e32 v178, 1.0, v200
	v_rcp_f32_e32 v180, v179
	v_add_f32_e32 v179, 1.0, v220
	v_add_f32_e32 v181, 1.0, v219
	v_add_f32_e32 v224, 1.0, v218
	v_add_f32_e32 v225, 1.0, v217
	v_add_f32_e32 v226, 1.0, v216
	v_add_f32_e32 v239, 1.0, v215
	v_rcp_f32_e32 v178, v178
	v_rcp_f32_e32 v179, v179
	v_rcp_f32_e32 v181, v181
	v_rcp_f32_e32 v224, v224
	v_rcp_f32_e32 v225, v225
	v_rcp_f32_e32 v226, v226
	v_rcp_f32_e32 v239, v239
	v_cvt_pk_bf16_f32 v178, v178, v179
	v_cvt_pk_bf16_f32 v180, v180, v181
	v_cvt_pk_bf16_f32 v179, v224, v226
	v_cvt_pk_bf16_f32 v181, v225, v239
	global_store_dwordx4 v[182:183], v[178:181], off offset:256
	s_nop 1
	v_add_f32_e32 v179, 1.0, v208
	v_add_f32_e32 v178, 1.0, v209
	v_rcp_f32_e32 v180, v179
	v_add_f32_e32 v179, 1.0, v207
	v_add_f32_e32 v183, 1.0, v205
	v_add_f32_e32 v225, 1.0, v203
	v_rcp_f32_e32 v178, v178
	v_rcp_f32_e32 v179, v179
	v_add_f32_e32 v181, 1.0, v206
	v_rcp_f32_e32 v183, v183
	v_add_f32_e32 v224, 1.0, v204
	v_rcp_f32_e32 v225, v225
	v_add_f32_e32 v226, 1.0, v202
	v_rcp_f32_e32 v181, v181
	v_rcp_f32_e32 v224, v224
	v_rcp_f32_e32 v226, v226
	v_add_u32_e32 v182, 0x80, v0
	v_cvt_pk_bf16_f32 v178, v178, v179
	v_cvt_pk_bf16_f32 v179, v183, v225
	v_mad_i64_i32 v[182:183], s[0:1], v182, s47, v[134:135]
	v_cvt_pk_bf16_f32 v180, v180, v181
	v_cvt_pk_bf16_f32 v181, v224, v226
	v_lshl_add_u64 v[182:183], v[182:183], 0, v[136:137]
	global_store_dwordx4 v[182:183], v[178:181], off
	s_nop 1
	v_add_f32_e32 v179, 1.0, v222
	v_rcp_f32_e32 v180, v179
	v_exp_f32_e32 v179, v237
	v_exp_f32_e32 v224, v236
	v_exp_f32_e32 v226, v234
	v_exp_f32_e32 v239, v233
	v_add_f32_e32 v179, 1.0, v179
	v_rcp_f32_e32 v225, v179
	v_exp_f32_e32 v179, v235
	v_add_f32_e32 v178, 1.0, v223
	v_add_f32_e32 v181, 1.0, v238
	v_add_f32_e32 v224, 1.0, v224
	v_add_f32_e32 v179, 1.0, v179
	v_rcp_f32_e32 v227, v179
	v_add_f32_e32 v179, 1.0, v226
	v_add_f32_e32 v226, 1.0, v239
	v_rcp_f32_e32 v178, v178
	v_rcp_f32_e32 v181, v181
	v_rcp_f32_e32 v224, v224
	v_rcp_f32_e32 v179, v179
	v_rcp_f32_e32 v226, v226
	v_cvt_pk_bf16_f32 v178, v178, v181
	v_cvt_pk_bf16_f32 v180, v180, v225
	v_cvt_pk_bf16_f32 v179, v224, v179
	v_cvt_pk_bf16_f32 v181, v227, v226
	global_store_dwordx4 v[182:183], v[178:181], off offset:256
	s_nop 1
	v_exp_f32_e32 v179, v231
	v_mul_f32_e32 v183, 0xbfb8aa3b, v52
	v_mul_f32_e32 v225, 0xbfb8aa3b, v53
	v_exp_f32_e32 v183, v183
	v_add_f32_e32 v179, 1.0, v179
	v_rcp_f32_e32 v181, v179
	v_exp_f32_e32 v179, v229
	v_exp_f32_e32 v225, v225
	v_mul_f32_e32 v226, 0xbfb8aa3b, v45
	v_exp_f32_e32 v178, v232
	v_add_f32_e32 v179, 1.0, v179
	v_rcp_f32_e32 v224, v179
	v_mul_f32_e32 v179, 0xbfb8aa3b, v44
	v_exp_f32_e32 v179, v179
	v_exp_f32_e32 v180, v230
	v_exp_f32_e32 v226, v226
	v_add_f32_e32 v183, 1.0, v183
	v_add_f32_e32 v179, 1.0, v179
	v_rcp_f32_e32 v227, v179
	v_add_f32_e32 v179, 1.0, v225
	v_add_f32_e32 v178, 1.0, v178
	v_add_f32_e32 v180, 1.0, v180
	v_rcp_f32_e32 v183, v183
	v_rcp_f32_e32 v179, v179
	v_add_f32_e32 v225, 1.0, v226
	v_rcp_f32_e32 v178, v178
	v_rcp_f32_e32 v180, v180
	v_rcp_f32_e32 v225, v225
	v_add_u32_e32 v182, 0x90, v0
	v_cvt_pk_bf16_f32 v179, v183, v179
	v_mad_i64_i32 v[182:183], s[0:1], v182, s47, v[134:135]
	v_cvt_pk_bf16_f32 v178, v178, v180
	v_cvt_pk_bf16_f32 v180, v181, v224
	v_cvt_pk_bf16_f32 v181, v227, v225
	v_lshl_add_u64 v[182:183], v[182:183], 0, v[136:137]
	global_store_dwordx4 v[182:183], v[178:181], off
	s_nop 1
	v_mul_f32_e32 v179, 0xbfb8aa3b, v30
	v_exp_f32_e32 v179, v179
	v_mul_f32_e32 v178, 0xbfb8aa3b, v38
	v_mul_f32_e32 v180, 0xbfb8aa3b, v39
	v_mul_f32_e32 v224, 0xbfb8aa3b, v40
	v_add_f32_e32 v179, 1.0, v179
	v_rcp_f32_e32 v181, v179
	v_mul_f32_e32 v179, 0xbfb8aa3b, v31
	v_exp_f32_e32 v179, v179
	v_mul_f32_e32 v226, 0xbfb8aa3b, v41
	v_mul_f32_e32 v227, 0xbfb8aa3b, v33
	v_exp_f32_e32 v178, v178
	v_add_f32_e32 v179, 1.0, v179
	v_rcp_f32_e32 v225, v179
	v_mul_f32_e32 v179, 0xbfb8aa3b, v32
	v_exp_f32_e32 v179, v179
	v_exp_f32_e32 v180, v180
	v_exp_f32_e32 v224, v224
	v_exp_f32_e32 v226, v226
	v_exp_f32_e32 v227, v227
	v_add_f32_e32 v179, 1.0, v179
	v_add_f32_e32 v178, 1.0, v178
	v_add_f32_e32 v180, 1.0, v180
	v_add_f32_e32 v224, 1.0, v224
	v_rcp_f32_e32 v239, v179
	v_add_f32_e32 v179, 1.0, v226
	v_add_f32_e32 v226, 1.0, v227
	v_rcp_f32_e32 v178, v178
	v_rcp_f32_e32 v180, v180
	v_rcp_f32_e32 v224, v224
	v_rcp_f32_e32 v179, v179
	v_rcp_f32_e32 v226, v226
	v_cvt_pk_bf16_f32 v178, v178, v180
	v_cvt_pk_bf16_f32 v180, v181, v225
	v_cvt_pk_bf16_f32 v179, v224, v179
	v_cvt_pk_bf16_f32 v181, v239, v226
	global_store_dwordx4 v[182:183], v[178:181], off offset:256
	s_nop 1
	v_mul_f32_e32 v179, 0xbfb8aa3b, v26
	v_exp_f32_e32 v179, v179
	v_mul_f32_e32 v183, 0xbfb8aa3b, v36
	v_mul_f32_e32 v225, 0xbfb8aa3b, v37
	v_mul_f32_e32 v178, 0xbfb8aa3b, v34
	v_add_f32_e32 v179, 1.0, v179
	v_rcp_f32_e32 v181, v179
	v_mul_f32_e32 v179, 0xbfb8aa3b, v27
	v_exp_f32_e32 v179, v179
	v_mul_f32_e32 v180, 0xbfb8aa3b, v35
	v_exp_f32_e32 v183, v183
	v_exp_f32_e32 v225, v225
	v_add_f32_e32 v179, 1.0, v179
	v_rcp_f32_e32 v224, v179
	v_mul_f32_e32 v179, 0xbfb8aa3b, v28
	v_exp_f32_e32 v179, v179
	v_mul_f32_e32 v226, 0xbfb8aa3b, v29
	v_exp_f32_e32 v178, v178
	v_exp_f32_e32 v180, v180
	v_exp_f32_e32 v226, v226
	v_add_f32_e32 v179, 1.0, v179
	v_add_f32_e32 v183, 1.0, v183
	v_rcp_f32_e32 v227, v179
	v_add_f32_e32 v179, 1.0, v225
	v_add_f32_e32 v178, 1.0, v178
	v_add_f32_e32 v180, 1.0, v180
	v_rcp_f32_e32 v183, v183
	v_rcp_f32_e32 v179, v179
	v_add_f32_e32 v225, 1.0, v226
	v_rcp_f32_e32 v178, v178
	v_rcp_f32_e32 v180, v180
	v_rcp_f32_e32 v225, v225
	v_add_u32_e32 v182, 0xa0, v0
	v_cvt_pk_bf16_f32 v179, v183, v179
	v_mad_i64_i32 v[182:183], s[0:1], v182, s47, v[134:135]
	v_cvt_pk_bf16_f32 v178, v178, v180
	v_cvt_pk_bf16_f32 v180, v181, v224
	v_cvt_pk_bf16_f32 v181, v227, v225
	v_lshl_add_u64 v[182:183], v[182:183], 0, v[136:137]
	global_store_dwordx4 v[182:183], v[178:181], off
	s_nop 1
	v_mul_f32_e32 v179, 0xbfb8aa3b, v14
	v_exp_f32_e32 v179, v179
	v_mul_f32_e32 v178, 0xbfb8aa3b, v22
	v_mul_f32_e32 v180, 0xbfb8aa3b, v23
	v_mul_f32_e32 v224, 0xbfb8aa3b, v24
	v_add_f32_e32 v179, 1.0, v179
	v_rcp_f32_e32 v181, v179
	v_mul_f32_e32 v179, 0xbfb8aa3b, v15
	v_exp_f32_e32 v179, v179
	v_mul_f32_e32 v226, 0xbfb8aa3b, v25
	v_mul_f32_e32 v227, 0xbfb8aa3b, v17
	v_exp_f32_e32 v178, v178
	v_add_f32_e32 v179, 1.0, v179
	v_rcp_f32_e32 v225, v179
	v_mul_f32_e32 v179, 0xbfb8aa3b, v16
	v_exp_f32_e32 v179, v179
	v_exp_f32_e32 v180, v180
	v_exp_f32_e32 v224, v224
	v_exp_f32_e32 v226, v226
	v_exp_f32_e32 v227, v227
	v_add_f32_e32 v179, 1.0, v179
	v_add_f32_e32 v178, 1.0, v178
	v_add_f32_e32 v180, 1.0, v180
	v_add_f32_e32 v224, 1.0, v224
	v_rcp_f32_e32 v239, v179
	v_add_f32_e32 v179, 1.0, v226
	v_add_f32_e32 v226, 1.0, v227
	v_rcp_f32_e32 v178, v178
	v_rcp_f32_e32 v180, v180
	v_rcp_f32_e32 v224, v224
	v_rcp_f32_e32 v179, v179
	v_rcp_f32_e32 v226, v226
	v_cvt_pk_bf16_f32 v178, v178, v180
	v_cvt_pk_bf16_f32 v180, v181, v225
	v_cvt_pk_bf16_f32 v179, v224, v179
	v_cvt_pk_bf16_f32 v181, v239, v226
	global_store_dwordx4 v[182:183], v[178:181], off offset:256
	s_nop 1
	v_mul_f32_e32 v179, 0xbfb8aa3b, v10
	v_exp_f32_e32 v179, v179
	v_mul_f32_e32 v180, 0xbfb8aa3b, v19
	v_mul_f32_e32 v181, 0xbfb8aa3b, v11
	v_exp_f32_e32 v180, v180
	v_exp_f32_e32 v181, v181
	v_add_f32_e32 v179, 1.0, v179
	v_rcp_f32_e32 v182, v179
	v_add_f32_e32 v179, 1.0, v180
	v_add_f32_e32 v180, 1.0, v181
	v_mul_f32_e32 v181, 0xbfb8aa3b, v20
	v_mul_f32_e32 v183, 0xbfb8aa3b, v12
	v_mul_f32_e32 v224, 0xbfb8aa3b, v21
	v_mul_f32_e32 v225, 0xbfb8aa3b, v13
	v_exp_f32_e32 v178, v228
	v_exp_f32_e32 v181, v181
	v_exp_f32_e32 v183, v183
	v_exp_f32_e32 v224, v224
	v_exp_f32_e32 v225, v225
	v_add_f32_e32 v178, 1.0, v178
	v_add_f32_e32 v181, 1.0, v181
	v_add_f32_e32 v183, 1.0, v183
	v_add_f32_e32 v224, 1.0, v224
	v_add_f32_e32 v225, 1.0, v225
	v_rcp_f32_e32 v178, v178
	v_rcp_f32_e32 v179, v179
	v_rcp_f32_e32 v180, v180
	v_rcp_f32_e32 v181, v181
	v_rcp_f32_e32 v183, v183
	v_rcp_f32_e32 v224, v224
	v_rcp_f32_e32 v225, v225
	v_add_u32_e32 v0, 0xb0, v0
	v_mad_i64_i32 v[134:135], s[0:1], v0, s47, v[134:135]
	v_cvt_pk_bf16_f32 v178, v178, v179
	v_cvt_pk_bf16_f32 v179, v181, v224
	v_cvt_pk_bf16_f32 v180, v182, v180
	v_cvt_pk_bf16_f32 v181, v183, v225
	v_lshl_add_u64 v[182:183], v[134:135], 0, v[136:137]
	global_store_dwordx4 v[182:183], v[178:181], off
	v_mul_f32_e32 v134, 0xbfb8aa3b, v2
	v_exp_f32_e32 v134, v134
	v_mul_f32_e32 v135, 0xbfb8aa3b, v7
	v_mul_f32_e32 v136, 0xbfb8aa3b, v3
	v_exp_f32_e32 v135, v135
	v_exp_f32_e32 v136, v136
	v_add_f32_e32 v134, 1.0, v134
	v_rcp_f32_e32 v137, v134
	v_add_f32_e32 v134, 1.0, v135
	v_add_f32_e32 v135, 1.0, v136
	v_mul_f32_e32 v136, 0xbfb8aa3b, v8
	v_mul_f32_e32 v178, 0xbfb8aa3b, v4
	v_exp_f32_e32 v136, v136
	v_exp_f32_e32 v178, v178
	v_mul_f32_e32 v0, 0xbfb8aa3b, v6
	v_rcp_f32_e32 v179, v135
	v_add_f32_e32 v135, 1.0, v136
	v_add_f32_e32 v136, 1.0, v178
	v_mul_f32_e32 v178, 0xbfb8aa3b, v9
	v_mul_f32_e32 v180, 0xbfb8aa3b, v5
	v_exp_f32_e32 v0, v0
	v_exp_f32_e32 v178, v178
	v_exp_f32_e32 v180, v180
	v_rcp_f32_e32 v181, v136
	v_add_f32_e32 v0, 1.0, v0
	v_add_f32_e32 v136, 1.0, v178
	v_add_f32_e32 v178, 1.0, v180
	v_rcp_f32_e32 v0, v0
	v_rcp_f32_e32 v134, v134
	v_rcp_f32_e32 v135, v135
	v_rcp_f32_e32 v136, v136
	v_rcp_f32_e32 v178, v178
	v_cvt_pk_bf16_f32 v134, v0, v134
	v_cvt_pk_bf16_f32 v135, v135, v136
	v_cvt_pk_bf16_f32 v136, v137, v179
	v_cvt_pk_bf16_f32 v137, v181, v178
	global_store_dwordx4 v[182:183], v[134:137], off offset:256
	s_mov_b64 s[0:1], 0

.LBB0_726:
	s_xor_b64 s[6:7], s[26:27], -1
	s_add_i32 vcc_lo, s14, 32
	s_lshl_b64 s[12:13], s[14:15], 7
	s_mov_b64 s[22:23], 0x1f00
	v_mov_b64_e32 v[130:131], v[158:159]
	v_mov_b64_e32 v[132:133], v[156:157]
	s_mov_b64 s[26:27], s[8:9]
	s_mov_b64 s[30:31], s[0:1]
	v_add_u32_e32 v224, 0x10000, v149
	v_add_u32_e32 v225, 0x14000, v149
	v_add_u32_e32 v226, 0x18000, v149
	v_add_u32_e32 v227, 0x1c000, v149
.LBB0_727:
	s_add_i32 s14, s14, 2
	s_add_u32 s40, s30, s12
	s_addc_u32 s41, s31, s13
	s_add_u32 s84, s26, s12
	s_addc_u32 s85, s27, s13
	s_add_i32 s86, 0, 0x10000
	ds_read_b128 v[134:137], v224
	ds_read_b128 v[152:155], v224 offset:1024
	ds_read_b128 v[162:165], v224 offset:2048
	ds_read_b128 v[166:169], v224 offset:3072
	s_cmp_eq_u32 s12, s22
	s_cselect_b32 s61, s51, s41
	s_cselect_b32 s60, s50, s40
	s_cselect_b32 s41, s49, s85
	s_cselect_b32 s40, s80, s84
	v_lshl_add_u64 v[202:203], v[132:133], 0, s[12:13]
	s_add_i32 m0, s66, 0xc000
	ds_read_b128 v[170:173], v160
	ds_read_b128 v[174:177], v160 offset:1024
	ds_read_b128 v[178:181], v160 offset:2048
	ds_read_b128 v[182:185], v160 offset:3072
	ds_read_b128 v[186:189], v160 offset:4096
	ds_read_b128 v[190:193], v160 offset:5120
	ds_read_b128 v[194:197], v160 offset:6144
	ds_read_b128 v[198:201], v160 offset:7168
	global_load_lds_dwordx4 v[202:203], off
	v_lshl_add_u64 v[202:203], v[130:131], 0, s[12:13]
	s_add_i32 m0, s66, 0xe000
	s_nop 0
	global_load_lds_dwordx4 v[202:203], off
	s_waitcnt lgkmcnt(8)
	s_barrier
	s_setprio 1
	s_waitcnt lgkmcnt(7)
	v_mfma_f32_16x16x32_bf16 v[126:129], v[134:137], v[170:173], v[126:129]
	v_mfma_f32_16x16x32_bf16 v[122:125], v[162:165], v[170:173], v[122:125]
	s_waitcnt lgkmcnt(5)
	v_mfma_f32_16x16x32_bf16 v[110:113], v[134:137], v[178:181], v[110:113]
	v_mfma_f32_16x16x32_bf16 v[106:109], v[162:165], v[178:181], v[106:109]
	s_waitcnt lgkmcnt(3)
	v_mfma_f32_16x16x32_bf16 v[94:97], v[134:137], v[186:189], v[94:97]
	v_mfma_f32_16x16x32_bf16 v[90:93], v[162:165], v[186:189], v[90:93]
	s_waitcnt lgkmcnt(1)
	v_mfma_f32_16x16x32_bf16 v[78:81], v[134:137], v[194:197], v[78:81]
	v_mfma_f32_16x16x32_bf16 v[74:77], v[162:165], v[194:197], v[74:77]
	v_mfma_f32_16x16x32_bf16 v[126:129], v[152:155], v[174:177], v[126:129]
	v_mfma_f32_16x16x32_bf16 v[122:125], v[166:169], v[174:177], v[122:125]
	v_mfma_f32_16x16x32_bf16 v[110:113], v[152:155], v[182:185], v[110:113]
	v_mfma_f32_16x16x32_bf16 v[106:109], v[166:169], v[182:185], v[106:109]
	v_mfma_f32_16x16x32_bf16 v[94:97], v[152:155], v[190:193], v[94:97]
	v_mfma_f32_16x16x32_bf16 v[90:93], v[166:169], v[190:193], v[90:93]
	s_waitcnt lgkmcnt(0)
	v_mfma_f32_16x16x32_bf16 v[78:81], v[152:155], v[198:201], v[78:81]
	v_mfma_f32_16x16x32_bf16 v[74:77], v[166:169], v[198:201], v[74:77]
	s_setprio 0
	s_barrier
	s_add_i32 s87, 0, 0x14000
	s_add_i32 s84, s86, s65
	s_mov_b32 m0, s84
	ds_read_b128 v[202:205], v225
	ds_read_b128 v[206:209], v225 offset:1024
	ds_read_b128 v[216:219], v225 offset:2048
	global_load_lds_dwordx4 v0, s[40:41]
	s_add_i32 m0, s84, 0x2000
	ds_read_b128 v[220:223], v225 offset:3072
	global_load_lds_dwordx4 v138, s[40:41]
	s_barrier
	s_setprio 1
	s_waitcnt lgkmcnt(3)
	v_mfma_f32_16x16x32_bf16 v[118:121], v[202:205], v[170:173], v[118:121]
	s_waitcnt lgkmcnt(1)
	v_mfma_f32_16x16x32_bf16 v[114:117], v[216:219], v[170:173], v[114:117]
	v_mfma_f32_16x16x32_bf16 v[102:105], v[202:205], v[178:181], v[102:105]
	v_mfma_f32_16x16x32_bf16 v[98:101], v[216:219], v[178:181], v[98:101]
	v_mfma_f32_16x16x32_bf16 v[86:89], v[202:205], v[186:189], v[86:89]
	v_mfma_f32_16x16x32_bf16 v[82:85], v[216:219], v[186:189], v[82:85]
	v_mfma_f32_16x16x32_bf16 v[70:73], v[202:205], v[194:197], v[70:73]
	v_mfma_f32_16x16x32_bf16 v[66:69], v[216:219], v[194:197], v[66:69]
	v_mfma_f32_16x16x32_bf16 v[118:121], v[206:209], v[174:177], v[118:121]
	s_waitcnt lgkmcnt(0)
	v_mfma_f32_16x16x32_bf16 v[114:117], v[220:223], v[174:177], v[114:117]
	v_mfma_f32_16x16x32_bf16 v[102:105], v[206:209], v[182:185], v[102:105]
	v_mfma_f32_16x16x32_bf16 v[98:101], v[220:223], v[182:185], v[98:101]
	v_mfma_f32_16x16x32_bf16 v[86:89], v[206:209], v[190:193], v[86:89]
	v_mfma_f32_16x16x32_bf16 v[82:85], v[220:223], v[190:193], v[82:85]
	v_mfma_f32_16x16x32_bf16 v[70:73], v[206:209], v[198:201], v[70:73]
	v_mfma_f32_16x16x32_bf16 v[66:69], v[220:223], v[198:201], v[66:69]
	s_setprio 0
	s_mov_b32 m0, s66
	s_add_u32 s98, s60, 0x80
	s_addc_u32 s99, s61, 0
	s_barrier
	ds_read_b128 v[170:173], v160 offset:16384
	ds_read_b128 v[174:177], v160 offset:17408
	ds_read_b128 v[178:181], v160 offset:18432
	ds_read_b128 v[182:185], v160 offset:19456
	ds_read_b128 v[186:189], v160 offset:20480
	ds_read_b128 v[190:193], v160 offset:21504
	ds_read_b128 v[194:197], v160 offset:22528
	global_load_lds_dwordx4 v142, s[60:61]
	s_mov_b32 m0, s67
	ds_read_b128 v[198:201], v160 offset:23552
	global_load_lds_dwordx4 v140, s[60:61]
	s_barrier
	s_setprio 1
	s_waitcnt lgkmcnt(7)
	v_mfma_f32_16x16x32_bf16 v[62:65], v[134:137], v[170:173], v[62:65]
	v_mfma_f32_16x16x32_bf16 v[58:61], v[162:165], v[170:173], v[58:61]
	s_waitcnt lgkmcnt(5)
	v_mfma_f32_16x16x32_bf16 v[46:49], v[134:137], v[178:181], v[46:49]
	v_mfma_f32_16x16x32_bf16 v[42:45], v[162:165], v[178:181], v[42:45]
	s_waitcnt lgkmcnt(3)
	v_mfma_f32_16x16x32_bf16 v[30:33], v[134:137], v[186:189], v[30:33]
	v_mfma_f32_16x16x32_bf16 v[26:29], v[162:165], v[186:189], v[26:29]
	s_waitcnt lgkmcnt(1)
	v_mfma_f32_16x16x32_bf16 v[14:17], v[134:137], v[194:197], v[14:17]
	v_mfma_f32_16x16x32_bf16 v[10:13], v[162:165], v[194:197], v[10:13]
	v_mfma_f32_16x16x32_bf16 v[62:65], v[152:155], v[174:177], v[62:65]
	v_mfma_f32_16x16x32_bf16 v[58:61], v[166:169], v[174:177], v[58:61]
	v_mfma_f32_16x16x32_bf16 v[46:49], v[152:155], v[182:185], v[46:49]
	v_mfma_f32_16x16x32_bf16 v[42:45], v[166:169], v[182:185], v[42:45]
	v_mfma_f32_16x16x32_bf16 v[30:33], v[152:155], v[190:193], v[30:33]
	v_mfma_f32_16x16x32_bf16 v[26:29], v[166:169], v[190:193], v[26:29]
	s_waitcnt lgkmcnt(0)
	v_mfma_f32_16x16x32_bf16 v[14:17], v[152:155], v[198:201], v[14:17]
	v_mfma_f32_16x16x32_bf16 v[10:13], v[166:169], v[198:201], v[10:13]
	s_setprio 0
	s_barrier
	s_add_i32 s86, s87, s65
	s_mov_b32 m0, s86
	s_add_u32 s84, s40, 0x100000
	s_addc_u32 s85, s41, 0
	global_load_lds_dwordx4 v0, s[84:85]
	s_add_i32 m0, s86, 0x2000
	s_nop 0
	global_load_lds_dwordx4 v138, s[84:85]
	s_waitcnt vmcnt(6)
	s_barrier
	s_setprio 1
	v_mfma_f32_16x16x32_bf16 v[54:57], v[202:205], v[170:173], v[54:57]
	v_mfma_f32_16x16x32_bf16 v[50:53], v[216:219], v[170:173], v[50:53]
	v_mfma_f32_16x16x32_bf16 v[38:41], v[202:205], v[178:181], v[38:41]
	v_mfma_f32_16x16x32_bf16 v[34:37], v[216:219], v[178:181], v[34:37]
	v_mfma_f32_16x16x32_bf16 v[22:25], v[202:205], v[186:189], v[22:25]
	v_mfma_f32_16x16x32_bf16 v[18:21], v[216:219], v[186:189], v[18:21]
	v_mfma_f32_16x16x32_bf16 v[6:9], v[202:205], v[194:197], v[6:9]
	v_mfma_f32_16x16x32_bf16 v[2:5], v[216:219], v[194:197], v[2:5]
	v_mfma_f32_16x16x32_bf16 v[54:57], v[206:209], v[174:177], v[54:57]
	v_mfma_f32_16x16x32_bf16 v[50:53], v[220:223], v[174:177], v[50:53]
	v_mfma_f32_16x16x32_bf16 v[38:41], v[206:209], v[182:185], v[38:41]
	v_mfma_f32_16x16x32_bf16 v[34:37], v[220:223], v[182:185], v[34:37]
	v_mfma_f32_16x16x32_bf16 v[22:25], v[206:209], v[190:193], v[22:25]
	v_mfma_f32_16x16x32_bf16 v[18:21], v[220:223], v[190:193], v[18:21]
	v_mfma_f32_16x16x32_bf16 v[6:9], v[206:209], v[198:201], v[6:9]
	v_mfma_f32_16x16x32_bf16 v[2:5], v[220:223], v[198:201], v[2:5]
	s_setprio 0
	s_add_i32 s84, 0, 0x18000
	s_barrier
	ds_read_b128 v[134:137], v226
	ds_read_b128 v[152:155], v226 offset:1024
	ds_read_b128 v[162:165], v226 offset:2048
	ds_read_b128 v[166:169], v226 offset:3072
	s_add_u32 s60, s60, 0x100000
	s_addc_u32 s61, s61, 0
	s_mov_b32 m0, s68
	ds_read_b128 v[170:173], v160 offset:32768
	ds_read_b128 v[174:177], v160 offset:33792
	ds_read_b128 v[178:181], v160 offset:34816
	ds_read_b128 v[182:185], v160 offset:35840
	ds_read_b128 v[186:189], v160 offset:36864
	ds_read_b128 v[190:193], v160 offset:37888
	ds_read_b128 v[194:197], v160 offset:38912
	global_load_lds_dwordx4 v142, s[60:61]
	s_mov_b32 m0, s69
	ds_read_b128 v[198:201], v160 offset:39936
	global_load_lds_dwordx4 v140, s[60:61]
	s_waitcnt lgkmcnt(8)
	s_barrier
	s_setprio 1
	s_waitcnt lgkmcnt(7)
	v_mfma_f32_16x16x32_bf16 v[126:129], v[134:137], v[170:173], v[126:129]
	v_mfma_f32_16x16x32_bf16 v[122:125], v[162:165], v[170:173], v[122:125]
	s_waitcnt lgkmcnt(5)
	v_mfma_f32_16x16x32_bf16 v[110:113], v[134:137], v[178:181], v[110:113]
	v_mfma_f32_16x16x32_bf16 v[106:109], v[162:165], v[178:181], v[106:109]
	s_waitcnt lgkmcnt(3)
	v_mfma_f32_16x16x32_bf16 v[94:97], v[134:137], v[186:189], v[94:97]
	v_mfma_f32_16x16x32_bf16 v[90:93], v[162:165], v[186:189], v[90:93]
	s_waitcnt lgkmcnt(1)
	v_mfma_f32_16x16x32_bf16 v[78:81], v[134:137], v[194:197], v[78:81]
	v_mfma_f32_16x16x32_bf16 v[74:77], v[162:165], v[194:197], v[74:77]
	v_mfma_f32_16x16x32_bf16 v[126:129], v[152:155], v[174:177], v[126:129]
	v_mfma_f32_16x16x32_bf16 v[122:125], v[166:169], v[174:177], v[122:125]
	v_mfma_f32_16x16x32_bf16 v[110:113], v[152:155], v[182:185], v[110:113]
	v_mfma_f32_16x16x32_bf16 v[106:109], v[166:169], v[182:185], v[106:109]
	v_mfma_f32_16x16x32_bf16 v[94:97], v[152:155], v[190:193], v[94:97]
	v_mfma_f32_16x16x32_bf16 v[90:93], v[166:169], v[190:193], v[90:93]
	s_waitcnt lgkmcnt(0)
	v_mfma_f32_16x16x32_bf16 v[78:81], v[152:155], v[198:201], v[78:81]
	v_mfma_f32_16x16x32_bf16 v[74:77], v[166:169], v[198:201], v[74:77]
	s_setprio 0
	s_barrier
	s_add_i32 s60, 0, 0x1c000
	s_add_i32 s61, s84, s65
	s_add_u32 s100, s40, 0x80
	s_addc_u32 s101, s41, 0
	s_mov_b32 m0, s61
	ds_read_b128 v[202:205], v227
	ds_read_b128 v[206:209], v227 offset:1024
	ds_read_b128 v[216:219], v227 offset:2048
	global_load_lds_dwordx4 v0, s[100:101]
	s_add_i32 m0, s61, 0x2000
	ds_read_b128 v[220:223], v227 offset:3072
	global_load_lds_dwordx4 v138, s[100:101]
	s_barrier
	s_setprio 1
	s_waitcnt lgkmcnt(3)
	v_mfma_f32_16x16x32_bf16 v[118:121], v[202:205], v[170:173], v[118:121]
	s_waitcnt lgkmcnt(1)
	v_mfma_f32_16x16x32_bf16 v[114:117], v[216:219], v[170:173], v[114:117]
	v_mfma_f32_16x16x32_bf16 v[102:105], v[202:205], v[178:181], v[102:105]
	v_mfma_f32_16x16x32_bf16 v[98:101], v[216:219], v[178:181], v[98:101]
	v_mfma_f32_16x16x32_bf16 v[86:89], v[202:205], v[186:189], v[86:89]
	v_mfma_f32_16x16x32_bf16 v[82:85], v[216:219], v[186:189], v[82:85]
	v_mfma_f32_16x16x32_bf16 v[70:73], v[202:205], v[194:197], v[70:73]
	v_mfma_f32_16x16x32_bf16 v[66:69], v[216:219], v[194:197], v[66:69]
	v_mfma_f32_16x16x32_bf16 v[118:121], v[206:209], v[174:177], v[118:121]
	s_waitcnt lgkmcnt(0)
	v_mfma_f32_16x16x32_bf16 v[114:117], v[220:223], v[174:177], v[114:117]
	v_mfma_f32_16x16x32_bf16 v[102:105], v[206:209], v[182:185], v[102:105]
	v_mfma_f32_16x16x32_bf16 v[98:101], v[220:223], v[182:185], v[98:101]
	v_mfma_f32_16x16x32_bf16 v[86:89], v[206:209], v[190:193], v[86:89]
	v_mfma_f32_16x16x32_bf16 v[82:85], v[220:223], v[190:193], v[82:85]
	v_mfma_f32_16x16x32_bf16 v[70:73], v[206:209], v[198:201], v[70:73]
	v_mfma_f32_16x16x32_bf16 v[66:69], v[220:223], v[198:201], v[66:69]
	s_setprio 0
	s_mov_b32 m0, s76
	s_barrier
	ds_read_b128 v[170:173], v160 offset:49152
	ds_read_b128 v[174:177], v160 offset:50176
	ds_read_b128 v[178:181], v160 offset:51200
	ds_read_b128 v[182:185], v160 offset:52224
	ds_read_b128 v[186:189], v160 offset:53248
	ds_read_b128 v[190:193], v160 offset:54272
	ds_read_b128 v[194:197], v160 offset:55296
	global_load_lds_dwordx4 v142, s[98:99]
	s_mov_b32 m0, s77
	ds_read_b128 v[198:201], v160 offset:56320
	global_load_lds_dwordx4 v140, s[98:99]
	s_barrier
	s_setprio 1
	s_waitcnt lgkmcnt(7)
	v_mfma_f32_16x16x32_bf16 v[62:65], v[134:137], v[170:173], v[62:65]
	v_mfma_f32_16x16x32_bf16 v[58:61], v[162:165], v[170:173], v[58:61]
	s_waitcnt lgkmcnt(5)
	v_mfma_f32_16x16x32_bf16 v[46:49], v[134:137], v[178:181], v[46:49]
	v_mfma_f32_16x16x32_bf16 v[42:45], v[162:165], v[178:181], v[42:45]
	s_waitcnt lgkmcnt(3)
	v_mfma_f32_16x16x32_bf16 v[30:33], v[134:137], v[186:189], v[30:33]
	v_mfma_f32_16x16x32_bf16 v[26:29], v[162:165], v[186:189], v[26:29]
	s_waitcnt lgkmcnt(1)
	v_mfma_f32_16x16x32_bf16 v[14:17], v[134:137], v[194:197], v[14:17]
	v_mfma_f32_16x16x32_bf16 v[10:13], v[162:165], v[194:197], v[10:13]
	v_mfma_f32_16x16x32_bf16 v[62:65], v[152:155], v[174:177], v[62:65]
	v_mfma_f32_16x16x32_bf16 v[58:61], v[166:169], v[174:177], v[58:61]
	v_mfma_f32_16x16x32_bf16 v[46:49], v[152:155], v[182:185], v[46:49]
	v_mfma_f32_16x16x32_bf16 v[42:45], v[166:169], v[182:185], v[42:45]
	v_mfma_f32_16x16x32_bf16 v[30:33], v[152:155], v[190:193], v[30:33]
	v_mfma_f32_16x16x32_bf16 v[26:29], v[166:169], v[190:193], v[26:29]
	s_waitcnt lgkmcnt(0)
	v_mfma_f32_16x16x32_bf16 v[14:17], v[152:155], v[198:201], v[14:17]
	v_mfma_f32_16x16x32_bf16 v[10:13], v[166:169], v[198:201], v[10:13]
	s_setprio 0
	s_barrier
	s_add_i32 s60, s60, s65
	s_mov_b32 m0, s60
	s_add_u32 s40, s40, 0x100080
	s_addc_u32 s41, s41, 0
	global_load_lds_dwordx4 v0, s[40:41]
	s_add_i32 m0, s60, 0x2000
	s_nop 0
	global_load_lds_dwordx4 v138, s[40:41]
	s_waitcnt vmcnt(6)
	s_barrier
	s_setprio 1
	v_mfma_f32_16x16x32_bf16 v[54:57], v[202:205], v[170:173], v[54:57]
	v_mfma_f32_16x16x32_bf16 v[50:53], v[216:219], v[170:173], v[50:53]
	v_mfma_f32_16x16x32_bf16 v[38:41], v[202:205], v[178:181], v[38:41]
	v_mfma_f32_16x16x32_bf16 v[34:37], v[216:219], v[178:181], v[34:37]
	v_mfma_f32_16x16x32_bf16 v[22:25], v[202:205], v[186:189], v[22:25]
	v_mfma_f32_16x16x32_bf16 v[18:21], v[216:219], v[186:189], v[18:21]
	v_mfma_f32_16x16x32_bf16 v[6:9], v[202:205], v[194:197], v[6:9]
	v_mfma_f32_16x16x32_bf16 v[2:5], v[216:219], v[194:197], v[2:5]
	v_mfma_f32_16x16x32_bf16 v[54:57], v[206:209], v[174:177], v[54:57]
	v_mfma_f32_16x16x32_bf16 v[50:53], v[220:223], v[174:177], v[50:53]
	v_mfma_f32_16x16x32_bf16 v[38:41], v[206:209], v[182:185], v[38:41]
	v_mfma_f32_16x16x32_bf16 v[34:37], v[220:223], v[182:185], v[34:37]
	v_mfma_f32_16x16x32_bf16 v[22:25], v[206:209], v[190:193], v[22:25]
	v_mfma_f32_16x16x32_bf16 v[18:21], v[220:223], v[190:193], v[18:21]
	v_mfma_f32_16x16x32_bf16 v[6:9], v[206:209], v[198:201], v[6:9]
	v_mfma_f32_16x16x32_bf16 v[2:5], v[220:223], v[198:201], v[2:5]
	s_setprio 0
	s_add_u32 s30, s30, 0x100
	s_addc_u32 s31, s31, 0
	s_add_u32 s26, s26, 0x100
	s_addc_u32 s27, s27, 0
	s_add_u32 s22, s22, 0xffffff00
	s_addc_u32 s23, s23, -1
	v_lshl_add_u64 v[132:133], v[132:133], 0, s[18:19]
	s_cmp_ge_u32 s14, vcc_lo
	v_lshl_add_u64 v[130:131], v[130:131], 0, s[18:19]
	s_barrier
	s_cbranch_scc0 .LBB0_727
	s_mov_b32 s14, 32
	s_mov_b64 s[26:27], 0
	s_andn2_b64 vcc, exec, s[6:7]
	s_mov_b64 s[6:7], -1
	s_cbranch_vccnz .LBB0_724
	v_mov_b32_e32 v130, v148
	v_mov_b64_e32 v[134:135], s[38:39]
	v_and_or_b32 v132, v130, 15, s82
	v_lshrrev_b32_e32 v130, 1, v130
	v_and_or_b32 v130, v130, 24, s75
	v_or_b32_e32 v130, s81, v130
	s_mov_b32 s14, s48
	v_ashrrev_i32_e32 v131, 31, v130
	v_mad_i64_i32 v[136:137], s[0:1], v132, s47, v[134:135]
	v_lshlrev_b64 v[130:131], 1, v[130:131]
	v_lshl_add_u64 v[136:137], v[136:137], 0, v[130:131]
	v_add_co_u32_e32 v152, vcc, s72, v136
	v_ashrrev_i32_e32 v133, 31, v132
	s_nop 0
	v_addc_co_u32_e32 v153, vcc, 0, v137, vcc
	global_load_dwordx4 v[152:155], v[152:153], off
	v_lshlrev_b64 v[156:157], 12, v[132:133]
	v_lshl_add_u64 v[156:157], s[28:29], 0, v[156:157]
	v_lshl_add_u64 v[156:157], v[156:157], 0, v[130:131]
	v_lshl_add_u64 v[136:137], v[136:137], 0, s[34:35]
	s_mov_b32 s22, s79
	s_mov_b64 s[6:7], s[52:53]
	s_mov_b64 s[12:13], s[50:51]
	s_waitcnt vmcnt(0)
	v_lshlrev_b32_e32 v158, 16, v152
	v_and_b32_e32 v159, 0xffff0000, v152
	v_lshlrev_b32_e32 v152, 16, v153
	v_and_b32_e32 v153, 0xffff0000, v153
	v_lshlrev_b32_e32 v162, 16, v154
	v_and_b32_e32 v163, 0xffff0000, v154
	v_lshlrev_b32_e32 v154, 16, v155
	v_and_b32_e32 v155, 0xffff0000, v155
	v_pk_mul_f32 v[128:129], v[128:129], v[152:153]
	v_pk_mul_f32 v[126:127], v[126:127], v[158:159]
	v_pk_mul_f32 v[152:153], v[124:125], v[154:155]
	v_pk_mul_f32 v[124:125], v[122:123], v[162:163]
	v_cvt_pk_bf16_f32 v122, v126, v127
	v_cvt_pk_bf16_f32 v123, v128, v129
	v_cvt_pk_bf16_f32 v124, v124, v125
	v_cvt_pk_bf16_f32 v125, v152, v153
	global_store_dwordx4 v[156:157], v[122:125], off
	global_load_dwordx4 v[122:125], v[136:137], off offset:256
	v_add_u32_e32 v126, 16, v132
	v_mad_i64_i32 v[128:129], s[0:1], v126, s47, v[134:135]
	v_lshl_add_u64 v[128:129], v[128:129], 0, v[130:131]
	v_add_co_u32_e32 v136, vcc, s72, v128
	v_ashrrev_i32_e32 v127, 31, v126
	s_nop 0
	v_addc_co_u32_e32 v137, vcc, 0, v129, vcc
	s_waitcnt vmcnt(0)
	v_lshlrev_b32_e32 v152, 16, v122
	v_and_b32_e32 v153, 0xffff0000, v122
	v_lshlrev_b32_e32 v122, 16, v123
	v_and_b32_e32 v123, 0xffff0000, v123
	v_lshlrev_b32_e32 v154, 16, v124
	v_and_b32_e32 v155, 0xffff0000, v124
	v_lshlrev_b32_e32 v124, 16, v125
	v_and_b32_e32 v125, 0xffff0000, v125
	v_pk_mul_f32 v[120:121], v[120:121], v[122:123]
	v_pk_mul_f32 v[118:119], v[118:119], v[152:153]
	v_pk_mul_f32 v[122:123], v[116:117], v[124:125]
	v_pk_mul_f32 v[116:117], v[114:115], v[154:155]
	v_cvt_pk_bf16_f32 v114, v118, v119
	v_cvt_pk_bf16_f32 v115, v120, v121
	v_cvt_pk_bf16_f32 v116, v116, v117
	v_cvt_pk_bf16_f32 v117, v122, v123
	global_store_dwordx4 v[156:157], v[114:117], off offset:256
	global_load_dwordx4 v[114:117], v[136:137], off
	v_lshlrev_b64 v[118:119], 12, v[126:127]
	v_lshl_add_u64 v[118:119], s[28:29], 0, v[118:119]
	v_lshl_add_u64 v[118:119], v[118:119], 0, v[130:131]
	v_lshl_add_u64 v[120:121], v[128:129], 0, s[34:35]
	s_waitcnt vmcnt(0)
	v_lshlrev_b32_e32 v122, 16, v114
	v_and_b32_e32 v123, 0xffff0000, v114
	v_lshlrev_b32_e32 v114, 16, v115
	v_and_b32_e32 v115, 0xffff0000, v115
	v_lshlrev_b32_e32 v124, 16, v116
	v_and_b32_e32 v125, 0xffff0000, v116
	v_lshlrev_b32_e32 v116, 16, v117
	v_and_b32_e32 v117, 0xffff0000, v117
	v_pk_mul_f32 v[112:113], v[112:113], v[114:115]
	v_pk_mul_f32 v[110:111], v[110:111], v[122:123]
	v_pk_mul_f32 v[114:115], v[108:109], v[116:117]
	v_pk_mul_f32 v[108:109], v[106:107], v[124:125]
	v_cvt_pk_bf16_f32 v106, v110, v111
	v_cvt_pk_bf16_f32 v107, v112, v113
	v_cvt_pk_bf16_f32 v108, v108, v109
	v_cvt_pk_bf16_f32 v109, v114, v115
	global_store_dwordx4 v[118:119], v[106:109], off
	global_load_dwordx4 v[106:109], v[120:121], off offset:256
	v_add_u32_e32 v110, 32, v132
	v_mad_i64_i32 v[112:113], s[0:1], v110, s47, v[134:135]
	v_lshl_add_u64 v[112:113], v[112:113], 0, v[130:131]
	v_add_co_u32_e32 v114, vcc, s72, v112
	v_ashrrev_i32_e32 v111, 31, v110
	s_nop 0
	v_addc_co_u32_e32 v115, vcc, 0, v113, vcc
	s_waitcnt vmcnt(0)
	v_lshlrev_b32_e32 v116, 16, v106
	v_and_b32_e32 v117, 0xffff0000, v106
	v_lshlrev_b32_e32 v106, 16, v107
	v_and_b32_e32 v107, 0xffff0000, v107
	v_lshlrev_b32_e32 v120, 16, v108
	v_and_b32_e32 v121, 0xffff0000, v108
	v_lshlrev_b32_e32 v108, 16, v109
	v_and_b32_e32 v109, 0xffff0000, v109
	v_pk_mul_f32 v[104:105], v[104:105], v[106:107]
	v_pk_mul_f32 v[102:103], v[102:103], v[116:117]
	v_pk_mul_f32 v[106:107], v[100:101], v[108:109]
	v_pk_mul_f32 v[100:101], v[98:99], v[120:121]
	v_cvt_pk_bf16_f32 v98, v102, v103
	v_cvt_pk_bf16_f32 v99, v104, v105
	v_cvt_pk_bf16_f32 v100, v100, v101
	v_cvt_pk_bf16_f32 v101, v106, v107
	global_store_dwordx4 v[118:119], v[98:101], off offset:256
	global_load_dwordx4 v[98:101], v[114:115], off
	v_lshlrev_b64 v[102:103], 12, v[110:111]
	v_lshl_add_u64 v[102:103], s[28:29], 0, v[102:103]
	v_lshl_add_u64 v[102:103], v[102:103], 0, v[130:131]
	v_lshl_add_u64 v[104:105], v[112:113], 0, s[34:35]
	s_waitcnt vmcnt(0)
	v_lshlrev_b32_e32 v106, 16, v98
	v_and_b32_e32 v107, 0xffff0000, v98
	v_lshlrev_b32_e32 v98, 16, v99
	v_and_b32_e32 v99, 0xffff0000, v99
	v_lshlrev_b32_e32 v108, 16, v100
	v_and_b32_e32 v109, 0xffff0000, v100
	v_lshlrev_b32_e32 v100, 16, v101
	v_and_b32_e32 v101, 0xffff0000, v101
	v_pk_mul_f32 v[96:97], v[96:97], v[98:99]
	v_pk_mul_f32 v[94:95], v[94:95], v[106:107]
	v_pk_mul_f32 v[98:99], v[92:93], v[100:101]
	v_pk_mul_f32 v[92:93], v[90:91], v[108:109]
	v_cvt_pk_bf16_f32 v90, v94, v95
	v_cvt_pk_bf16_f32 v91, v96, v97
	v_cvt_pk_bf16_f32 v92, v92, v93
	v_cvt_pk_bf16_f32 v93, v98, v99
	global_store_dwordx4 v[102:103], v[90:93], off
	global_load_dwordx4 v[90:93], v[104:105], off offset:256
	v_add_u32_e32 v94, 48, v132
	v_mad_i64_i32 v[96:97], s[0:1], v94, s47, v[134:135]
	v_lshl_add_u64 v[96:97], v[96:97], 0, v[130:131]
	v_add_co_u32_e32 v98, vcc, s72, v96
	v_ashrrev_i32_e32 v95, 31, v94
	s_nop 0
	v_addc_co_u32_e32 v99, vcc, 0, v97, vcc
	s_waitcnt vmcnt(0)
	v_lshlrev_b32_e32 v100, 16, v90
	v_and_b32_e32 v101, 0xffff0000, v90
	v_lshlrev_b32_e32 v90, 16, v91
	v_and_b32_e32 v91, 0xffff0000, v91
	v_lshlrev_b32_e32 v104, 16, v92
	v_and_b32_e32 v105, 0xffff0000, v92
	v_lshlrev_b32_e32 v92, 16, v93
	v_and_b32_e32 v93, 0xffff0000, v93
	v_pk_mul_f32 v[88:89], v[88:89], v[90:91]
	v_pk_mul_f32 v[86:87], v[86:87], v[100:101]
	v_pk_mul_f32 v[90:91], v[84:85], v[92:93]
	v_pk_mul_f32 v[84:85], v[82:83], v[104:105]
	v_cvt_pk_bf16_f32 v82, v86, v87
	v_cvt_pk_bf16_f32 v83, v88, v89
	v_cvt_pk_bf16_f32 v84, v84, v85
	v_cvt_pk_bf16_f32 v85, v90, v91
	global_store_dwordx4 v[102:103], v[82:85], off offset:256
	global_load_dwordx4 v[82:85], v[98:99], off
	v_lshlrev_b64 v[86:87], 12, v[94:95]
	v_lshl_add_u64 v[86:87], s[28:29], 0, v[86:87]
	v_lshl_add_u64 v[86:87], v[86:87], 0, v[130:131]
	v_lshl_add_u64 v[88:89], v[96:97], 0, s[34:35]
	s_waitcnt vmcnt(0)
	v_lshlrev_b32_e32 v90, 16, v82
	v_and_b32_e32 v91, 0xffff0000, v82
	v_lshlrev_b32_e32 v82, 16, v83
	v_and_b32_e32 v83, 0xffff0000, v83
	v_lshlrev_b32_e32 v92, 16, v84
	v_and_b32_e32 v93, 0xffff0000, v84
	v_lshlrev_b32_e32 v84, 16, v85
	v_and_b32_e32 v85, 0xffff0000, v85
	v_pk_mul_f32 v[80:81], v[80:81], v[82:83]
	v_pk_mul_f32 v[78:79], v[78:79], v[90:91]
	v_pk_mul_f32 v[82:83], v[76:77], v[84:85]
	v_pk_mul_f32 v[76:77], v[74:75], v[92:93]
	v_cvt_pk_bf16_f32 v74, v78, v79
	v_cvt_pk_bf16_f32 v75, v80, v81
	v_cvt_pk_bf16_f32 v76, v76, v77
	v_cvt_pk_bf16_f32 v77, v82, v83
	global_store_dwordx4 v[86:87], v[74:77], off
	global_load_dwordx4 v[74:77], v[88:89], off offset:256
	v_add_u32_e32 v78, 0x80, v132
	v_mad_i64_i32 v[80:81], s[0:1], v78, s47, v[134:135]
	v_lshl_add_u64 v[80:81], v[80:81], 0, v[130:131]
	v_add_co_u32_e32 v82, vcc, s72, v80
	v_ashrrev_i32_e32 v79, 31, v78
	s_nop 0
	v_addc_co_u32_e32 v83, vcc, 0, v81, vcc
	s_waitcnt vmcnt(0)
	v_lshlrev_b32_e32 v84, 16, v74
	v_and_b32_e32 v85, 0xffff0000, v74
	v_lshlrev_b32_e32 v74, 16, v75
	v_and_b32_e32 v75, 0xffff0000, v75
	v_lshlrev_b32_e32 v88, 16, v76
	v_and_b32_e32 v89, 0xffff0000, v76
	v_lshlrev_b32_e32 v76, 16, v77
	v_and_b32_e32 v77, 0xffff0000, v77
	v_pk_mul_f32 v[72:73], v[72:73], v[74:75]
	v_pk_mul_f32 v[70:71], v[70:71], v[84:85]
	v_pk_mul_f32 v[74:75], v[68:69], v[76:77]
	v_pk_mul_f32 v[68:69], v[66:67], v[88:89]
	v_cvt_pk_bf16_f32 v66, v70, v71
	v_cvt_pk_bf16_f32 v67, v72, v73
	v_cvt_pk_bf16_f32 v68, v68, v69
	v_cvt_pk_bf16_f32 v69, v74, v75
	global_store_dwordx4 v[86:87], v[66:69], off offset:256
	global_load_dwordx4 v[66:69], v[82:83], off
	v_lshlrev_b64 v[70:71], 12, v[78:79]
	v_lshl_add_u64 v[70:71], s[28:29], 0, v[70:71]
	v_lshl_add_u64 v[70:71], v[70:71], 0, v[130:131]
	v_lshl_add_u64 v[72:73], v[80:81], 0, s[34:35]
	s_waitcnt vmcnt(0)
	v_lshlrev_b32_e32 v74, 16, v66
	v_and_b32_e32 v75, 0xffff0000, v66
	v_lshlrev_b32_e32 v66, 16, v67
	v_and_b32_e32 v67, 0xffff0000, v67
	v_lshlrev_b32_e32 v76, 16, v68
	v_and_b32_e32 v77, 0xffff0000, v68
	v_lshlrev_b32_e32 v68, 16, v69
	v_and_b32_e32 v69, 0xffff0000, v69
	v_pk_mul_f32 v[64:65], v[64:65], v[66:67]
	v_pk_mul_f32 v[62:63], v[62:63], v[74:75]
	v_pk_mul_f32 v[66:67], v[60:61], v[68:69]
	v_pk_mul_f32 v[60:61], v[58:59], v[76:77]
	v_cvt_pk_bf16_f32 v58, v62, v63
	v_cvt_pk_bf16_f32 v59, v64, v65
	v_cvt_pk_bf16_f32 v60, v60, v61
	v_cvt_pk_bf16_f32 v61, v66, v67
	global_store_dwordx4 v[70:71], v[58:61], off
	global_load_dwordx4 v[58:61], v[72:73], off offset:256
	v_add_u32_e32 v62, 0x90, v132
	v_mad_i64_i32 v[64:65], s[0:1], v62, s47, v[134:135]
	v_lshl_add_u64 v[64:65], v[64:65], 0, v[130:131]
	v_add_co_u32_e32 v66, vcc, s72, v64
	v_ashrrev_i32_e32 v63, 31, v62
	s_nop 0
	v_addc_co_u32_e32 v67, vcc, 0, v65, vcc
	s_waitcnt vmcnt(0)
	v_lshlrev_b32_e32 v68, 16, v58
	v_and_b32_e32 v69, 0xffff0000, v58
	v_lshlrev_b32_e32 v58, 16, v59
	v_and_b32_e32 v59, 0xffff0000, v59
	v_lshlrev_b32_e32 v72, 16, v60
	v_and_b32_e32 v73, 0xffff0000, v60
	v_lshlrev_b32_e32 v60, 16, v61
	v_and_b32_e32 v61, 0xffff0000, v61
	v_pk_mul_f32 v[56:57], v[56:57], v[58:59]
	v_pk_mul_f32 v[54:55], v[54:55], v[68:69]
	v_pk_mul_f32 v[58:59], v[52:53], v[60:61]
	v_pk_mul_f32 v[52:53], v[50:51], v[72:73]
	v_cvt_pk_bf16_f32 v50, v54, v55
	v_cvt_pk_bf16_f32 v51, v56, v57
	v_cvt_pk_bf16_f32 v52, v52, v53
	v_cvt_pk_bf16_f32 v53, v58, v59
	global_store_dwordx4 v[70:71], v[50:53], off offset:256
	global_load_dwordx4 v[50:53], v[66:67], off
	v_lshlrev_b64 v[54:55], 12, v[62:63]
	v_lshl_add_u64 v[54:55], s[28:29], 0, v[54:55]
	v_lshl_add_u64 v[54:55], v[54:55], 0, v[130:131]
	v_lshl_add_u64 v[56:57], v[64:65], 0, s[34:35]
	s_waitcnt vmcnt(0)
	v_lshlrev_b32_e32 v58, 16, v50
	v_and_b32_e32 v59, 0xffff0000, v50
	v_lshlrev_b32_e32 v50, 16, v51
	v_and_b32_e32 v51, 0xffff0000, v51
	v_lshlrev_b32_e32 v60, 16, v52
	v_and_b32_e32 v61, 0xffff0000, v52
	v_lshlrev_b32_e32 v52, 16, v53
	v_and_b32_e32 v53, 0xffff0000, v53
	v_pk_mul_f32 v[48:49], v[48:49], v[50:51]
	v_pk_mul_f32 v[46:47], v[46:47], v[58:59]
	v_pk_mul_f32 v[50:51], v[44:45], v[52:53]
	v_pk_mul_f32 v[44:45], v[42:43], v[60:61]
	v_cvt_pk_bf16_f32 v42, v46, v47
	v_cvt_pk_bf16_f32 v43, v48, v49
	v_cvt_pk_bf16_f32 v44, v44, v45
	v_cvt_pk_bf16_f32 v45, v50, v51
	global_store_dwordx4 v[54:55], v[42:45], off
	global_load_dwordx4 v[42:45], v[56:57], off offset:256
	v_add_u32_e32 v46, 0xa0, v132
	v_mad_i64_i32 v[48:49], s[0:1], v46, s47, v[134:135]
	v_lshl_add_u64 v[48:49], v[48:49], 0, v[130:131]
	v_add_co_u32_e32 v50, vcc, s72, v48
	v_ashrrev_i32_e32 v47, 31, v46
	s_nop 0
	v_addc_co_u32_e32 v51, vcc, 0, v49, vcc
	s_waitcnt vmcnt(0)
	v_lshlrev_b32_e32 v52, 16, v42
	v_and_b32_e32 v53, 0xffff0000, v42
	v_lshlrev_b32_e32 v42, 16, v43
	v_and_b32_e32 v43, 0xffff0000, v43
	v_lshlrev_b32_e32 v56, 16, v44
	v_and_b32_e32 v57, 0xffff0000, v44
	v_lshlrev_b32_e32 v44, 16, v45
	v_and_b32_e32 v45, 0xffff0000, v45
	v_pk_mul_f32 v[40:41], v[40:41], v[42:43]
	v_pk_mul_f32 v[38:39], v[38:39], v[52:53]
	v_pk_mul_f32 v[42:43], v[36:37], v[44:45]
	v_pk_mul_f32 v[36:37], v[34:35], v[56:57]
	v_cvt_pk_bf16_f32 v34, v38, v39
	v_cvt_pk_bf16_f32 v35, v40, v41
	v_cvt_pk_bf16_f32 v36, v36, v37
	v_cvt_pk_bf16_f32 v37, v42, v43
	global_store_dwordx4 v[54:55], v[34:37], off offset:256
	global_load_dwordx4 v[34:37], v[50:51], off
	v_lshlrev_b64 v[38:39], 12, v[46:47]
	v_lshl_add_u64 v[38:39], s[28:29], 0, v[38:39]
	v_lshl_add_u64 v[38:39], v[38:39], 0, v[130:131]
	v_lshl_add_u64 v[40:41], v[48:49], 0, s[34:35]
	s_waitcnt vmcnt(0)
	v_lshlrev_b32_e32 v42, 16, v34
	v_and_b32_e32 v43, 0xffff0000, v34
	v_lshlrev_b32_e32 v34, 16, v35
	v_and_b32_e32 v35, 0xffff0000, v35
	v_lshlrev_b32_e32 v44, 16, v36
	v_and_b32_e32 v45, 0xffff0000, v36
	v_lshlrev_b32_e32 v36, 16, v37
	v_and_b32_e32 v37, 0xffff0000, v37
	v_pk_mul_f32 v[32:33], v[32:33], v[34:35]
	v_pk_mul_f32 v[30:31], v[30:31], v[42:43]
	v_pk_mul_f32 v[34:35], v[28:29], v[36:37]
	v_pk_mul_f32 v[28:29], v[26:27], v[44:45]
	v_cvt_pk_bf16_f32 v26, v30, v31
	v_cvt_pk_bf16_f32 v27, v32, v33
	v_cvt_pk_bf16_f32 v28, v28, v29
	v_cvt_pk_bf16_f32 v29, v34, v35
	global_store_dwordx4 v[38:39], v[26:29], off
	global_load_dwordx4 v[26:29], v[40:41], off offset:256
	v_add_u32_e32 v30, 0xb0, v132
	v_mad_i64_i32 v[32:33], s[0:1], v30, s47, v[134:135]
	v_lshl_add_u64 v[32:33], v[32:33], 0, v[130:131]
	v_add_co_u32_e32 v34, vcc, s72, v32
	v_ashrrev_i32_e32 v31, 31, v30
	s_nop 0
	v_addc_co_u32_e32 v35, vcc, 0, v33, vcc
	s_and_b64 vcc, exec, s[36:37]
	s_waitcnt vmcnt(0)
	v_lshlrev_b32_e32 v36, 16, v26
	v_and_b32_e32 v37, 0xffff0000, v26
	v_lshlrev_b32_e32 v26, 16, v27
	v_and_b32_e32 v27, 0xffff0000, v27
	v_lshlrev_b32_e32 v40, 16, v28
	v_and_b32_e32 v41, 0xffff0000, v28
	v_lshlrev_b32_e32 v28, 16, v29
	v_and_b32_e32 v29, 0xffff0000, v29
	v_pk_mul_f32 v[24:25], v[24:25], v[26:27]
	v_pk_mul_f32 v[22:23], v[22:23], v[36:37]
	v_pk_mul_f32 v[26:27], v[20:21], v[28:29]
	v_pk_mul_f32 v[20:21], v[18:19], v[40:41]
	v_cvt_pk_bf16_f32 v18, v22, v23
	v_cvt_pk_bf16_f32 v19, v24, v25
	v_cvt_pk_bf16_f32 v20, v20, v21
	v_cvt_pk_bf16_f32 v21, v26, v27
	global_store_dwordx4 v[38:39], v[18:21], off offset:256
	global_load_dwordx4 v[18:21], v[34:35], off
	v_lshlrev_b64 v[22:23], 12, v[30:31]
	v_lshl_add_u64 v[22:23], s[28:29], 0, v[22:23]
	v_lshl_add_u64 v[22:23], v[22:23], 0, v[130:131]
	v_lshl_add_u64 v[24:25], v[32:33], 0, s[34:35]
	s_waitcnt vmcnt(0)
	v_lshlrev_b32_e32 v26, 16, v18
	v_and_b32_e32 v27, 0xffff0000, v18
	v_lshlrev_b32_e32 v18, 16, v19
	v_and_b32_e32 v19, 0xffff0000, v19
	v_lshlrev_b32_e32 v28, 16, v20
	v_and_b32_e32 v29, 0xffff0000, v20
	v_lshlrev_b32_e32 v20, 16, v21
	v_and_b32_e32 v21, 0xffff0000, v21
	v_pk_mul_f32 v[16:17], v[16:17], v[18:19]
	v_pk_mul_f32 v[14:15], v[14:15], v[26:27]
	v_pk_mul_f32 v[18:19], v[12:13], v[20:21]
	v_pk_mul_f32 v[12:13], v[10:11], v[28:29]
	v_cvt_pk_bf16_f32 v10, v14, v15
	v_cvt_pk_bf16_f32 v11, v16, v17
	v_cvt_pk_bf16_f32 v12, v12, v13
	v_cvt_pk_bf16_f32 v13, v18, v19
	global_store_dwordx4 v[22:23], v[10:13], off
	global_load_dwordx4 v[10:13], v[24:25], off offset:256
	s_waitcnt vmcnt(0)
	v_lshlrev_b32_e32 v14, 16, v10
	v_and_b32_e32 v15, 0xffff0000, v10
	v_lshlrev_b32_e32 v10, 16, v11
	v_and_b32_e32 v11, 0xffff0000, v11
	v_lshlrev_b32_e32 v16, 16, v12
	v_and_b32_e32 v17, 0xffff0000, v12
	v_lshlrev_b32_e32 v12, 16, v13
	v_and_b32_e32 v13, 0xffff0000, v13
	v_pk_mul_f32 v[8:9], v[8:9], v[10:11]
	v_pk_mul_f32 v[6:7], v[6:7], v[14:15]
	v_pk_mul_f32 v[10:11], v[4:5], v[12:13]
	v_pk_mul_f32 v[4:5], v[2:3], v[16:17]
	v_cvt_pk_bf16_f32 v2, v6, v7
	v_cvt_pk_bf16_f32 v3, v8, v9
	v_cvt_pk_bf16_f32 v4, v4, v5
	v_cvt_pk_bf16_f32 v5, v10, v11
	global_store_dwordx4 v[22:23], v[2:5], off offset:256
	s_cbranch_vccz .LBB0_715
	s_waitcnt vmcnt(0)
	s_cmpk_gt_u32 s97, 0xff
	s_cbranch_scc1 .LBB0_732
	s_barrier

.LBB0_806:
	s_add_u32 s79, s26, 0x100
	s_addc_u32 s80, s27, 0
	s_ashr_i32 s9, s8, 31
	s_lshl_b64 s[12:13], s[8:9], 20
	s_add_u32 s12, s38, s12
	s_addc_u32 s13, s39, s13
	s_and_b64 s[30:31], s[44:45], exec
	s_cselect_b32 s9, s13, s27
	s_cselect_b32 s44, s12, s26
	s_add_u32 s26, s6, 0x80080
	s_addc_u32 s27, s7, 0
	v_lshl_add_u64 v[140:141], s[26:27], 0, v[136:137]
	v_lshl_add_u64 v[142:143], s[26:27], 0, v[138:139]
	s_mov_b32 s45, -2
	s_mov_b64 s[26:27], 0
	v_add_u32_e32 v224, 0x10000, v144
	v_add_u32_e32 v225, 0x14000, v144
	v_add_u32_e32 v226, 0x18000, v144
	v_add_u32_e32 v227, 0x1c000, v144
.LBB0_807:
	s_add_u32 s30, s6, s26
	s_addc_u32 s31, s7, s27
	s_add_u32 s30, s30, 0x100
	s_addc_u32 s31, s31, 0
	s_add_u32 s81, s79, s26
	s_addc_u32 s82, s80, s27
	s_add_i32 s83, 0, 0x10000
	ds_read_b128 v[152:155], v224
	ds_read_b128 v[156:159], v224 offset:1024
	ds_read_b128 v[160:163], v224 offset:2048
	ds_read_b128 v[164:167], v224 offset:3072
	s_cmpk_eq_i32 s26, 0xf00
	s_cselect_b32 s41, s23, s31
	s_cselect_b32 s40, s22, s30
	s_cselect_b32 s31, s9, s82
	s_cselect_b32 s30, s44, s81
	v_lshl_add_u64 v[146:147], v[140:141], 0, s[26:27]
	s_add_i32 m0, s61, 0xc000
	ds_read_b128 v[168:171], v145
	ds_read_b128 v[172:175], v145 offset:1024
	ds_read_b128 v[176:179], v145 offset:2048
	ds_read_b128 v[180:183], v145 offset:3072
	ds_read_b128 v[184:187], v145 offset:4096
	ds_read_b128 v[188:191], v145 offset:5120
	ds_read_b128 v[192:195], v145 offset:6144
	ds_read_b128 v[196:199], v145 offset:7168
	global_load_lds_dwordx4 v[146:147], off
	v_lshl_add_u64 v[146:147], v[142:143], 0, s[26:27]
	s_add_i32 m0, s61, 0xe000
	s_nop 0
	global_load_lds_dwordx4 v[146:147], off
	s_waitcnt lgkmcnt(8)
	s_barrier
	s_setprio 1
	s_waitcnt lgkmcnt(7)
	v_mfma_f32_16x16x32_bf16 v[126:129], v[152:155], v[168:171], v[126:129]
	v_mfma_f32_16x16x32_bf16 v[122:125], v[160:163], v[168:171], v[122:125]
	s_waitcnt lgkmcnt(5)
	v_mfma_f32_16x16x32_bf16 v[110:113], v[152:155], v[176:179], v[110:113]
	v_mfma_f32_16x16x32_bf16 v[106:109], v[160:163], v[176:179], v[106:109]
	s_waitcnt lgkmcnt(3)
	v_mfma_f32_16x16x32_bf16 v[94:97], v[152:155], v[184:187], v[94:97]
	v_mfma_f32_16x16x32_bf16 v[90:93], v[160:163], v[184:187], v[90:93]
	s_waitcnt lgkmcnt(1)
	v_mfma_f32_16x16x32_bf16 v[78:81], v[152:155], v[192:195], v[78:81]
	v_mfma_f32_16x16x32_bf16 v[74:77], v[160:163], v[192:195], v[74:77]
	v_mfma_f32_16x16x32_bf16 v[126:129], v[156:159], v[172:175], v[126:129]
	v_mfma_f32_16x16x32_bf16 v[122:125], v[164:167], v[172:175], v[122:125]
	v_mfma_f32_16x16x32_bf16 v[110:113], v[156:159], v[180:183], v[110:113]
	v_mfma_f32_16x16x32_bf16 v[106:109], v[164:167], v[180:183], v[106:109]
	v_mfma_f32_16x16x32_bf16 v[94:97], v[156:159], v[188:191], v[94:97]
	v_mfma_f32_16x16x32_bf16 v[90:93], v[164:167], v[188:191], v[90:93]
	s_waitcnt lgkmcnt(0)
	v_mfma_f32_16x16x32_bf16 v[78:81], v[156:159], v[196:199], v[78:81]
	v_mfma_f32_16x16x32_bf16 v[74:77], v[164:167], v[196:199], v[74:77]
	s_setprio 0
	s_barrier
	s_add_i32 s81, 0, 0x14000
	s_add_i32 s82, s83, s60
	ds_read_b128 v[200:203], v225
	ds_read_b128 v[204:207], v225 offset:1024
	ds_read_b128 v[216:219], v225 offset:2048
	ds_read_b128 v[220:223], v225 offset:3072
	s_mov_b32 m0, s82
	s_nop 0
	global_load_lds_dwordx4 v0, s[30:31]
	s_add_i32 m0, s82, 0x2000
	s_nop 0
	global_load_lds_dwordx4 v134, s[30:31]
	s_barrier
	s_setprio 1
	s_waitcnt lgkmcnt(3)
	v_mfma_f32_16x16x32_bf16 v[118:121], v[200:203], v[168:171], v[118:121]
	s_waitcnt lgkmcnt(1)
	v_mfma_f32_16x16x32_bf16 v[114:117], v[216:219], v[168:171], v[114:117]
	v_mfma_f32_16x16x32_bf16 v[102:105], v[200:203], v[176:179], v[102:105]
	v_mfma_f32_16x16x32_bf16 v[98:101], v[216:219], v[176:179], v[98:101]
	v_mfma_f32_16x16x32_bf16 v[86:89], v[200:203], v[184:187], v[86:89]
	v_mfma_f32_16x16x32_bf16 v[82:85], v[216:219], v[184:187], v[82:85]
	v_mfma_f32_16x16x32_bf16 v[70:73], v[200:203], v[192:195], v[70:73]
	v_mfma_f32_16x16x32_bf16 v[66:69], v[216:219], v[192:195], v[66:69]
	v_mfma_f32_16x16x32_bf16 v[118:121], v[204:207], v[172:175], v[118:121]
	s_waitcnt lgkmcnt(0)
	v_mfma_f32_16x16x32_bf16 v[114:117], v[220:223], v[172:175], v[114:117]
	v_mfma_f32_16x16x32_bf16 v[102:105], v[204:207], v[180:183], v[102:105]
	v_mfma_f32_16x16x32_bf16 v[98:101], v[220:223], v[180:183], v[98:101]
	v_mfma_f32_16x16x32_bf16 v[86:89], v[204:207], v[188:191], v[86:89]
	v_mfma_f32_16x16x32_bf16 v[82:85], v[220:223], v[188:191], v[82:85]
	v_mfma_f32_16x16x32_bf16 v[70:73], v[204:207], v[196:199], v[70:73]
	v_mfma_f32_16x16x32_bf16 v[66:69], v[220:223], v[196:199], v[66:69]
	s_setprio 0
	s_mov_b32 m0, s61
	s_add_u32 s98, s40, 0x80
	s_addc_u32 s99, s41, 0
	s_barrier
	ds_read_b128 v[168:171], v145 offset:16384
	ds_read_b128 v[172:175], v145 offset:17408
	ds_read_b128 v[176:179], v145 offset:18432
	ds_read_b128 v[180:183], v145 offset:19456
	ds_read_b128 v[184:187], v145 offset:20480
	ds_read_b128 v[188:191], v145 offset:21504
	ds_read_b128 v[192:195], v145 offset:22528
	global_load_lds_dwordx4 v0, s[40:41]
	s_mov_b32 m0, s64
	ds_read_b128 v[196:199], v145 offset:23552
	global_load_lds_dwordx4 v134, s[40:41]
	s_barrier
	s_setprio 1
	s_waitcnt lgkmcnt(7)
	v_mfma_f32_16x16x32_bf16 v[62:65], v[152:155], v[168:171], v[62:65]
	v_mfma_f32_16x16x32_bf16 v[58:61], v[160:163], v[168:171], v[58:61]
	s_waitcnt lgkmcnt(5)
	v_mfma_f32_16x16x32_bf16 v[46:49], v[152:155], v[176:179], v[46:49]
	v_mfma_f32_16x16x32_bf16 v[42:45], v[160:163], v[176:179], v[42:45]
	s_waitcnt lgkmcnt(3)
	v_mfma_f32_16x16x32_bf16 v[30:33], v[152:155], v[184:187], v[30:33]
	v_mfma_f32_16x16x32_bf16 v[26:29], v[160:163], v[184:187], v[26:29]
	s_waitcnt lgkmcnt(1)
	v_mfma_f32_16x16x32_bf16 v[14:17], v[152:155], v[192:195], v[14:17]
	v_mfma_f32_16x16x32_bf16 v[10:13], v[160:163], v[192:195], v[10:13]
	v_mfma_f32_16x16x32_bf16 v[62:65], v[156:159], v[172:175], v[62:65]
	v_mfma_f32_16x16x32_bf16 v[58:61], v[164:167], v[172:175], v[58:61]
	v_mfma_f32_16x16x32_bf16 v[46:49], v[156:159], v[180:183], v[46:49]
	v_mfma_f32_16x16x32_bf16 v[42:45], v[164:167], v[180:183], v[42:45]
	v_mfma_f32_16x16x32_bf16 v[30:33], v[156:159], v[188:191], v[30:33]
	v_mfma_f32_16x16x32_bf16 v[26:29], v[164:167], v[188:191], v[26:29]
	s_waitcnt lgkmcnt(0)
	v_mfma_f32_16x16x32_bf16 v[14:17], v[156:159], v[196:199], v[14:17]
	v_mfma_f32_16x16x32_bf16 v[10:13], v[164:167], v[196:199], v[10:13]
	s_setprio 0
	s_barrier
	s_add_i32 s81, s81, s60
	s_mov_b32 m0, s81
	s_add_u32 s82, s30, 0x80000
	s_addc_u32 s83, s31, 0
	global_load_lds_dwordx4 v0, s[82:83]
	s_add_i32 m0, s81, 0x2000
	s_nop 0
	global_load_lds_dwordx4 v134, s[82:83]
	s_waitcnt vmcnt(6)
	s_barrier
	s_setprio 1
	v_mfma_f32_16x16x32_bf16 v[54:57], v[200:203], v[168:171], v[54:57]
	v_mfma_f32_16x16x32_bf16 v[50:53], v[216:219], v[168:171], v[50:53]
	v_mfma_f32_16x16x32_bf16 v[38:41], v[200:203], v[176:179], v[38:41]
	v_mfma_f32_16x16x32_bf16 v[34:37], v[216:219], v[176:179], v[34:37]
	v_mfma_f32_16x16x32_bf16 v[22:25], v[200:203], v[184:187], v[22:25]
	v_mfma_f32_16x16x32_bf16 v[18:21], v[216:219], v[184:187], v[18:21]
	v_mfma_f32_16x16x32_bf16 v[6:9], v[200:203], v[192:195], v[6:9]
	v_mfma_f32_16x16x32_bf16 v[2:5], v[216:219], v[192:195], v[2:5]
	v_mfma_f32_16x16x32_bf16 v[54:57], v[204:207], v[172:175], v[54:57]
	v_mfma_f32_16x16x32_bf16 v[50:53], v[220:223], v[172:175], v[50:53]
	v_mfma_f32_16x16x32_bf16 v[38:41], v[204:207], v[180:183], v[38:41]
	v_mfma_f32_16x16x32_bf16 v[34:37], v[220:223], v[180:183], v[34:37]
	v_mfma_f32_16x16x32_bf16 v[22:25], v[204:207], v[188:191], v[22:25]
	v_mfma_f32_16x16x32_bf16 v[18:21], v[220:223], v[188:191], v[18:21]
	v_mfma_f32_16x16x32_bf16 v[6:9], v[204:207], v[196:199], v[6:9]
	v_mfma_f32_16x16x32_bf16 v[2:5], v[220:223], v[196:199], v[2:5]
	s_setprio 0
	s_add_i32 s81, 0, 0x18000
	s_barrier
	ds_read_b128 v[152:155], v226
	ds_read_b128 v[156:159], v226 offset:1024
	ds_read_b128 v[160:163], v226 offset:2048
	ds_read_b128 v[164:167], v226 offset:3072
	s_add_u32 s40, s40, 0x80000
	s_addc_u32 s41, s41, 0
	s_mov_b32 m0, s67
	ds_read_b128 v[168:171], v145 offset:32768
	ds_read_b128 v[172:175], v145 offset:33792
	ds_read_b128 v[176:179], v145 offset:34816
	ds_read_b128 v[180:183], v145 offset:35840
	ds_read_b128 v[184:187], v145 offset:36864
	ds_read_b128 v[188:191], v145 offset:37888
	ds_read_b128 v[192:195], v145 offset:38912
	global_load_lds_dwordx4 v0, s[40:41]
	s_mov_b32 m0, s68
	ds_read_b128 v[196:199], v145 offset:39936
	global_load_lds_dwordx4 v134, s[40:41]
	s_waitcnt lgkmcnt(8)
	s_barrier
	s_setprio 1
	s_waitcnt lgkmcnt(7)
	v_mfma_f32_16x16x32_bf16 v[126:129], v[152:155], v[168:171], v[126:129]
	v_mfma_f32_16x16x32_bf16 v[122:125], v[160:163], v[168:171], v[122:125]
	s_waitcnt lgkmcnt(5)
	v_mfma_f32_16x16x32_bf16 v[110:113], v[152:155], v[176:179], v[110:113]
	v_mfma_f32_16x16x32_bf16 v[106:109], v[160:163], v[176:179], v[106:109]
	s_waitcnt lgkmcnt(3)
	v_mfma_f32_16x16x32_bf16 v[94:97], v[152:155], v[184:187], v[94:97]
	v_mfma_f32_16x16x32_bf16 v[90:93], v[160:163], v[184:187], v[90:93]
	s_waitcnt lgkmcnt(1)
	v_mfma_f32_16x16x32_bf16 v[78:81], v[152:155], v[192:195], v[78:81]
	v_mfma_f32_16x16x32_bf16 v[74:77], v[160:163], v[192:195], v[74:77]
	v_mfma_f32_16x16x32_bf16 v[126:129], v[156:159], v[172:175], v[126:129]
	v_mfma_f32_16x16x32_bf16 v[122:125], v[164:167], v[172:175], v[122:125]
	v_mfma_f32_16x16x32_bf16 v[110:113], v[156:159], v[180:183], v[110:113]
	v_mfma_f32_16x16x32_bf16 v[106:109], v[164:167], v[180:183], v[106:109]
	v_mfma_f32_16x16x32_bf16 v[94:97], v[156:159], v[188:191], v[94:97]
	v_mfma_f32_16x16x32_bf16 v[90:93], v[164:167], v[188:191], v[90:93]
	s_waitcnt lgkmcnt(0)
	v_mfma_f32_16x16x32_bf16 v[78:81], v[156:159], v[196:199], v[78:81]
	v_mfma_f32_16x16x32_bf16 v[74:77], v[164:167], v[196:199], v[74:77]
	s_setprio 0
	s_barrier
	s_add_i32 s40, 0, 0x1c000
	s_add_i32 s41, s81, s60
	s_add_u32 s100, s30, 0x80
	s_addc_u32 s101, s31, 0
	s_mov_b32 m0, s41
	ds_read_b128 v[200:203], v227
	ds_read_b128 v[204:207], v227 offset:1024
	ds_read_b128 v[216:219], v227 offset:2048
	global_load_lds_dwordx4 v0, s[100:101]
	s_add_i32 m0, s41, 0x2000
	ds_read_b128 v[220:223], v227 offset:3072
	global_load_lds_dwordx4 v134, s[100:101]
	s_barrier
	s_setprio 1
	s_waitcnt lgkmcnt(3)
	v_mfma_f32_16x16x32_bf16 v[118:121], v[200:203], v[168:171], v[118:121]
	s_waitcnt lgkmcnt(1)
	v_mfma_f32_16x16x32_bf16 v[114:117], v[216:219], v[168:171], v[114:117]
	v_mfma_f32_16x16x32_bf16 v[102:105], v[200:203], v[176:179], v[102:105]
	v_mfma_f32_16x16x32_bf16 v[98:101], v[216:219], v[176:179], v[98:101]
	v_mfma_f32_16x16x32_bf16 v[86:89], v[200:203], v[184:187], v[86:89]
	v_mfma_f32_16x16x32_bf16 v[82:85], v[216:219], v[184:187], v[82:85]
	v_mfma_f32_16x16x32_bf16 v[70:73], v[200:203], v[192:195], v[70:73]
	v_mfma_f32_16x16x32_bf16 v[66:69], v[216:219], v[192:195], v[66:69]
	v_mfma_f32_16x16x32_bf16 v[118:121], v[204:207], v[172:175], v[118:121]
	s_waitcnt lgkmcnt(0)
	v_mfma_f32_16x16x32_bf16 v[114:117], v[220:223], v[172:175], v[114:117]
	v_mfma_f32_16x16x32_bf16 v[102:105], v[204:207], v[180:183], v[102:105]
	v_mfma_f32_16x16x32_bf16 v[98:101], v[220:223], v[180:183], v[98:101]
	v_mfma_f32_16x16x32_bf16 v[86:89], v[204:207], v[188:191], v[86:89]
	v_mfma_f32_16x16x32_bf16 v[82:85], v[220:223], v[188:191], v[82:85]
	v_mfma_f32_16x16x32_bf16 v[70:73], v[204:207], v[196:199], v[70:73]
	v_mfma_f32_16x16x32_bf16 v[66:69], v[220:223], v[196:199], v[66:69]
	s_setprio 0
	s_mov_b32 m0, s69
	s_barrier
	ds_read_b128 v[168:171], v145 offset:49152
	ds_read_b128 v[172:175], v145 offset:50176
	ds_read_b128 v[176:179], v145 offset:51200
	ds_read_b128 v[180:183], v145 offset:52224
	ds_read_b128 v[184:187], v145 offset:53248
	ds_read_b128 v[188:191], v145 offset:54272
	ds_read_b128 v[192:195], v145 offset:55296
	global_load_lds_dwordx4 v0, s[98:99]
	s_mov_b32 m0, s75
	ds_read_b128 v[196:199], v145 offset:56320
	global_load_lds_dwordx4 v134, s[98:99]
	s_barrier
	s_setprio 1
	s_waitcnt lgkmcnt(7)
	v_mfma_f32_16x16x32_bf16 v[62:65], v[152:155], v[168:171], v[62:65]
	v_mfma_f32_16x16x32_bf16 v[58:61], v[160:163], v[168:171], v[58:61]
	s_waitcnt lgkmcnt(5)
	v_mfma_f32_16x16x32_bf16 v[46:49], v[152:155], v[176:179], v[46:49]
	v_mfma_f32_16x16x32_bf16 v[42:45], v[160:163], v[176:179], v[42:45]
	s_waitcnt lgkmcnt(3)
	v_mfma_f32_16x16x32_bf16 v[30:33], v[152:155], v[184:187], v[30:33]
	v_mfma_f32_16x16x32_bf16 v[26:29], v[160:163], v[184:187], v[26:29]
	s_waitcnt lgkmcnt(1)
	v_mfma_f32_16x16x32_bf16 v[14:17], v[152:155], v[192:195], v[14:17]
	v_mfma_f32_16x16x32_bf16 v[10:13], v[160:163], v[192:195], v[10:13]
	v_mfma_f32_16x16x32_bf16 v[62:65], v[156:159], v[172:175], v[62:65]
	v_mfma_f32_16x16x32_bf16 v[58:61], v[164:167], v[172:175], v[58:61]
	v_mfma_f32_16x16x32_bf16 v[46:49], v[156:159], v[180:183], v[46:49]
	v_mfma_f32_16x16x32_bf16 v[42:45], v[164:167], v[180:183], v[42:45]
	v_mfma_f32_16x16x32_bf16 v[30:33], v[156:159], v[188:191], v[30:33]
	v_mfma_f32_16x16x32_bf16 v[26:29], v[164:167], v[188:191], v[26:29]
	s_waitcnt lgkmcnt(0)
	v_mfma_f32_16x16x32_bf16 v[14:17], v[156:159], v[196:199], v[14:17]
	v_mfma_f32_16x16x32_bf16 v[10:13], v[164:167], v[196:199], v[10:13]
	s_setprio 0
	s_barrier
	s_add_i32 s40, s40, s60
	s_mov_b32 m0, s40
	s_add_u32 s30, s30, 0x80080
	s_addc_u32 s31, s31, 0
	global_load_lds_dwordx4 v0, s[30:31]
	s_add_i32 m0, s40, 0x2000
	s_nop 0
	global_load_lds_dwordx4 v134, s[30:31]
	s_waitcnt vmcnt(6)
	s_barrier
	s_setprio 1
	v_mfma_f32_16x16x32_bf16 v[54:57], v[200:203], v[168:171], v[54:57]
	v_mfma_f32_16x16x32_bf16 v[50:53], v[216:219], v[168:171], v[50:53]
	v_mfma_f32_16x16x32_bf16 v[38:41], v[200:203], v[176:179], v[38:41]
	v_mfma_f32_16x16x32_bf16 v[34:37], v[216:219], v[176:179], v[34:37]
	v_mfma_f32_16x16x32_bf16 v[22:25], v[200:203], v[184:187], v[22:25]
	v_mfma_f32_16x16x32_bf16 v[18:21], v[216:219], v[184:187], v[18:21]
	v_mfma_f32_16x16x32_bf16 v[6:9], v[200:203], v[192:195], v[6:9]
	v_mfma_f32_16x16x32_bf16 v[2:5], v[216:219], v[192:195], v[2:5]
	v_mfma_f32_16x16x32_bf16 v[54:57], v[204:207], v[172:175], v[54:57]
	v_mfma_f32_16x16x32_bf16 v[50:53], v[220:223], v[172:175], v[50:53]
	v_mfma_f32_16x16x32_bf16 v[38:41], v[204:207], v[180:183], v[38:41]
	v_mfma_f32_16x16x32_bf16 v[34:37], v[220:223], v[180:183], v[34:37]
	v_mfma_f32_16x16x32_bf16 v[22:25], v[204:207], v[188:191], v[22:25]
	v_mfma_f32_16x16x32_bf16 v[18:21], v[220:223], v[188:191], v[18:21]
	v_mfma_f32_16x16x32_bf16 v[6:9], v[204:207], v[196:199], v[6:9]
	v_mfma_f32_16x16x32_bf16 v[2:5], v[220:223], v[196:199], v[2:5]
	s_setprio 0
	s_add_i32 s45, s45, 2
	s_add_u32 s26, s26, 0x100
	s_addc_u32 s27, s27, 0
	s_cmp_gt_u32 s45, 29
	s_barrier
	s_cbranch_scc0 .LBB0_807
	s_add_u32 s26, s79, 0xffffff00
	s_addc_u32 s27, s80, -1
	s_and_b64 vcc, exec, s[42:43]
	s_cbranch_vccnz .LBB0_796
	v_mov_b32_e32 v2, 0
	s_mov_b32 s14, s8
	s_mov_b32 s50, s77
	s_mov_b64 s[6:7], s[22:23]
	s_mov_b32 s76, s78
	v_mov_b32_e32 v3, v2
	v_mov_b32_e32 v4, v2
	v_mov_b32_e32 v5, v2
	v_mov_b32_e32 v6, v2
	v_mov_b32_e32 v7, v2
	v_mov_b32_e32 v8, v2
	v_mov_b32_e32 v9, v2
	v_mov_b32_e32 v18, v2
	v_mov_b32_e32 v19, v2
	v_mov_b32_e32 v20, v2
	v_mov_b32_e32 v21, v2
	v_mov_b32_e32 v22, v2
	v_mov_b32_e32 v23, v2
	v_mov_b32_e32 v24, v2
	v_mov_b32_e32 v25, v2
	v_mov_b32_e32 v34, v2
	v_mov_b32_e32 v35, v2
	v_mov_b32_e32 v36, v2
	v_mov_b32_e32 v37, v2
	v_mov_b32_e32 v38, v2
	v_mov_b32_e32 v39, v2
	v_mov_b32_e32 v40, v2
	v_mov_b32_e32 v41, v2
	v_mov_b32_e32 v50, v2
	v_mov_b32_e32 v51, v2
	v_mov_b32_e32 v52, v2
	v_mov_b32_e32 v53, v2
	v_mov_b32_e32 v54, v2
	v_mov_b32_e32 v55, v2
	v_mov_b32_e32 v56, v2
	v_mov_b32_e32 v57, v2
	v_mov_b32_e32 v10, v2
	v_mov_b32_e32 v11, v2
	v_mov_b32_e32 v12, v2
	v_mov_b32_e32 v13, v2
	v_mov_b32_e32 v14, v2
	v_mov_b32_e32 v15, v2
	v_mov_b32_e32 v16, v2
	v_mov_b32_e32 v17, v2
	v_mov_b32_e32 v26, v2
	v_mov_b32_e32 v27, v2
	v_mov_b32_e32 v28, v2
	v_mov_b32_e32 v29, v2
	v_mov_b32_e32 v30, v2
	v_mov_b32_e32 v31, v2
	v_mov_b32_e32 v32, v2
	v_mov_b32_e32 v33, v2
	v_mov_b32_e32 v42, v2
	v_mov_b32_e32 v43, v2
	v_mov_b32_e32 v44, v2
	v_mov_b32_e32 v45, v2
	v_mov_b32_e32 v46, v2
	v_mov_b32_e32 v47, v2
	v_mov_b32_e32 v48, v2
	v_mov_b32_e32 v49, v2
	v_mov_b32_e32 v58, v2
	v_mov_b32_e32 v59, v2
	v_mov_b32_e32 v60, v2
	v_mov_b32_e32 v61, v2
	v_mov_b32_e32 v62, v2
	v_mov_b32_e32 v63, v2
	v_mov_b32_e32 v64, v2
	v_mov_b32_e32 v65, v2
	v_mov_b32_e32 v66, v2
	v_mov_b32_e32 v67, v2
	v_mov_b32_e32 v68, v2
	v_mov_b32_e32 v69, v2
	v_mov_b32_e32 v70, v2
	v_mov_b32_e32 v71, v2
	v_mov_b32_e32 v72, v2
	v_mov_b32_e32 v73, v2
	v_mov_b32_e32 v82, v2
	v_mov_b32_e32 v83, v2
	v_mov_b32_e32 v84, v2
	v_mov_b32_e32 v85, v2
	v_mov_b32_e32 v86, v2
	v_mov_b32_e32 v87, v2
	v_mov_b32_e32 v88, v2
	v_mov_b32_e32 v89, v2
	v_mov_b32_e32 v98, v2
	v_mov_b32_e32 v99, v2
	v_mov_b32_e32 v100, v2
	v_mov_b32_e32 v101, v2
	v_mov_b32_e32 v102, v2
	v_mov_b32_e32 v103, v2
	v_mov_b32_e32 v104, v2
	v_mov_b32_e32 v105, v2
	v_mov_b32_e32 v114, v2
	v_mov_b32_e32 v115, v2
	v_mov_b32_e32 v116, v2
	v_mov_b32_e32 v117, v2
	v_mov_b32_e32 v118, v2
	v_mov_b32_e32 v119, v2
	v_mov_b32_e32 v120, v2
	v_mov_b32_e32 v121, v2
	v_mov_b32_e32 v74, v2
	v_mov_b32_e32 v75, v2
	v_mov_b32_e32 v76, v2
	v_mov_b32_e32 v77, v2
	v_mov_b32_e32 v78, v2
	v_mov_b32_e32 v79, v2
	v_mov_b32_e32 v80, v2
	v_mov_b32_e32 v81, v2
	v_mov_b32_e32 v90, v2
	v_mov_b32_e32 v91, v2
	v_mov_b32_e32 v92, v2
	v_mov_b32_e32 v93, v2
	v_mov_b32_e32 v94, v2
	v_mov_b32_e32 v95, v2
	v_mov_b32_e32 v96, v2
	v_mov_b32_e32 v97, v2
	v_mov_b32_e32 v106, v2
	v_mov_b32_e32 v107, v2
	v_mov_b32_e32 v108, v2
	v_mov_b32_e32 v109, v2
	v_mov_b32_e32 v110, v2
	v_mov_b32_e32 v111, v2
	v_mov_b32_e32 v112, v2
	v_mov_b32_e32 v113, v2
	v_mov_b32_e32 v122, v2
	v_mov_b32_e32 v123, v2
	v_mov_b32_e32 v124, v2
	v_mov_b32_e32 v125, v2
	v_mov_b32_e32 v126, v2
	v_mov_b32_e32 v127, v2
	v_mov_b32_e32 v128, v2
	v_mov_b32_e32 v129, v2
	s_andn2_b64 vcc, exec, s[0:1]
	s_cbranch_vccnz .LBB0_797

.LBB0_938:
	s_ashr_i32 s23, s22, 31
	s_lshl_b64 s[28:29], s[22:23], 20
	s_add_u32 s28, s8, s28
	s_addc_u32 s29, s9, s29
	s_and_b64 s[38:39], s[42:43], exec
	s_cselect_b32 s23, s29, s37
	s_cselect_b32 s42, s28, s36
	s_add_u32 s30, s30, 0x80080
	s_addc_u32 s31, s31, 0
	s_add_u32 s43, s36, 0x100
	v_mov_b32_e32 v2, 0
	s_addc_u32 s67, s37, 0
	s_mov_b32 s68, -2
	v_mov_b32_e32 v3, v2
	v_mov_b32_e32 v4, v2
	v_mov_b32_e32 v5, v2
	v_mov_b32_e32 v6, v2
	v_mov_b32_e32 v7, v2
	v_mov_b32_e32 v8, v2
	v_mov_b32_e32 v9, v2
	v_mov_b32_e32 v10, v2
	v_mov_b32_e32 v11, v2
	v_mov_b32_e32 v12, v2
	v_mov_b32_e32 v13, v2
	v_mov_b32_e32 v14, v2
	v_mov_b32_e32 v15, v2
	v_mov_b32_e32 v16, v2
	v_mov_b32_e32 v17, v2
	v_mov_b32_e32 v26, v2
	v_mov_b32_e32 v27, v2
	v_mov_b32_e32 v28, v2
	v_mov_b32_e32 v29, v2
	v_mov_b32_e32 v30, v2
	v_mov_b32_e32 v31, v2
	v_mov_b32_e32 v32, v2
	v_mov_b32_e32 v33, v2
	v_mov_b32_e32 v42, v2
	v_mov_b32_e32 v43, v2
	v_mov_b32_e32 v44, v2
	v_mov_b32_e32 v45, v2
	v_mov_b32_e32 v46, v2
	v_mov_b32_e32 v47, v2
	v_mov_b32_e32 v48, v2
	v_mov_b32_e32 v49, v2
	v_mov_b32_e32 v18, v2
	v_mov_b32_e32 v19, v2
	v_mov_b32_e32 v20, v2
	v_mov_b32_e32 v21, v2
	v_mov_b32_e32 v22, v2
	v_mov_b32_e32 v23, v2
	v_mov_b32_e32 v24, v2
	v_mov_b32_e32 v25, v2
	v_mov_b32_e32 v34, v2
	v_mov_b32_e32 v35, v2
	v_mov_b32_e32 v36, v2
	v_mov_b32_e32 v37, v2
	v_mov_b32_e32 v38, v2
	v_mov_b32_e32 v39, v2
	v_mov_b32_e32 v40, v2
	v_mov_b32_e32 v41, v2
	v_mov_b32_e32 v50, v2
	v_mov_b32_e32 v51, v2
	v_mov_b32_e32 v52, v2
	v_mov_b32_e32 v53, v2
	v_mov_b32_e32 v54, v2
	v_mov_b32_e32 v55, v2
	v_mov_b32_e32 v56, v2
	v_mov_b32_e32 v57, v2
	v_mov_b32_e32 v58, v2
	v_mov_b32_e32 v59, v2
	v_mov_b32_e32 v60, v2
	v_mov_b32_e32 v61, v2
	v_mov_b32_e32 v62, v2
	v_mov_b32_e32 v63, v2
	v_mov_b32_e32 v64, v2
	v_mov_b32_e32 v65, v2
	v_mov_b32_e32 v66, v2
	v_mov_b32_e32 v67, v2
	v_mov_b32_e32 v68, v2
	v_mov_b32_e32 v69, v2
	v_mov_b32_e32 v70, v2
	v_mov_b32_e32 v71, v2
	v_mov_b32_e32 v72, v2
	v_mov_b32_e32 v73, v2
	v_mov_b32_e32 v74, v2
	v_mov_b32_e32 v75, v2
	v_mov_b32_e32 v76, v2
	v_mov_b32_e32 v77, v2
	v_mov_b32_e32 v78, v2
	v_mov_b32_e32 v79, v2
	v_mov_b32_e32 v80, v2
	v_mov_b32_e32 v81, v2
	v_mov_b32_e32 v90, v2
	v_mov_b32_e32 v91, v2
	v_mov_b32_e32 v92, v2
	v_mov_b32_e32 v93, v2
	v_mov_b32_e32 v94, v2
	v_mov_b32_e32 v95, v2
	v_mov_b32_e32 v96, v2
	v_mov_b32_e32 v97, v2
	v_mov_b32_e32 v106, v2
	v_mov_b32_e32 v107, v2
	v_mov_b32_e32 v108, v2
	v_mov_b32_e32 v109, v2
	v_mov_b32_e32 v110, v2
	v_mov_b32_e32 v111, v2
	v_mov_b32_e32 v112, v2
	v_mov_b32_e32 v113, v2
	v_mov_b32_e32 v82, v2
	v_mov_b32_e32 v83, v2
	v_mov_b32_e32 v84, v2
	v_mov_b32_e32 v85, v2
	v_mov_b32_e32 v86, v2
	v_mov_b32_e32 v87, v2
	v_mov_b32_e32 v88, v2
	v_mov_b32_e32 v89, v2
	v_mov_b32_e32 v98, v2
	v_mov_b32_e32 v99, v2
	v_mov_b32_e32 v100, v2
	v_mov_b32_e32 v101, v2
	v_mov_b32_e32 v102, v2
	v_mov_b32_e32 v103, v2
	v_mov_b32_e32 v104, v2
	v_mov_b32_e32 v105, v2
	v_mov_b32_e32 v114, v2
	v_mov_b32_e32 v115, v2
	v_mov_b32_e32 v116, v2
	v_mov_b32_e32 v117, v2
	v_mov_b32_e32 v118, v2
	v_mov_b32_e32 v119, v2
	v_mov_b32_e32 v120, v2
	v_mov_b32_e32 v121, v2
	v_mov_b32_e32 v122, v2
	v_mov_b32_e32 v123, v2
	v_mov_b32_e32 v124, v2
	v_mov_b32_e32 v125, v2
	v_mov_b32_e32 v126, v2
	v_mov_b32_e32 v127, v2
	v_mov_b32_e32 v128, v2
	v_mov_b32_e32 v129, v2
	v_add_u32_e32 v224, 0x10000, v140
	v_add_u32_e32 v225, 0x14000, v140
	v_add_u32_e32 v226, 0x18000, v140
	v_add_u32_e32 v227, 0x1c000, v140
.LBB0_939:
	s_add_u32 s36, s30, 0xfff80080
	s_addc_u32 s37, s31, -1
	s_add_i32 s69, 0, 0x10000
	ds_read_b128 v[142:145], v224
	ds_read_b128 v[152:155], v224 offset:1024
	ds_read_b128 v[156:159], v224 offset:2048
	ds_read_b128 v[160:163], v224 offset:3072
	s_cmp_eq_u32 s68, 28
	s_cselect_b32 s39, s27, s37
	s_cselect_b32 s38, s26, s36
	s_cselect_b32 s37, s23, s67
	s_cselect_b32 s36, s42, s43
	s_add_i32 m0, s41, 0xc000
	ds_read_b128 v[164:167], v141
	ds_read_b128 v[168:171], v141 offset:1024
	ds_read_b128 v[172:175], v141 offset:2048
	ds_read_b128 v[176:179], v141 offset:3072
	ds_read_b128 v[180:183], v141 offset:4096
	ds_read_b128 v[184:187], v141 offset:5120
	ds_read_b128 v[188:191], v141 offset:6144
	global_load_lds_dwordx4 v136, s[30:31]
	s_add_i32 m0, s41, 0xe000
	ds_read_b128 v[192:195], v141 offset:7168
	global_load_lds_dwordx4 v138, s[30:31]
	s_waitcnt lgkmcnt(8)
	s_barrier
	s_setprio 1
	s_waitcnt lgkmcnt(7)
	v_mfma_f32_16x16x32_bf16 v[126:129], v[142:145], v[164:167], v[126:129]
	v_mfma_f32_16x16x32_bf16 v[122:125], v[156:159], v[164:167], v[122:125]
	s_waitcnt lgkmcnt(5)
	v_mfma_f32_16x16x32_bf16 v[118:121], v[142:145], v[172:175], v[118:121]
	v_mfma_f32_16x16x32_bf16 v[114:117], v[156:159], v[172:175], v[114:117]
	s_waitcnt lgkmcnt(3)
	v_mfma_f32_16x16x32_bf16 v[102:105], v[142:145], v[180:183], v[102:105]
	v_mfma_f32_16x16x32_bf16 v[98:101], v[156:159], v[180:183], v[98:101]
	s_waitcnt lgkmcnt(1)
	v_mfma_f32_16x16x32_bf16 v[86:89], v[142:145], v[188:191], v[86:89]
	v_mfma_f32_16x16x32_bf16 v[82:85], v[156:159], v[188:191], v[82:85]
	v_mfma_f32_16x16x32_bf16 v[126:129], v[152:155], v[168:171], v[126:129]
	v_mfma_f32_16x16x32_bf16 v[122:125], v[160:163], v[168:171], v[122:125]
	v_mfma_f32_16x16x32_bf16 v[118:121], v[152:155], v[176:179], v[118:121]
	v_mfma_f32_16x16x32_bf16 v[114:117], v[160:163], v[176:179], v[114:117]
	v_mfma_f32_16x16x32_bf16 v[102:105], v[152:155], v[184:187], v[102:105]
	v_mfma_f32_16x16x32_bf16 v[98:101], v[160:163], v[184:187], v[98:101]
	s_waitcnt lgkmcnt(0)
	v_mfma_f32_16x16x32_bf16 v[86:89], v[152:155], v[192:195], v[86:89]
	v_mfma_f32_16x16x32_bf16 v[82:85], v[160:163], v[192:195], v[82:85]
	s_setprio 0
	s_barrier
	s_add_i32 s75, 0, 0x14000
	s_add_i32 s69, s69, s40
	ds_read_b128 v[196:199], v225
	ds_read_b128 v[200:203], v225 offset:1024
	ds_read_b128 v[204:207], v225 offset:2048
	ds_read_b128 v[216:219], v225 offset:3072
	s_mov_b32 m0, s69
	s_nop 0
	global_load_lds_dwordx4 v0, s[36:37]
	s_add_i32 m0, s69, 0x2000
	s_nop 0
	global_load_lds_dwordx4 v130, s[36:37]
	s_barrier
	s_setprio 1
	s_waitcnt lgkmcnt(3)
	v_mfma_f32_16x16x32_bf16 v[110:113], v[196:199], v[164:167], v[110:113]
	s_waitcnt lgkmcnt(1)
	v_mfma_f32_16x16x32_bf16 v[106:109], v[204:207], v[164:167], v[106:109]
	v_mfma_f32_16x16x32_bf16 v[94:97], v[196:199], v[172:175], v[94:97]
	v_mfma_f32_16x16x32_bf16 v[90:93], v[204:207], v[172:175], v[90:93]
	v_mfma_f32_16x16x32_bf16 v[78:81], v[196:199], v[180:183], v[78:81]
	v_mfma_f32_16x16x32_bf16 v[74:77], v[204:207], v[180:183], v[74:77]
	v_mfma_f32_16x16x32_bf16 v[70:73], v[196:199], v[188:191], v[70:73]
	v_mfma_f32_16x16x32_bf16 v[66:69], v[204:207], v[188:191], v[66:69]
	v_mfma_f32_16x16x32_bf16 v[110:113], v[200:203], v[168:171], v[110:113]
	s_waitcnt lgkmcnt(0)
	v_mfma_f32_16x16x32_bf16 v[106:109], v[216:219], v[168:171], v[106:109]
	v_mfma_f32_16x16x32_bf16 v[94:97], v[200:203], v[176:179], v[94:97]
	v_mfma_f32_16x16x32_bf16 v[90:93], v[216:219], v[176:179], v[90:93]
	v_mfma_f32_16x16x32_bf16 v[78:81], v[200:203], v[184:187], v[78:81]
	v_mfma_f32_16x16x32_bf16 v[74:77], v[216:219], v[184:187], v[74:77]
	v_mfma_f32_16x16x32_bf16 v[70:73], v[200:203], v[192:195], v[70:73]
	v_mfma_f32_16x16x32_bf16 v[66:69], v[216:219], v[192:195], v[66:69]
	s_setprio 0
	s_mov_b32 m0, s41
	s_add_u32 s98, s38, 0x80
	s_addc_u32 s99, s39, 0
	s_barrier
	ds_read_b128 v[164:167], v141 offset:16384
	ds_read_b128 v[168:171], v141 offset:17408
	ds_read_b128 v[172:175], v141 offset:18432
	ds_read_b128 v[176:179], v141 offset:19456
	ds_read_b128 v[180:183], v141 offset:20480
	ds_read_b128 v[184:187], v141 offset:21504
	ds_read_b128 v[188:191], v141 offset:22528
	global_load_lds_dwordx4 v134, s[38:39]
	s_mov_b32 m0, s44
	ds_read_b128 v[192:195], v141 offset:23552
	global_load_lds_dwordx4 v132, s[38:39]
	s_barrier
	s_setprio 1
	s_waitcnt lgkmcnt(7)
	v_mfma_f32_16x16x32_bf16 v[62:65], v[142:145], v[164:167], v[62:65]
	v_mfma_f32_16x16x32_bf16 v[58:61], v[156:159], v[164:167], v[58:61]
	s_waitcnt lgkmcnt(5)
	v_mfma_f32_16x16x32_bf16 v[54:57], v[142:145], v[172:175], v[54:57]
	v_mfma_f32_16x16x32_bf16 v[50:53], v[156:159], v[172:175], v[50:53]
	s_waitcnt lgkmcnt(3)
	v_mfma_f32_16x16x32_bf16 v[38:41], v[142:145], v[180:183], v[38:41]
	v_mfma_f32_16x16x32_bf16 v[34:37], v[156:159], v[180:183], v[34:37]
	s_waitcnt lgkmcnt(1)
	v_mfma_f32_16x16x32_bf16 v[22:25], v[142:145], v[188:191], v[22:25]
	v_mfma_f32_16x16x32_bf16 v[18:21], v[156:159], v[188:191], v[18:21]
	v_mfma_f32_16x16x32_bf16 v[62:65], v[152:155], v[168:171], v[62:65]
	v_mfma_f32_16x16x32_bf16 v[58:61], v[160:163], v[168:171], v[58:61]
	v_mfma_f32_16x16x32_bf16 v[54:57], v[152:155], v[176:179], v[54:57]
	v_mfma_f32_16x16x32_bf16 v[50:53], v[160:163], v[176:179], v[50:53]
	v_mfma_f32_16x16x32_bf16 v[38:41], v[152:155], v[184:187], v[38:41]
	v_mfma_f32_16x16x32_bf16 v[34:37], v[160:163], v[184:187], v[34:37]
	s_waitcnt lgkmcnt(0)
	v_mfma_f32_16x16x32_bf16 v[22:25], v[152:155], v[192:195], v[22:25]
	v_mfma_f32_16x16x32_bf16 v[18:21], v[160:163], v[192:195], v[18:21]
	s_setprio 0
	s_barrier
	s_add_i32 s69, s75, s40
	s_mov_b32 m0, s69
	s_add_u32 s76, s36, 0x80000
	s_addc_u32 s77, s37, 0
	global_load_lds_dwordx4 v0, s[76:77]
	s_add_i32 m0, s69, 0x2000
	s_nop 0
	global_load_lds_dwordx4 v130, s[76:77]
	s_waitcnt vmcnt(6)
	s_barrier
	s_setprio 1
	v_mfma_f32_16x16x32_bf16 v[46:49], v[196:199], v[164:167], v[46:49]
	v_mfma_f32_16x16x32_bf16 v[42:45], v[204:207], v[164:167], v[42:45]
	v_mfma_f32_16x16x32_bf16 v[30:33], v[196:199], v[172:175], v[30:33]
	v_mfma_f32_16x16x32_bf16 v[26:29], v[204:207], v[172:175], v[26:29]
	v_mfma_f32_16x16x32_bf16 v[14:17], v[196:199], v[180:183], v[14:17]
	v_mfma_f32_16x16x32_bf16 v[10:13], v[204:207], v[180:183], v[10:13]
	v_mfma_f32_16x16x32_bf16 v[6:9], v[196:199], v[188:191], v[6:9]
	v_mfma_f32_16x16x32_bf16 v[2:5], v[204:207], v[188:191], v[2:5]
	v_mfma_f32_16x16x32_bf16 v[46:49], v[200:203], v[168:171], v[46:49]
	v_mfma_f32_16x16x32_bf16 v[42:45], v[216:219], v[168:171], v[42:45]
	v_mfma_f32_16x16x32_bf16 v[30:33], v[200:203], v[176:179], v[30:33]
	v_mfma_f32_16x16x32_bf16 v[26:29], v[216:219], v[176:179], v[26:29]
	v_mfma_f32_16x16x32_bf16 v[14:17], v[200:203], v[184:187], v[14:17]
	v_mfma_f32_16x16x32_bf16 v[10:13], v[216:219], v[184:187], v[10:13]
	v_mfma_f32_16x16x32_bf16 v[6:9], v[200:203], v[192:195], v[6:9]
	v_mfma_f32_16x16x32_bf16 v[2:5], v[216:219], v[192:195], v[2:5]
	s_setprio 0
	s_add_i32 s69, 0, 0x18000
	s_barrier
	ds_read_b128 v[142:145], v226
	ds_read_b128 v[152:155], v226 offset:1024
	ds_read_b128 v[156:159], v226 offset:2048
	ds_read_b128 v[160:163], v226 offset:3072
	s_add_u32 s38, s38, 0x80000
	s_addc_u32 s39, s39, 0
	s_mov_b32 m0, s45
	ds_read_b128 v[164:167], v141 offset:32768
	ds_read_b128 v[168:171], v141 offset:33792
	ds_read_b128 v[172:175], v141 offset:34816
	ds_read_b128 v[176:179], v141 offset:35840
	ds_read_b128 v[180:183], v141 offset:36864
	ds_read_b128 v[184:187], v141 offset:37888
	ds_read_b128 v[188:191], v141 offset:38912
	global_load_lds_dwordx4 v134, s[38:39]
	s_mov_b32 m0, s50
	ds_read_b128 v[192:195], v141 offset:39936
	global_load_lds_dwordx4 v132, s[38:39]
	s_waitcnt lgkmcnt(8)
	s_barrier
	s_setprio 1
	s_waitcnt lgkmcnt(7)
	v_mfma_f32_16x16x32_bf16 v[126:129], v[142:145], v[164:167], v[126:129]
	v_mfma_f32_16x16x32_bf16 v[122:125], v[156:159], v[164:167], v[122:125]
	s_waitcnt lgkmcnt(5)
	v_mfma_f32_16x16x32_bf16 v[118:121], v[142:145], v[172:175], v[118:121]
	v_mfma_f32_16x16x32_bf16 v[114:117], v[156:159], v[172:175], v[114:117]
	s_waitcnt lgkmcnt(3)
	v_mfma_f32_16x16x32_bf16 v[102:105], v[142:145], v[180:183], v[102:105]
	v_mfma_f32_16x16x32_bf16 v[98:101], v[156:159], v[180:183], v[98:101]
	s_waitcnt lgkmcnt(1)
	v_mfma_f32_16x16x32_bf16 v[86:89], v[142:145], v[188:191], v[86:89]
	v_mfma_f32_16x16x32_bf16 v[82:85], v[156:159], v[188:191], v[82:85]
	v_mfma_f32_16x16x32_bf16 v[126:129], v[152:155], v[168:171], v[126:129]
	v_mfma_f32_16x16x32_bf16 v[122:125], v[160:163], v[168:171], v[122:125]
	v_mfma_f32_16x16x32_bf16 v[118:121], v[152:155], v[176:179], v[118:121]
	v_mfma_f32_16x16x32_bf16 v[114:117], v[160:163], v[176:179], v[114:117]
	v_mfma_f32_16x16x32_bf16 v[102:105], v[152:155], v[184:187], v[102:105]
	v_mfma_f32_16x16x32_bf16 v[98:101], v[160:163], v[184:187], v[98:101]
	s_waitcnt lgkmcnt(0)
	v_mfma_f32_16x16x32_bf16 v[86:89], v[152:155], v[192:195], v[86:89]
	v_mfma_f32_16x16x32_bf16 v[82:85], v[160:163], v[192:195], v[82:85]
	s_setprio 0
	s_barrier
	s_add_i32 s38, 0, 0x1c000
	s_add_i32 s39, s69, s40
	s_add_u32 s100, s36, 0x80
	s_addc_u32 s101, s37, 0
	s_mov_b32 m0, s39
	ds_read_b128 v[196:199], v227
	ds_read_b128 v[200:203], v227 offset:1024
	ds_read_b128 v[204:207], v227 offset:2048
	global_load_lds_dwordx4 v0, s[100:101]
	s_add_i32 m0, s39, 0x2000
	ds_read_b128 v[216:219], v227 offset:3072
	global_load_lds_dwordx4 v130, s[100:101]
	s_barrier
	s_setprio 1
	s_waitcnt lgkmcnt(3)
	v_mfma_f32_16x16x32_bf16 v[110:113], v[196:199], v[164:167], v[110:113]
	s_waitcnt lgkmcnt(1)
	v_mfma_f32_16x16x32_bf16 v[106:109], v[204:207], v[164:167], v[106:109]
	v_mfma_f32_16x16x32_bf16 v[94:97], v[196:199], v[172:175], v[94:97]
	v_mfma_f32_16x16x32_bf16 v[90:93], v[204:207], v[172:175], v[90:93]
	v_mfma_f32_16x16x32_bf16 v[78:81], v[196:199], v[180:183], v[78:81]
	v_mfma_f32_16x16x32_bf16 v[74:77], v[204:207], v[180:183], v[74:77]
	v_mfma_f32_16x16x32_bf16 v[70:73], v[196:199], v[188:191], v[70:73]
	v_mfma_f32_16x16x32_bf16 v[66:69], v[204:207], v[188:191], v[66:69]
	v_mfma_f32_16x16x32_bf16 v[110:113], v[200:203], v[168:171], v[110:113]
	s_waitcnt lgkmcnt(0)
	v_mfma_f32_16x16x32_bf16 v[106:109], v[216:219], v[168:171], v[106:109]
	v_mfma_f32_16x16x32_bf16 v[94:97], v[200:203], v[176:179], v[94:97]
	v_mfma_f32_16x16x32_bf16 v[90:93], v[216:219], v[176:179], v[90:93]
	v_mfma_f32_16x16x32_bf16 v[78:81], v[200:203], v[184:187], v[78:81]
	v_mfma_f32_16x16x32_bf16 v[74:77], v[216:219], v[184:187], v[74:77]
	v_mfma_f32_16x16x32_bf16 v[70:73], v[200:203], v[192:195], v[70:73]
	v_mfma_f32_16x16x32_bf16 v[66:69], v[216:219], v[192:195], v[66:69]
	s_setprio 0
	s_mov_b32 m0, s52
	s_barrier
	ds_read_b128 v[164:167], v141 offset:49152
	ds_read_b128 v[168:171], v141 offset:50176
	ds_read_b128 v[172:175], v141 offset:51200
	ds_read_b128 v[176:179], v141 offset:52224
	ds_read_b128 v[180:183], v141 offset:53248
	ds_read_b128 v[184:187], v141 offset:54272
	ds_read_b128 v[188:191], v141 offset:55296
	global_load_lds_dwordx4 v134, s[98:99]
	s_mov_b32 m0, s53
	ds_read_b128 v[192:195], v141 offset:56320
	global_load_lds_dwordx4 v132, s[98:99]
	s_barrier
	s_setprio 1
	s_waitcnt lgkmcnt(7)
	v_mfma_f32_16x16x32_bf16 v[62:65], v[142:145], v[164:167], v[62:65]
	v_mfma_f32_16x16x32_bf16 v[58:61], v[156:159], v[164:167], v[58:61]
	s_waitcnt lgkmcnt(5)
	v_mfma_f32_16x16x32_bf16 v[54:57], v[142:145], v[172:175], v[54:57]
	v_mfma_f32_16x16x32_bf16 v[50:53], v[156:159], v[172:175], v[50:53]
	s_waitcnt lgkmcnt(3)
	v_mfma_f32_16x16x32_bf16 v[38:41], v[142:145], v[180:183], v[38:41]
	v_mfma_f32_16x16x32_bf16 v[34:37], v[156:159], v[180:183], v[34:37]
	s_waitcnt lgkmcnt(1)
	v_mfma_f32_16x16x32_bf16 v[22:25], v[142:145], v[188:191], v[22:25]
	v_mfma_f32_16x16x32_bf16 v[18:21], v[156:159], v[188:191], v[18:21]
	v_mfma_f32_16x16x32_bf16 v[62:65], v[152:155], v[168:171], v[62:65]
	v_mfma_f32_16x16x32_bf16 v[58:61], v[160:163], v[168:171], v[58:61]
	v_mfma_f32_16x16x32_bf16 v[54:57], v[152:155], v[176:179], v[54:57]
	v_mfma_f32_16x16x32_bf16 v[50:53], v[160:163], v[176:179], v[50:53]
	v_mfma_f32_16x16x32_bf16 v[38:41], v[152:155], v[184:187], v[38:41]
	v_mfma_f32_16x16x32_bf16 v[34:37], v[160:163], v[184:187], v[34:37]
	s_waitcnt lgkmcnt(0)
	v_mfma_f32_16x16x32_bf16 v[22:25], v[152:155], v[192:195], v[22:25]
	v_mfma_f32_16x16x32_bf16 v[18:21], v[160:163], v[192:195], v[18:21]
	s_setprio 0
	s_barrier
	s_add_i32 s38, s38, s40
	s_mov_b32 m0, s38
	s_add_u32 s36, s36, 0x80080
	s_addc_u32 s37, s37, 0
	global_load_lds_dwordx4 v0, s[36:37]
	s_add_i32 m0, s38, 0x2000
	s_nop 0
	global_load_lds_dwordx4 v130, s[36:37]
	s_waitcnt vmcnt(6)
	s_barrier
	s_setprio 1
	v_mfma_f32_16x16x32_bf16 v[46:49], v[196:199], v[164:167], v[46:49]
	v_mfma_f32_16x16x32_bf16 v[42:45], v[204:207], v[164:167], v[42:45]
	v_mfma_f32_16x16x32_bf16 v[30:33], v[196:199], v[172:175], v[30:33]
	v_mfma_f32_16x16x32_bf16 v[26:29], v[204:207], v[172:175], v[26:29]
	v_mfma_f32_16x16x32_bf16 v[14:17], v[196:199], v[180:183], v[14:17]
	v_mfma_f32_16x16x32_bf16 v[10:13], v[204:207], v[180:183], v[10:13]
	v_mfma_f32_16x16x32_bf16 v[6:9], v[196:199], v[188:191], v[6:9]
	v_mfma_f32_16x16x32_bf16 v[2:5], v[204:207], v[188:191], v[2:5]
	v_mfma_f32_16x16x32_bf16 v[46:49], v[200:203], v[168:171], v[46:49]
	v_mfma_f32_16x16x32_bf16 v[42:45], v[216:219], v[168:171], v[42:45]
	v_mfma_f32_16x16x32_bf16 v[30:33], v[200:203], v[176:179], v[30:33]
	v_mfma_f32_16x16x32_bf16 v[26:29], v[216:219], v[176:179], v[26:29]
	v_mfma_f32_16x16x32_bf16 v[14:17], v[200:203], v[184:187], v[14:17]
	v_mfma_f32_16x16x32_bf16 v[10:13], v[216:219], v[184:187], v[10:13]
	v_mfma_f32_16x16x32_bf16 v[6:9], v[200:203], v[192:195], v[6:9]
	v_mfma_f32_16x16x32_bf16 v[2:5], v[216:219], v[192:195], v[2:5]
	s_setprio 0
	s_add_i32 s68, s68, 2
	s_add_u32 s30, s30, 0x100
	s_addc_u32 s31, s31, 0
	s_add_u32 s43, s43, 0x100
	s_addc_u32 s67, s67, 0
	s_cmp_gt_u32 s68, 29
	s_barrier
	s_cbranch_scc0 .LBB0_939
	s_lshr_b32 s23, s66, 3
	s_mulk_i32 s23, 0x880
	s_lshl_b32 s30, s66, 8
	v_mov_b32_e32 v142, v148
	s_and_b32 s30, s30, 0x700
	s_add_i32 s23, s60, s23
	s_add_i32 s23, s23, s30
	v_and_or_b32 v144, v142, 15, s23
	s_lshl_b32 s23, s65, 8
	v_lshrrev_b32_e32 v142, 1, v142
	v_and_or_b32 v142, v142, 24, s23
	v_or_b32_e32 v142, s51, v142
	v_cvt_pk_bf16_f32 v126, v126, v127
	v_cvt_pk_bf16_f32 v127, v128, v129
	v_cvt_pk_bf16_f32 v128, v122, v123
	v_mov_b64_e32 v[122:123], s[6:7]
	v_ashrrev_i32_e32 v143, 31, v142
	v_cvt_pk_bf16_f32 v70, v70, v71
	v_cvt_pk_bf16_f32 v71, v72, v73
	v_cvt_pk_bf16_f32 v72, v66, v67
	v_add_u32_e32 v66, 0x80, v144
	v_cvt_pk_bf16_f32 v129, v124, v125
	v_mad_i64_i32 v[124:125], s[30:31], v144, s74, v[122:123]
	v_lshlrev_b64 v[142:143], 1, v[142:143]
	v_cvt_pk_bf16_f32 v62, v62, v63
	v_cvt_pk_bf16_f32 v63, v64, v65
	v_cvt_pk_bf16_f32 v64, v58, v59
	v_mad_i64_i32 v[58:59], s[30:31], v66, s74, v[122:123]
	v_lshl_add_u64 v[124:125], v[124:125], 0, v[142:143]
	v_cvt_pk_bf16_f32 v110, v110, v111
	v_cvt_pk_bf16_f32 v111, v112, v113
	v_cvt_pk_bf16_f32 v112, v106, v107
	v_cvt_pk_bf16_f32 v113, v108, v109
	v_lshl_add_u64 v[58:59], v[58:59], 0, v[142:143]
	v_cvt_pk_bf16_f32 v46, v46, v47
	v_cvt_pk_bf16_f32 v47, v48, v49
	v_cvt_pk_bf16_f32 v48, v42, v43
	v_cvt_pk_bf16_f32 v49, v44, v45
	global_store_dwordx4 v[124:125], v[110:113], off offset:256
	global_store_dwordx4 v[58:59], v[46:49], off offset:256
	v_cvt_pk_bf16_f32 v94, v94, v95
	v_add_u32_e32 v110, 16, v144
	v_add_u32_e32 v46, 0x90, v144
	v_mad_i64_i32 v[110:111], s[30:31], v110, s74, v[122:123]
	v_mad_i64_i32 v[46:47], s[30:31], v46, s74, v[122:123]
	v_lshl_add_u64 v[110:111], v[110:111], 0, v[142:143]
	v_cvt_pk_bf16_f32 v95, v96, v97
	v_cvt_pk_bf16_f32 v96, v90, v91
	v_cvt_pk_bf16_f32 v97, v92, v93
	v_lshl_add_u64 v[46:47], v[46:47], 0, v[142:143]
	v_cvt_pk_bf16_f32 v30, v30, v31
	v_cvt_pk_bf16_f32 v31, v32, v33
	v_cvt_pk_bf16_f32 v32, v26, v27
	v_cvt_pk_bf16_f32 v33, v28, v29
	global_store_dwordx4 v[110:111], v[94:97], off offset:256
	global_store_dwordx4 v[46:47], v[30:33], off offset:256
	v_cvt_pk_bf16_f32 v78, v78, v79
	v_add_u32_e32 v94, 32, v144
	v_add_u32_e32 v30, 0xa0, v144
	v_mad_i64_i32 v[94:95], s[30:31], v94, s74, v[122:123]
	v_mad_i64_i32 v[30:31], s[30:31], v30, s74, v[122:123]
	v_lshl_add_u64 v[94:95], v[94:95], 0, v[142:143]
	v_cvt_pk_bf16_f32 v79, v80, v81
	v_cvt_pk_bf16_f32 v80, v74, v75
	v_cvt_pk_bf16_f32 v81, v76, v77
	v_lshl_add_u64 v[30:31], v[30:31], 0, v[142:143]
	v_cvt_pk_bf16_f32 v14, v14, v15
	v_cvt_pk_bf16_f32 v15, v16, v17
	v_cvt_pk_bf16_f32 v16, v10, v11
	v_cvt_pk_bf16_f32 v17, v12, v13
	global_store_dwordx4 v[94:95], v[78:81], off offset:256
	global_store_dwordx4 v[30:31], v[14:17], off offset:256
	v_cvt_pk_bf16_f32 v106, v118, v119
	v_add_u32_e32 v78, 48, v144
	v_add_u32_e32 v14, 0xb0, v144
	v_mad_i64_i32 v[78:79], s[30:31], v78, s74, v[122:123]
	v_mad_i64_i32 v[14:15], s[30:31], v14, s74, v[122:123]
	v_cvt_pk_bf16_f32 v107, v120, v121
	v_cvt_pk_bf16_f32 v108, v114, v115
	v_cvt_pk_bf16_f32 v109, v116, v117
	v_cvt_pk_bf16_f32 v90, v102, v103
	v_cvt_pk_bf16_f32 v91, v104, v105
	v_cvt_pk_bf16_f32 v92, v98, v99
	v_cvt_pk_bf16_f32 v93, v100, v101
	v_cvt_pk_bf16_f32 v74, v86, v87
	v_cvt_pk_bf16_f32 v75, v88, v89
	v_cvt_pk_bf16_f32 v76, v82, v83
	v_cvt_pk_bf16_f32 v77, v84, v85
	v_lshl_add_u64 v[78:79], v[78:79], 0, v[142:143]
	v_cvt_pk_bf16_f32 v73, v68, v69
	v_cvt_pk_bf16_f32 v65, v60, v61
	v_cvt_pk_bf16_f32 v42, v54, v55
	v_cvt_pk_bf16_f32 v43, v56, v57
	v_cvt_pk_bf16_f32 v44, v50, v51
	v_cvt_pk_bf16_f32 v45, v52, v53
	v_cvt_pk_bf16_f32 v26, v38, v39
	v_cvt_pk_bf16_f32 v27, v40, v41
	v_cvt_pk_bf16_f32 v28, v34, v35
	v_cvt_pk_bf16_f32 v29, v36, v37
	v_cvt_pk_bf16_f32 v10, v22, v23
	v_cvt_pk_bf16_f32 v11, v24, v25
	v_cvt_pk_bf16_f32 v12, v18, v19
	v_cvt_pk_bf16_f32 v13, v20, v21
	v_lshl_add_u64 v[14:15], v[14:15], 0, v[142:143]
	v_cvt_pk_bf16_f32 v6, v6, v7
	v_cvt_pk_bf16_f32 v7, v8, v9
	v_cvt_pk_bf16_f32 v8, v2, v3
	v_cvt_pk_bf16_f32 v9, v4, v5
	s_and_b64 vcc, exec, s[0:1]
	s_mov_b32 s65, s22
	s_mov_b32 s66, s64
	s_mov_b64 s[36:37], s[28:29]
	s_mov_b64 s[30:31], s[26:27]
	global_store_dwordx4 v[124:125], v[126:129], off
	global_store_dwordx4 v[110:111], v[106:109], off
	global_store_dwordx4 v[94:95], v[90:93], off
	global_store_dwordx4 v[78:79], v[74:77], off
	global_store_dwordx4 v[78:79], v[70:73], off offset:256
	global_store_dwordx4 v[58:59], v[62:65], off
	global_store_dwordx4 v[46:47], v[42:45], off
	global_store_dwordx4 v[30:31], v[26:29], off
	global_store_dwordx4 v[14:15], v[10:13], off
	global_store_dwordx4 v[14:15], v[6:9], off offset:256
	s_cbranch_vccz .LBB0_934
	s_waitcnt vmcnt(0)
	s_cmpk_gt_u32 s14, 0xff
	s_cbranch_scc1 .LBB0_943
	s_barrier

.LBB0_1083:
	s_add_u32 s42, s22, 0x100
	s_addc_u32 s43, s23, 0
	s_add_u32 s22, s6, 0x158080
	s_addc_u32 s23, s7, 0
	v_lshl_add_u64 v[142:143], s[22:23], 0, v[138:139]
	v_lshl_add_u64 v[144:145], s[22:23], 0, v[140:141]
	s_mov_b32 s78, -2
	s_mov_b64 s[22:23], 0
	v_add_u32_e32 v224, 0x10000, v146
	v_add_u32_e32 v225, 0x14000, v146
	v_add_u32_e32 v226, 0x18000, v146
	v_add_u32_e32 v227, 0x1c000, v146
.LBB0_1084:
	s_add_u32 s30, s6, s22
	s_addc_u32 s31, s7, s23
	s_add_u32 s30, s30, 0x100
	s_addc_u32 s31, s31, 0
	s_add_u32 s79, s42, s22
	s_addc_u32 s80, s43, s23
	s_add_i32 s81, 0, 0x10000
	ds_read_b128 v[152:155], v224
	ds_read_b128 v[156:159], v224 offset:1024
	ds_read_b128 v[160:163], v224 offset:2048
	ds_read_b128 v[164:167], v224 offset:3072
	s_cmpk_eq_i32 s22, 0x2a00
	s_cselect_b32 s41, s13, s31
	s_cselect_b32 s40, s12, s30
	s_cselect_b32 s31, s9, s80
	s_cselect_b32 s30, s8, s79
	v_lshl_add_u64 v[200:201], v[142:143], 0, s[22:23]
	s_add_i32 m0, s53, 0xc000
	ds_read_b128 v[168:171], v147
	ds_read_b128 v[172:175], v147 offset:1024
	ds_read_b128 v[176:179], v147 offset:2048
	ds_read_b128 v[180:183], v147 offset:3072
	ds_read_b128 v[184:187], v147 offset:4096
	ds_read_b128 v[188:191], v147 offset:5120
	ds_read_b128 v[192:195], v147 offset:6144
	ds_read_b128 v[196:199], v147 offset:7168
	global_load_lds_dwordx4 v[200:201], off
	v_lshl_add_u64 v[200:201], v[144:145], 0, s[22:23]
	s_add_i32 m0, s53, 0xe000
	s_nop 0
	global_load_lds_dwordx4 v[200:201], off
	s_waitcnt lgkmcnt(8)
	s_barrier
	s_setprio 1
	s_waitcnt lgkmcnt(7)
	v_mfma_f32_16x16x32_bf16 v[126:129], v[152:155], v[168:171], v[126:129]
	v_mfma_f32_16x16x32_bf16 v[122:125], v[160:163], v[168:171], v[122:125]
	s_waitcnt lgkmcnt(5)
	v_mfma_f32_16x16x32_bf16 v[110:113], v[152:155], v[176:179], v[110:113]
	v_mfma_f32_16x16x32_bf16 v[106:109], v[160:163], v[176:179], v[106:109]
	s_waitcnt lgkmcnt(3)
	v_mfma_f32_16x16x32_bf16 v[94:97], v[152:155], v[184:187], v[94:97]
	v_mfma_f32_16x16x32_bf16 v[90:93], v[160:163], v[184:187], v[90:93]
	s_waitcnt lgkmcnt(1)
	v_mfma_f32_16x16x32_bf16 v[78:81], v[152:155], v[192:195], v[78:81]
	v_mfma_f32_16x16x32_bf16 v[74:77], v[160:163], v[192:195], v[74:77]
	v_mfma_f32_16x16x32_bf16 v[126:129], v[156:159], v[172:175], v[126:129]
	v_mfma_f32_16x16x32_bf16 v[122:125], v[164:167], v[172:175], v[122:125]
	v_mfma_f32_16x16x32_bf16 v[110:113], v[156:159], v[180:183], v[110:113]
	v_mfma_f32_16x16x32_bf16 v[106:109], v[164:167], v[180:183], v[106:109]
	v_mfma_f32_16x16x32_bf16 v[94:97], v[156:159], v[188:191], v[94:97]
	v_mfma_f32_16x16x32_bf16 v[90:93], v[164:167], v[188:191], v[90:93]
	s_waitcnt lgkmcnt(0)
	v_mfma_f32_16x16x32_bf16 v[78:81], v[156:159], v[196:199], v[78:81]
	v_mfma_f32_16x16x32_bf16 v[74:77], v[164:167], v[196:199], v[74:77]
	s_setprio 0
	s_barrier
	s_add_i32 s79, 0, 0x14000
	s_add_i32 s80, s81, s52
	s_mov_b32 m0, s80
	ds_read_b128 v[200:203], v225
	ds_read_b128 v[204:207], v225 offset:1024
	ds_read_b128 v[216:219], v225 offset:2048
	global_load_lds_dwordx4 v0, s[30:31]
	s_add_i32 m0, s80, 0x2000
	ds_read_b128 v[220:223], v225 offset:3072
	global_load_lds_dwordx4 v136, s[30:31]
	s_barrier
	s_setprio 1
	s_waitcnt lgkmcnt(3)
	v_mfma_f32_16x16x32_bf16 v[118:121], v[200:203], v[168:171], v[118:121]
	s_waitcnt lgkmcnt(1)
	v_mfma_f32_16x16x32_bf16 v[114:117], v[216:219], v[168:171], v[114:117]
	v_mfma_f32_16x16x32_bf16 v[102:105], v[200:203], v[176:179], v[102:105]
	v_mfma_f32_16x16x32_bf16 v[98:101], v[216:219], v[176:179], v[98:101]
	v_mfma_f32_16x16x32_bf16 v[86:89], v[200:203], v[184:187], v[86:89]
	v_mfma_f32_16x16x32_bf16 v[82:85], v[216:219], v[184:187], v[82:85]
	v_mfma_f32_16x16x32_bf16 v[70:73], v[200:203], v[192:195], v[70:73]
	v_mfma_f32_16x16x32_bf16 v[66:69], v[216:219], v[192:195], v[66:69]
	v_mfma_f32_16x16x32_bf16 v[118:121], v[204:207], v[172:175], v[118:121]
	s_waitcnt lgkmcnt(0)
	v_mfma_f32_16x16x32_bf16 v[114:117], v[220:223], v[172:175], v[114:117]
	v_mfma_f32_16x16x32_bf16 v[102:105], v[204:207], v[180:183], v[102:105]
	v_mfma_f32_16x16x32_bf16 v[98:101], v[220:223], v[180:183], v[98:101]
	v_mfma_f32_16x16x32_bf16 v[86:89], v[204:207], v[188:191], v[86:89]
	v_mfma_f32_16x16x32_bf16 v[82:85], v[220:223], v[188:191], v[82:85]
	v_mfma_f32_16x16x32_bf16 v[70:73], v[204:207], v[196:199], v[70:73]
	v_mfma_f32_16x16x32_bf16 v[66:69], v[220:223], v[196:199], v[66:69]
	s_setprio 0
	s_mov_b32 m0, s53
	s_add_u32 s98, s40, 0x80
	s_addc_u32 s99, s41, 0
	s_barrier
	ds_read_b128 v[168:171], v147 offset:16384
	ds_read_b128 v[172:175], v147 offset:17408
	ds_read_b128 v[176:179], v147 offset:18432
	ds_read_b128 v[180:183], v147 offset:19456
	ds_read_b128 v[184:187], v147 offset:20480
	ds_read_b128 v[188:191], v147 offset:21504
	ds_read_b128 v[192:195], v147 offset:22528
	global_load_lds_dwordx4 v0, s[40:41]
	s_mov_b32 m0, s60
	ds_read_b128 v[196:199], v147 offset:23552
	global_load_lds_dwordx4 v136, s[40:41]
	s_barrier
	s_setprio 1
	s_waitcnt lgkmcnt(7)
	v_mfma_f32_16x16x32_bf16 v[62:65], v[152:155], v[168:171], v[62:65]
	v_mfma_f32_16x16x32_bf16 v[58:61], v[160:163], v[168:171], v[58:61]
	s_waitcnt lgkmcnt(5)
	v_mfma_f32_16x16x32_bf16 v[46:49], v[152:155], v[176:179], v[46:49]
	v_mfma_f32_16x16x32_bf16 v[42:45], v[160:163], v[176:179], v[42:45]
	s_waitcnt lgkmcnt(3)
	v_mfma_f32_16x16x32_bf16 v[30:33], v[152:155], v[184:187], v[30:33]
	v_mfma_f32_16x16x32_bf16 v[26:29], v[160:163], v[184:187], v[26:29]
	s_waitcnt lgkmcnt(1)
	v_mfma_f32_16x16x32_bf16 v[14:17], v[152:155], v[192:195], v[14:17]
	v_mfma_f32_16x16x32_bf16 v[10:13], v[160:163], v[192:195], v[10:13]
	v_mfma_f32_16x16x32_bf16 v[62:65], v[156:159], v[172:175], v[62:65]
	v_mfma_f32_16x16x32_bf16 v[58:61], v[164:167], v[172:175], v[58:61]
	v_mfma_f32_16x16x32_bf16 v[46:49], v[156:159], v[180:183], v[46:49]
	v_mfma_f32_16x16x32_bf16 v[42:45], v[164:167], v[180:183], v[42:45]
	v_mfma_f32_16x16x32_bf16 v[30:33], v[156:159], v[188:191], v[30:33]
	v_mfma_f32_16x16x32_bf16 v[26:29], v[164:167], v[188:191], v[26:29]
	s_waitcnt lgkmcnt(0)
	v_mfma_f32_16x16x32_bf16 v[14:17], v[156:159], v[196:199], v[14:17]
	v_mfma_f32_16x16x32_bf16 v[10:13], v[164:167], v[196:199], v[10:13]
	s_setprio 0
	s_barrier
	s_add_i32 s79, s79, s52
	s_mov_b32 m0, s79
	s_add_u32 s80, s30, 0x158000
	s_addc_u32 s81, s31, 0
	global_load_lds_dwordx4 v0, s[80:81]
	s_add_i32 m0, s79, 0x2000
	s_nop 0
	global_load_lds_dwordx4 v136, s[80:81]
	s_waitcnt vmcnt(6)
	s_barrier
	s_setprio 1
	v_mfma_f32_16x16x32_bf16 v[54:57], v[200:203], v[168:171], v[54:57]
	v_mfma_f32_16x16x32_bf16 v[50:53], v[216:219], v[168:171], v[50:53]
	v_mfma_f32_16x16x32_bf16 v[38:41], v[200:203], v[176:179], v[38:41]
	v_mfma_f32_16x16x32_bf16 v[34:37], v[216:219], v[176:179], v[34:37]
	v_mfma_f32_16x16x32_bf16 v[22:25], v[200:203], v[184:187], v[22:25]
	v_mfma_f32_16x16x32_bf16 v[18:21], v[216:219], v[184:187], v[18:21]
	v_mfma_f32_16x16x32_bf16 v[6:9], v[200:203], v[192:195], v[6:9]
	v_mfma_f32_16x16x32_bf16 v[2:5], v[216:219], v[192:195], v[2:5]
	v_mfma_f32_16x16x32_bf16 v[54:57], v[204:207], v[172:175], v[54:57]
	v_mfma_f32_16x16x32_bf16 v[50:53], v[220:223], v[172:175], v[50:53]
	v_mfma_f32_16x16x32_bf16 v[38:41], v[204:207], v[180:183], v[38:41]
	v_mfma_f32_16x16x32_bf16 v[34:37], v[220:223], v[180:183], v[34:37]
	v_mfma_f32_16x16x32_bf16 v[22:25], v[204:207], v[188:191], v[22:25]
	v_mfma_f32_16x16x32_bf16 v[18:21], v[220:223], v[188:191], v[18:21]
	v_mfma_f32_16x16x32_bf16 v[6:9], v[204:207], v[196:199], v[6:9]
	v_mfma_f32_16x16x32_bf16 v[2:5], v[220:223], v[196:199], v[2:5]
	s_setprio 0
	s_add_i32 s79, 0, 0x18000
	s_barrier
	ds_read_b128 v[152:155], v226
	ds_read_b128 v[156:159], v226 offset:1024
	ds_read_b128 v[160:163], v226 offset:2048
	ds_read_b128 v[164:167], v226 offset:3072
	s_add_u32 s40, s40, 0x158000
	s_addc_u32 s41, s41, 0
	s_mov_b32 m0, s65
	ds_read_b128 v[168:171], v147 offset:32768
	ds_read_b128 v[172:175], v147 offset:33792
	ds_read_b128 v[176:179], v147 offset:34816
	ds_read_b128 v[180:183], v147 offset:35840
	ds_read_b128 v[184:187], v147 offset:36864
	ds_read_b128 v[188:191], v147 offset:37888
	ds_read_b128 v[192:195], v147 offset:38912
	global_load_lds_dwordx4 v0, s[40:41]
	s_mov_b32 m0, s66
	ds_read_b128 v[196:199], v147 offset:39936
	global_load_lds_dwordx4 v136, s[40:41]
	s_waitcnt lgkmcnt(8)
	s_barrier
	s_setprio 1
	s_waitcnt lgkmcnt(7)
	v_mfma_f32_16x16x32_bf16 v[126:129], v[152:155], v[168:171], v[126:129]
	v_mfma_f32_16x16x32_bf16 v[122:125], v[160:163], v[168:171], v[122:125]
	s_waitcnt lgkmcnt(5)
	v_mfma_f32_16x16x32_bf16 v[110:113], v[152:155], v[176:179], v[110:113]
	v_mfma_f32_16x16x32_bf16 v[106:109], v[160:163], v[176:179], v[106:109]
	s_waitcnt lgkmcnt(3)
	v_mfma_f32_16x16x32_bf16 v[94:97], v[152:155], v[184:187], v[94:97]
	v_mfma_f32_16x16x32_bf16 v[90:93], v[160:163], v[184:187], v[90:93]
	s_waitcnt lgkmcnt(1)
	v_mfma_f32_16x16x32_bf16 v[78:81], v[152:155], v[192:195], v[78:81]
	v_mfma_f32_16x16x32_bf16 v[74:77], v[160:163], v[192:195], v[74:77]
	v_mfma_f32_16x16x32_bf16 v[126:129], v[156:159], v[172:175], v[126:129]
	v_mfma_f32_16x16x32_bf16 v[122:125], v[164:167], v[172:175], v[122:125]
	v_mfma_f32_16x16x32_bf16 v[110:113], v[156:159], v[180:183], v[110:113]
	v_mfma_f32_16x16x32_bf16 v[106:109], v[164:167], v[180:183], v[106:109]
	v_mfma_f32_16x16x32_bf16 v[94:97], v[156:159], v[188:191], v[94:97]
	v_mfma_f32_16x16x32_bf16 v[90:93], v[164:167], v[188:191], v[90:93]
	s_waitcnt lgkmcnt(0)
	v_mfma_f32_16x16x32_bf16 v[78:81], v[156:159], v[196:199], v[78:81]
	v_mfma_f32_16x16x32_bf16 v[74:77], v[164:167], v[196:199], v[74:77]
	s_setprio 0
	s_barrier
	s_add_i32 s40, 0, 0x1c000
	s_add_i32 s41, s79, s52
	s_add_u32 s100, s30, 0x80
	s_addc_u32 s101, s31, 0
	s_mov_b32 m0, s41
	ds_read_b128 v[200:203], v227
	ds_read_b128 v[204:207], v227 offset:1024
	ds_read_b128 v[216:219], v227 offset:2048
	global_load_lds_dwordx4 v0, s[100:101]
	s_add_i32 m0, s41, 0x2000
	ds_read_b128 v[220:223], v227 offset:3072
	global_load_lds_dwordx4 v136, s[100:101]
	s_barrier
	s_setprio 1
	s_waitcnt lgkmcnt(3)
	v_mfma_f32_16x16x32_bf16 v[118:121], v[200:203], v[168:171], v[118:121]
	s_waitcnt lgkmcnt(1)
	v_mfma_f32_16x16x32_bf16 v[114:117], v[216:219], v[168:171], v[114:117]
	v_mfma_f32_16x16x32_bf16 v[102:105], v[200:203], v[176:179], v[102:105]
	v_mfma_f32_16x16x32_bf16 v[98:101], v[216:219], v[176:179], v[98:101]
	v_mfma_f32_16x16x32_bf16 v[86:89], v[200:203], v[184:187], v[86:89]
	v_mfma_f32_16x16x32_bf16 v[82:85], v[216:219], v[184:187], v[82:85]
	v_mfma_f32_16x16x32_bf16 v[70:73], v[200:203], v[192:195], v[70:73]
	v_mfma_f32_16x16x32_bf16 v[66:69], v[216:219], v[192:195], v[66:69]
	v_mfma_f32_16x16x32_bf16 v[118:121], v[204:207], v[172:175], v[118:121]
	s_waitcnt lgkmcnt(0)
	v_mfma_f32_16x16x32_bf16 v[114:117], v[220:223], v[172:175], v[114:117]
	v_mfma_f32_16x16x32_bf16 v[102:105], v[204:207], v[180:183], v[102:105]
	v_mfma_f32_16x16x32_bf16 v[98:101], v[220:223], v[180:183], v[98:101]
	v_mfma_f32_16x16x32_bf16 v[86:89], v[204:207], v[188:191], v[86:89]
	v_mfma_f32_16x16x32_bf16 v[82:85], v[220:223], v[188:191], v[82:85]
	v_mfma_f32_16x16x32_bf16 v[70:73], v[204:207], v[196:199], v[70:73]
	v_mfma_f32_16x16x32_bf16 v[66:69], v[220:223], v[196:199], v[66:69]
	s_setprio 0
	s_mov_b32 m0, s67
	s_barrier
	ds_read_b128 v[168:171], v147 offset:49152
	ds_read_b128 v[172:175], v147 offset:50176
	ds_read_b128 v[176:179], v147 offset:51200
	ds_read_b128 v[180:183], v147 offset:52224
	ds_read_b128 v[184:187], v147 offset:53248
	ds_read_b128 v[188:191], v147 offset:54272
	ds_read_b128 v[192:195], v147 offset:55296
	global_load_lds_dwordx4 v0, s[98:99]
	s_mov_b32 m0, s68
	ds_read_b128 v[196:199], v147 offset:56320
	global_load_lds_dwordx4 v136, s[98:99]
	s_barrier
	s_setprio 1
	s_waitcnt lgkmcnt(7)
	v_mfma_f32_16x16x32_bf16 v[62:65], v[152:155], v[168:171], v[62:65]
	v_mfma_f32_16x16x32_bf16 v[58:61], v[160:163], v[168:171], v[58:61]
	s_waitcnt lgkmcnt(5)
	v_mfma_f32_16x16x32_bf16 v[46:49], v[152:155], v[176:179], v[46:49]
	v_mfma_f32_16x16x32_bf16 v[42:45], v[160:163], v[176:179], v[42:45]
	s_waitcnt lgkmcnt(3)
	v_mfma_f32_16x16x32_bf16 v[30:33], v[152:155], v[184:187], v[30:33]
	v_mfma_f32_16x16x32_bf16 v[26:29], v[160:163], v[184:187], v[26:29]
	s_waitcnt lgkmcnt(1)
	v_mfma_f32_16x16x32_bf16 v[14:17], v[152:155], v[192:195], v[14:17]
	v_mfma_f32_16x16x32_bf16 v[10:13], v[160:163], v[192:195], v[10:13]
	v_mfma_f32_16x16x32_bf16 v[62:65], v[156:159], v[172:175], v[62:65]
	v_mfma_f32_16x16x32_bf16 v[58:61], v[164:167], v[172:175], v[58:61]
	v_mfma_f32_16x16x32_bf16 v[46:49], v[156:159], v[180:183], v[46:49]
	v_mfma_f32_16x16x32_bf16 v[42:45], v[164:167], v[180:183], v[42:45]
	v_mfma_f32_16x16x32_bf16 v[30:33], v[156:159], v[188:191], v[30:33]
	v_mfma_f32_16x16x32_bf16 v[26:29], v[164:167], v[188:191], v[26:29]
	s_waitcnt lgkmcnt(0)
	v_mfma_f32_16x16x32_bf16 v[14:17], v[156:159], v[196:199], v[14:17]
	v_mfma_f32_16x16x32_bf16 v[10:13], v[164:167], v[196:199], v[10:13]
	s_setprio 0
	s_barrier
	s_add_i32 s40, s40, s52
	s_mov_b32 m0, s40
	s_add_u32 s30, s30, 0x158080
	s_addc_u32 s31, s31, 0
	global_load_lds_dwordx4 v0, s[30:31]
	s_add_i32 m0, s40, 0x2000
	s_nop 0
	global_load_lds_dwordx4 v136, s[30:31]
	s_waitcnt vmcnt(6)
	s_barrier
	s_setprio 1
	v_mfma_f32_16x16x32_bf16 v[54:57], v[200:203], v[168:171], v[54:57]
	v_mfma_f32_16x16x32_bf16 v[50:53], v[216:219], v[168:171], v[50:53]
	v_mfma_f32_16x16x32_bf16 v[38:41], v[200:203], v[176:179], v[38:41]
	v_mfma_f32_16x16x32_bf16 v[34:37], v[216:219], v[176:179], v[34:37]
	v_mfma_f32_16x16x32_bf16 v[22:25], v[200:203], v[184:187], v[22:25]
	v_mfma_f32_16x16x32_bf16 v[18:21], v[216:219], v[184:187], v[18:21]
	v_mfma_f32_16x16x32_bf16 v[6:9], v[200:203], v[192:195], v[6:9]
	v_mfma_f32_16x16x32_bf16 v[2:5], v[216:219], v[192:195], v[2:5]
	v_mfma_f32_16x16x32_bf16 v[54:57], v[204:207], v[172:175], v[54:57]
	v_mfma_f32_16x16x32_bf16 v[50:53], v[220:223], v[172:175], v[50:53]
	v_mfma_f32_16x16x32_bf16 v[38:41], v[204:207], v[180:183], v[38:41]
	v_mfma_f32_16x16x32_bf16 v[34:37], v[220:223], v[180:183], v[34:37]
	v_mfma_f32_16x16x32_bf16 v[22:25], v[204:207], v[188:191], v[22:25]
	v_mfma_f32_16x16x32_bf16 v[18:21], v[220:223], v[188:191], v[18:21]
	v_mfma_f32_16x16x32_bf16 v[6:9], v[204:207], v[196:199], v[6:9]
	v_mfma_f32_16x16x32_bf16 v[2:5], v[220:223], v[196:199], v[2:5]
	s_setprio 0
	s_add_i32 s78, s78, 2
	s_add_u32 s22, s22, 0x100
	s_addc_u32 s23, s23, 0
	s_cmpk_gt_u32 s78, 0x53
	s_barrier
	s_cbranch_scc0 .LBB0_1084
	s_add_u32 s22, s42, 0xffffff00
	s_addc_u32 s23, s43, -1
	s_and_b64 vcc, exec, s[38:39]
	s_cbranch_vccnz .LBB0_1071
	v_mov_b32_e32 v2, 0
	s_mov_b32 s14, s75
	s_mov_b32 s50, s76
	s_mov_b64 s[6:7], s[12:13]
	s_mov_b32 s69, s77
	v_mov_b32_e32 v3, v2
	v_mov_b32_e32 v4, v2
	v_mov_b32_e32 v5, v2
	v_mov_b32_e32 v6, v2
	v_mov_b32_e32 v7, v2
	v_mov_b32_e32 v8, v2
	v_mov_b32_e32 v9, v2
	v_mov_b32_e32 v18, v2
	v_mov_b32_e32 v19, v2
	v_mov_b32_e32 v20, v2
	v_mov_b32_e32 v21, v2
	v_mov_b32_e32 v22, v2
	v_mov_b32_e32 v23, v2
	v_mov_b32_e32 v24, v2
	v_mov_b32_e32 v25, v2
	v_mov_b32_e32 v34, v2
	v_mov_b32_e32 v35, v2
	v_mov_b32_e32 v36, v2
	v_mov_b32_e32 v37, v2
	v_mov_b32_e32 v38, v2
	v_mov_b32_e32 v39, v2
	v_mov_b32_e32 v40, v2
	v_mov_b32_e32 v41, v2
	v_mov_b32_e32 v50, v2
	v_mov_b32_e32 v51, v2
	v_mov_b32_e32 v52, v2
	v_mov_b32_e32 v53, v2
	v_mov_b32_e32 v54, v2
	v_mov_b32_e32 v55, v2
	v_mov_b32_e32 v56, v2
	v_mov_b32_e32 v57, v2
	v_mov_b32_e32 v10, v2
	v_mov_b32_e32 v11, v2
	v_mov_b32_e32 v12, v2
	v_mov_b32_e32 v13, v2
	v_mov_b32_e32 v14, v2
	v_mov_b32_e32 v15, v2
	v_mov_b32_e32 v16, v2
	v_mov_b32_e32 v17, v2
	v_mov_b32_e32 v26, v2
	v_mov_b32_e32 v27, v2
	v_mov_b32_e32 v28, v2
	v_mov_b32_e32 v29, v2
	v_mov_b32_e32 v30, v2
	v_mov_b32_e32 v31, v2
	v_mov_b32_e32 v32, v2
	v_mov_b32_e32 v33, v2
	v_mov_b32_e32 v42, v2
	v_mov_b32_e32 v43, v2
	v_mov_b32_e32 v44, v2
	v_mov_b32_e32 v45, v2
	v_mov_b32_e32 v46, v2
	v_mov_b32_e32 v47, v2
	v_mov_b32_e32 v48, v2
	v_mov_b32_e32 v49, v2
	v_mov_b32_e32 v58, v2
	v_mov_b32_e32 v59, v2
	v_mov_b32_e32 v60, v2
	v_mov_b32_e32 v61, v2
	v_mov_b32_e32 v62, v2
	v_mov_b32_e32 v63, v2
	v_mov_b32_e32 v64, v2
	v_mov_b32_e32 v65, v2
	v_mov_b32_e32 v66, v2
	v_mov_b32_e32 v67, v2
	v_mov_b32_e32 v68, v2
	v_mov_b32_e32 v69, v2
	v_mov_b32_e32 v70, v2
	v_mov_b32_e32 v71, v2
	v_mov_b32_e32 v72, v2
	v_mov_b32_e32 v73, v2
	v_mov_b32_e32 v82, v2
	v_mov_b32_e32 v83, v2
	v_mov_b32_e32 v84, v2
	v_mov_b32_e32 v85, v2
	v_mov_b32_e32 v86, v2
	v_mov_b32_e32 v87, v2
	v_mov_b32_e32 v88, v2
	v_mov_b32_e32 v89, v2
	v_mov_b32_e32 v98, v2
	v_mov_b32_e32 v99, v2
	v_mov_b32_e32 v100, v2
	v_mov_b32_e32 v101, v2
	v_mov_b32_e32 v102, v2
	v_mov_b32_e32 v103, v2
	v_mov_b32_e32 v104, v2
	v_mov_b32_e32 v105, v2
	v_mov_b32_e32 v114, v2
	v_mov_b32_e32 v115, v2
	v_mov_b32_e32 v116, v2
	v_mov_b32_e32 v117, v2
	v_mov_b32_e32 v118, v2
	v_mov_b32_e32 v119, v2
	v_mov_b32_e32 v120, v2
	v_mov_b32_e32 v121, v2
	v_mov_b32_e32 v74, v2
	v_mov_b32_e32 v75, v2
	v_mov_b32_e32 v76, v2
	v_mov_b32_e32 v77, v2
	v_mov_b32_e32 v78, v2
	v_mov_b32_e32 v79, v2
	v_mov_b32_e32 v80, v2
	v_mov_b32_e32 v81, v2
	v_mov_b32_e32 v90, v2
	v_mov_b32_e32 v91, v2
	v_mov_b32_e32 v92, v2
	v_mov_b32_e32 v93, v2
	v_mov_b32_e32 v94, v2
	v_mov_b32_e32 v95, v2
	v_mov_b32_e32 v96, v2
	v_mov_b32_e32 v97, v2
	v_mov_b32_e32 v106, v2
	v_mov_b32_e32 v107, v2
	v_mov_b32_e32 v108, v2
	v_mov_b32_e32 v109, v2
	v_mov_b32_e32 v110, v2
	v_mov_b32_e32 v111, v2
	v_mov_b32_e32 v112, v2
	v_mov_b32_e32 v113, v2
	v_mov_b32_e32 v122, v2
	v_mov_b32_e32 v123, v2
	v_mov_b32_e32 v124, v2
	v_mov_b32_e32 v125, v2
	v_mov_b32_e32 v126, v2
	v_mov_b32_e32 v127, v2
	v_mov_b32_e32 v128, v2
	v_mov_b32_e32 v129, v2
	s_andn2_b64 vcc, exec, s[0:1]
	s_cbranch_vccnz .LBB0_1072
